# attention priority raise limited to the key loop (prio 0 during the item epilogue, re-raised at the item top)
# baseline (speedup 1.0000x reference)
; __device__ __forceinline__ void attn_phase(const Params& p, LAS unsigned char* lds, int li, int tid, int G, bf16_t* __restrict__ dst, const bf16_t* __restrict__ ZGA) {
;     ...
;         u32x2 gv[3][8];
; #pragma unroll
;         for (int mb = 0; mb < 3; ++mb) {
;             const int hh = mb, r = 16 * w + lq;
;             const bf16_t* gp = ZGA + (size_t)(t0 + r) * 1536 + (3 * hk + hh) * 128 + 4 * g;
; #pragma unroll
;             for (int db = 0; db < 8; ++db) gv[mb][db] = *(const u32x2*)(gp + 16 * db);
;         }
;         load_q(nitem >= 0 ? nitem : item, lq, g);
; #pragma unroll
;         for (int mb = 0; mb < 3; ++mb) {
;             const int hh = mb, r = 16 * w + lq;
;             const size_t tok = (size_t)(t0 + r); const int hcol = (3 * hk + hh) * 128 + 4 * g;
;             float lt = lrun[mb]; lt += __shfl_xor(lt, 16); lt += __shfl_xor(lt, 32);
;             lt += __builtin_amdgcn_exp2f(BS[hh * 260 + 257]);
;             const float inv = 1.f / lt;
; #pragma unroll
;             for (int db = 0; db < 8; ++db) {
;                 const f32x4 o = oacc[mb][db] * inv;
.LBB0_307:
	s_setprio 0
	s_lshl_b32 s0, s38, 7
	s_add_i32 s0, s0, s35
	v_or_b32_e32 v198, s0, v208
	v_mov_b64_e32 v[98:99], s[26:27]
	s_movk_i32 s0, 0xc00
	v_mad_i64_i32 v[98:99], s[0:1], v198, s0, v[98:99]
	v_ashrrev_i32_e32 v171, 31, v170
	s_mulk_i32 s46, 0x180
	v_lshl_add_u64 v[98:99], v[170:171], 1, v[98:99]
	s_lshl_b32 s0, s46, 1
	s_mov_b32 s1, s47
	v_lshl_add_u64 v[98:99], v[98:99], 0, s[0:1]
	global_load_dwordx2 v[196:197], v[98:99], off
	global_load_dwordx2 v[194:195], v[98:99], off offset:32
	global_load_dwordx2 v[192:193], v[98:99], off offset:64
	global_load_dwordx2 v[190:191], v[98:99], off offset:96
	global_load_dwordx2 v[188:189], v[98:99], off offset:128
	global_load_dwordx2 v[186:187], v[98:99], off offset:160
	global_load_dwordx2 v[184:185], v[98:99], off offset:192
	global_load_dwordx2 v[182:183], v[98:99], off offset:224
	global_load_dwordx2 v[180:181], v[98:99], off offset:256
	global_load_dwordx2 v[178:179], v[98:99], off offset:288
	global_load_dwordx2 v[176:177], v[98:99], off offset:320
	global_load_dwordx2 v[174:175], v[98:99], off offset:352
	global_load_dwordx2 v[168:169], v[98:99], off offset:384
	global_load_dwordx2 v[166:167], v[98:99], off offset:416
	global_load_dwordx2 v[164:165], v[98:99], off offset:448
	global_load_dwordx2 v[162:163], v[98:99], off offset:480
	global_load_dwordx2 v[160:161], v[98:99], off offset:512
	global_load_dwordx2 v[158:159], v[98:99], off offset:544
	global_load_dwordx2 v[156:157], v[98:99], off offset:576
	global_load_dwordx2 v[154:155], v[98:99], off offset:608
	global_load_dwordx2 v[152:153], v[98:99], off offset:640
	global_load_dwordx2 v[150:151], v[98:99], off offset:672
	global_load_dwordx2 v[148:149], v[98:99], off offset:704
	global_load_dwordx2 v[110:111], v[98:99], off offset:736
	s_cmp_lt_i32 s97, 0
	s_cselect_b32 s0, s34, s97
	s_and_b32 s1, s0, 3
	s_lshl_b32 s0, s0, 5
	s_and_b32 s0, s0, 0xffffff80
	s_add_i32 s0, s0, s35
	v_or_b32_e32 v98, s0, v208
	v_ashrrev_i32_e32 v99, 31, v98
	v_lshlrev_b64 v[98:99], 12, v[98:99]
	v_lshl_add_u64 v[98:99], s[20:21], 0, v[98:99]
	s_mul_i32 s0, s1, 0x300
	s_mov_b32 s1, s47
	ds_bpermute_b32 v0, v204, v209
	v_lshl_add_u64 v[98:99], v[98:99], 0, s[0:1]
	v_lshl_add_u64 v[140:141], v[172:173], 1, v[98:99]
	v_mov_b32_e32 v142, s90
	global_load_dwordx4 v[136:139], v[140:141], off
	global_load_dwordx4 v[106:109], v[140:141], off offset:64
	global_load_dwordx4 v[102:105], v[140:141], off offset:128
	global_load_dwordx4 v[98:101], v[140:141], off offset:192
	global_load_dwordx4 v[124:127], v[140:141], off offset:256
	global_load_dwordx4 v[120:123], v[140:141], off offset:320
	global_load_dwordx4 v[116:119], v[140:141], off offset:384
	global_load_dwordx4 v[112:115], v[140:141], off offset:448
	global_load_dwordx4 v[132:135], v[140:141], off offset:512
	global_load_dwordx4 v[128:131], v[140:141], off offset:576
	ds_read_b32 v142, v142
	s_waitcnt lgkmcnt(0)
	v_add_f32_e32 v0, v209, v0
	ds_bpermute_b32 v172, v205, v0
	v_ashrrev_i32_e32 v199, 31, v198
	v_mov_b32_e32 v143, s91
	v_exp_f32_e32 v173, v142
	v_mov_b32_e32 v144, s92
	s_waitcnt lgkmcnt(0)
	v_add_f32_e32 v0, v0, v172
	ds_read_b32 v209, v143
	ds_read_b32 v208, v144
	v_add_f32_e32 v0, v0, v173
	v_div_scale_f32 v210, s[0:1], v0, v0, 1.0
	v_rcp_f32_e32 v211, v210
	v_lshlrev_b64 v[172:173], 12, v[198:199]
	v_add_u32_e32 v198, s46, v170
	v_lshl_add_u64 v[172:173], s[42:43], 0, v[172:173]
	v_fma_f32 v199, -v210, v211, 1.0
	v_fmac_f32_e32 v211, v199, v211
	v_div_scale_f32 v199, vcc, 1.0, v0, 1.0
	v_mul_f32_e32 v212, v199, v211
	v_fma_f32 v213, -v210, v212, v199
	v_fmac_f32_e32 v212, v213, v211
	v_fma_f32 v199, -v210, v212, v199
	v_div_fmas_f32 v199, v199, v211, v212
	v_div_fixup_f32 v0, v199, v0, 1.0
	v_pk_mul_f32 v[94:95], v[94:95], v[0:1] op_sel_hi:[1,0]
	v_ashrrev_i32_e32 v199, 31, v198
	v_pk_mul_f32 v[96:97], v[96:97], v[0:1] op_sel_hi:[1,0]
	v_lshl_add_u64 v[198:199], v[198:199], 1, v[172:173]
	global_load_dwordx4 v[144:147], v[140:141], off offset:640
	s_nop 0
	global_load_dwordx4 v[140:143], v[140:141], off offset:704
	v_pk_mul_f32 v[90:91], v[90:91], v[0:1] op_sel_hi:[1,0]
	v_pk_mul_f32 v[92:93], v[92:93], v[0:1] op_sel_hi:[1,0]
	v_pk_mul_f32 v[86:87], v[86:87], v[0:1] op_sel_hi:[1,0]
	v_pk_mul_f32 v[88:89], v[88:89], v[0:1] op_sel_hi:[1,0]
	v_pk_mul_f32 v[82:83], v[82:83], v[0:1] op_sel_hi:[1,0]
	v_pk_mul_f32 v[84:85], v[84:85], v[0:1] op_sel_hi:[1,0]
	v_pk_mul_f32 v[78:79], v[78:79], v[0:1] op_sel_hi:[1,0]
	s_waitcnt vmcnt(0)
; __device__ __forceinline__ unsigned cvt_pk_bf16(float lo, float hi) { unsigned r; asm("v_cvt_pk_bf16_f32 %0, %1, %2" : "=v"(r) : "v"(lo), "v"(hi)); return r; }
; __device__ __forceinline__ float silu_f(float x) { return x * __builtin_amdgcn_rcpf(1.f + __builtin_amdgcn_exp2f(-LOG2E * x)); }
; __device__ __forceinline__ void attn_phase(const Params& p, LAS unsigned char* lds, int li, int tid, int G, bf16_t* __restrict__ dst, const bf16_t* __restrict__ ZGA) {
;     ...
; #pragma unroll
;         for (int mb = 0; mb < 3; ++mb) {
;             const int hh = mb, r = 16 * w + lq;
;             const size_t tok = (size_t)(t0 + r); const int hcol = (3 * hk + hh) * 128 + 4 * g;
;             float lt = lrun[mb]; lt += __shfl_xor(lt, 16); lt += __shfl_xor(lt, 32);
;             lt += __builtin_amdgcn_exp2f(BS[hh * 260 + 257]);
;             const float inv = 1.f / lt;
; #pragma unroll
;             for (int db = 0; db < 8; ++db) {
;                 const f32x4 o = oacc[mb][db] * inv;
;                 u32x2 wv; wv.x = cvt_pk_bf16(o[0] * silu_f(bf_lo(gv[mb][db].x)), o[1] * silu_f(bf_hi(gv[mb][db].x))); wv.y = cvt_pk_bf16(o[2] * silu_f(bf_lo(gv[mb][db].y)), o[3] * silu_f(bf_hi(gv[mb][db].y)));
;                 *(u32x2*)(dst + tok * 2048 + hcol + 16 * db) = wv;
;             }
	v_lshlrev_b32_e32 v210, 16, v196
	v_mul_f32_e32 v211, 0xbfb8aa3b, v210
	v_exp_f32_e32 v211, v211
	v_and_b32_e32 v196, 0xffff0000, v196
	v_mul_f32_e32 v212, 0xbfb8aa3b, v196
	v_exp_f32_e32 v212, v212
	v_add_f32_e32 v211, 1.0, v211
	v_rcp_f32_e32 v211, v211
	v_pk_mul_f32 v[80:81], v[80:81], v[0:1] op_sel_hi:[1,0]
	v_add_f32_e32 v212, 1.0, v212
	v_rcp_f32_e32 v212, v212
	v_mul_f32_e32 v210, v211, v210
	v_mul_f32_e32 v94, v210, v94
	v_lshlrev_b32_e32 v210, 16, v197
	v_mul_f32_e32 v211, 0xbfb8aa3b, v210
	v_and_b32_e32 v197, 0xffff0000, v197
	v_mul_f32_e32 v196, v212, v196
	v_exp_f32_e32 v211, v211
	v_mul_f32_e32 v212, 0xbfb8aa3b, v197
	v_exp_f32_e32 v212, v212
	v_mul_f32_e32 v95, v196, v95
	v_add_f32_e32 v196, 1.0, v211
	v_rcp_f32_e32 v196, v196
	v_add_f32_e32 v211, 1.0, v212
	v_rcp_f32_e32 v211, v211
	v_cvt_pk_bf16_f32 v94, v94, v95
	v_mul_f32_e32 v95, v196, v210
	v_mul_f32_e32 v95, v95, v96
	v_mul_f32_e32 v96, v211, v197
	v_mul_f32_e32 v96, v96, v97
	v_cvt_pk_bf16_f32 v95, v95, v96
	global_store_dwordx2 v[198:199], v[94:95], off
	v_lshlrev_b32_e32 v94, 16, v194
	v_mul_f32_e32 v95, 0xbfb8aa3b, v94
	v_and_b32_e32 v96, 0xffff0000, v194
	v_exp_f32_e32 v95, v95
	v_mul_f32_e32 v97, 0xbfb8aa3b, v96
	v_exp_f32_e32 v97, v97
	v_pk_mul_f32 v[74:75], v[74:75], v[0:1] op_sel_hi:[1,0]
	v_add_f32_e32 v95, 1.0, v95
	v_rcp_f32_e32 v95, v95
	v_add_f32_e32 v97, 1.0, v97
	v_rcp_f32_e32 v97, v97
	v_pk_mul_f32 v[76:77], v[76:77], v[0:1] op_sel_hi:[1,0]
	v_mul_f32_e32 v94, v95, v94
	v_lshlrev_b32_e32 v95, 16, v195
	v_mul_f32_e32 v90, v94, v90
	v_mul_f32_e32 v94, v97, v96
	v_mul_f32_e32 v96, 0xbfb8aa3b, v95
	v_and_b32_e32 v97, 0xffff0000, v195
	v_exp_f32_e32 v96, v96
	v_mul_f32_e32 v194, 0xbfb8aa3b, v97
	v_exp_f32_e32 v194, v194
	v_mul_f32_e32 v91, v94, v91
	v_add_f32_e32 v94, 1.0, v96
	v_rcp_f32_e32 v94, v94
	v_add_f32_e32 v96, 1.0, v194
	v_rcp_f32_e32 v96, v96
	v_cvt_pk_bf16_f32 v90, v90, v91
	v_mul_f32_e32 v91, v94, v95
	v_mul_f32_e32 v91, v91, v92
	v_mul_f32_e32 v92, v96, v97
	v_mul_f32_e32 v92, v92, v93
	v_cvt_pk_bf16_f32 v91, v91, v92
	global_store_dwordx2 v[198:199], v[90:91], off offset:32
	v_lshlrev_b32_e32 v90, 16, v192
	v_mul_f32_e32 v91, 0xbfb8aa3b, v90
	v_and_b32_e32 v92, 0xffff0000, v192
	v_exp_f32_e32 v91, v91
	v_mul_f32_e32 v93, 0xbfb8aa3b, v92
	v_exp_f32_e32 v93, v93
	v_pk_mul_f32 v[70:71], v[70:71], v[0:1] op_sel_hi:[1,0]
	v_add_f32_e32 v91, 1.0, v91
	v_rcp_f32_e32 v91, v91
	v_add_f32_e32 v93, 1.0, v93
	v_rcp_f32_e32 v93, v93
	v_pk_mul_f32 v[72:73], v[72:73], v[0:1] op_sel_hi:[1,0]
	v_mul_f32_e32 v90, v91, v90
	v_lshlrev_b32_e32 v91, 16, v193
	v_mul_f32_e32 v86, v90, v86
	v_mul_f32_e32 v90, v93, v92
	v_mul_f32_e32 v92, 0xbfb8aa3b, v91
	v_and_b32_e32 v93, 0xffff0000, v193
	v_exp_f32_e32 v92, v92
	v_mul_f32_e32 v94, 0xbfb8aa3b, v93
	v_exp_f32_e32 v94, v94
	v_mul_f32_e32 v87, v90, v87
	v_add_f32_e32 v90, 1.0, v92
	v_rcp_f32_e32 v90, v90
	v_add_f32_e32 v92, 1.0, v94
	v_rcp_f32_e32 v92, v92
	v_cvt_pk_bf16_f32 v86, v86, v87
	v_mul_f32_e32 v87, v90, v91
	v_mul_f32_e32 v87, v87, v88
	v_mul_f32_e32 v88, v92, v93
	v_mul_f32_e32 v88, v88, v89
	v_cvt_pk_bf16_f32 v87, v87, v88
	global_store_dwordx2 v[198:199], v[86:87], off offset:64
	v_lshlrev_b32_e32 v86, 16, v190
	v_mul_f32_e32 v87, 0xbfb8aa3b, v86
	v_and_b32_e32 v88, 0xffff0000, v190
	v_exp_f32_e32 v87, v87
	v_mul_f32_e32 v89, 0xbfb8aa3b, v88
	v_exp_f32_e32 v89, v89
	v_pk_mul_f32 v[68:69], v[68:69], v[0:1] op_sel_hi:[1,0]
	v_add_f32_e32 v87, 1.0, v87
	v_rcp_f32_e32 v87, v87
	v_add_f32_e32 v89, 1.0, v89
	v_rcp_f32_e32 v89, v89
	v_pk_mul_f32 v[66:67], v[66:67], v[0:1] op_sel_hi:[1,0]
	v_mul_f32_e32 v86, v87, v86
	v_lshlrev_b32_e32 v87, 16, v191
	v_mul_f32_e32 v82, v86, v82
	v_mul_f32_e32 v86, v89, v88
	v_mul_f32_e32 v88, 0xbfb8aa3b, v87
	v_and_b32_e32 v89, 0xffff0000, v191
	v_exp_f32_e32 v88, v88
	v_mul_f32_e32 v90, 0xbfb8aa3b, v89
	v_exp_f32_e32 v90, v90
	v_mul_f32_e32 v83, v86, v83
	v_add_f32_e32 v86, 1.0, v88
	v_rcp_f32_e32 v86, v86
	v_add_f32_e32 v88, 1.0, v90
	v_rcp_f32_e32 v88, v88
	v_cvt_pk_bf16_f32 v82, v82, v83
	v_mul_f32_e32 v83, v86, v87
	v_mul_f32_e32 v83, v83, v84
	v_mul_f32_e32 v84, v88, v89
	v_mul_f32_e32 v84, v84, v85
	v_cvt_pk_bf16_f32 v83, v83, v84
	global_store_dwordx2 v[198:199], v[82:83], off offset:96
	v_lshlrev_b32_e32 v82, 16, v188
	v_mul_f32_e32 v83, 0xbfb8aa3b, v82
	v_and_b32_e32 v84, 0xffff0000, v188
	v_exp_f32_e32 v83, v83
	v_mul_f32_e32 v85, 0xbfb8aa3b, v84
	v_exp_f32_e32 v85, v85
	s_add_i32 s93, s93, s2
	v_add_f32_e32 v83, 1.0, v83
	v_rcp_f32_e32 v83, v83
	v_add_f32_e32 v85, 1.0, v85
	v_rcp_f32_e32 v85, v85
	s_cmp_eq_u32 s95, s14
	v_mul_f32_e32 v82, v83, v82
	v_lshlrev_b32_e32 v83, 16, v189
	v_mul_f32_e32 v78, v82, v78
	v_mul_f32_e32 v82, v85, v84
	v_mul_f32_e32 v84, 0xbfb8aa3b, v83
	v_and_b32_e32 v85, 0xffff0000, v189
	v_exp_f32_e32 v84, v84
	v_mul_f32_e32 v86, 0xbfb8aa3b, v85
	v_exp_f32_e32 v86, v86
	v_mul_f32_e32 v79, v82, v79
	v_add_f32_e32 v82, 1.0, v84
	v_rcp_f32_e32 v82, v82
	v_add_f32_e32 v84, 1.0, v86
	v_rcp_f32_e32 v84, v84
	v_cvt_pk_bf16_f32 v78, v78, v79
	v_mul_f32_e32 v79, v82, v83
	v_mul_f32_e32 v79, v79, v80
	v_mul_f32_e32 v80, v84, v85
	v_mul_f32_e32 v80, v80, v81
	v_cvt_pk_bf16_f32 v79, v79, v80
	global_store_dwordx2 v[198:199], v[78:79], off offset:128
	v_lshlrev_b32_e32 v78, 16, v186
	v_mul_f32_e32 v79, 0xbfb8aa3b, v78
	v_and_b32_e32 v80, 0xffff0000, v186
	v_exp_f32_e32 v79, v79
	v_mul_f32_e32 v81, 0xbfb8aa3b, v80
	v_exp_f32_e32 v81, v81
	v_add_f32_e32 v79, 1.0, v79
	v_rcp_f32_e32 v79, v79
	v_add_f32_e32 v81, 1.0, v81
	v_rcp_f32_e32 v81, v81
	v_mul_f32_e32 v78, v79, v78
	v_lshlrev_b32_e32 v79, 16, v187
	v_mul_f32_e32 v74, v78, v74
	v_mul_f32_e32 v78, v81, v80
; __device__ __forceinline__ unsigned cvt_pk_bf16(float lo, float hi) { unsigned r; asm("v_cvt_pk_bf16_f32 %0, %1, %2" : "=v"(r) : "v"(lo), "v"(hi)); return r; }
; __device__ __forceinline__ float silu_f(float x) { return x * __builtin_amdgcn_rcpf(1.f + __builtin_amdgcn_exp2f(-LOG2E * x)); }
; __device__ __forceinline__ void attn_phase(const Params& p, LAS unsigned char* lds, int li, int tid, int G, bf16_t* __restrict__ dst, const bf16_t* __restrict__ ZGA) {
;     ...
; #pragma unroll
;         for (int mb = 0; mb < 3; ++mb) {
;             const int hh = mb, r = 16 * w + lq;
;             const size_t tok = (size_t)(t0 + r); const int hcol = (3 * hk + hh) * 128 + 4 * g;
;             float lt = lrun[mb]; lt += __shfl_xor(lt, 16); lt += __shfl_xor(lt, 32);
;             lt += __builtin_amdgcn_exp2f(BS[hh * 260 + 257]);
;             const float inv = 1.f / lt;
; #pragma unroll
;             for (int db = 0; db < 8; ++db) {
;                 const f32x4 o = oacc[mb][db] * inv;
;                 u32x2 wv; wv.x = cvt_pk_bf16(o[0] * silu_f(bf_lo(gv[mb][db].x)), o[1] * silu_f(bf_hi(gv[mb][db].x))); wv.y = cvt_pk_bf16(o[2] * silu_f(bf_lo(gv[mb][db].y)), o[3] * silu_f(bf_hi(gv[mb][db].y)));
;                 *(u32x2*)(dst + tok * 2048 + hcol + 16 * db) = wv;
;             }
;         }
	v_mul_f32_e32 v80, 0xbfb8aa3b, v79
	v_and_b32_e32 v81, 0xffff0000, v187
	v_exp_f32_e32 v80, v80
	v_mul_f32_e32 v82, 0xbfb8aa3b, v81
	v_exp_f32_e32 v82, v82
	v_mul_f32_e32 v75, v78, v75
	v_add_f32_e32 v78, 1.0, v80
	v_rcp_f32_e32 v78, v78
	v_add_f32_e32 v80, 1.0, v82
	v_rcp_f32_e32 v80, v80
	v_cvt_pk_bf16_f32 v74, v74, v75
	v_mul_f32_e32 v75, v78, v79
	v_mul_f32_e32 v75, v75, v76
	v_mul_f32_e32 v76, v80, v81
	v_mul_f32_e32 v76, v76, v77
	v_cvt_pk_bf16_f32 v75, v75, v76
	global_store_dwordx2 v[198:199], v[74:75], off offset:160
	v_lshlrev_b32_e32 v74, 16, v184
	v_mul_f32_e32 v75, 0xbfb8aa3b, v74
	v_and_b32_e32 v76, 0xffff0000, v184
	v_exp_f32_e32 v75, v75
	v_mul_f32_e32 v77, 0xbfb8aa3b, v76
	v_exp_f32_e32 v77, v77
	v_add_f32_e32 v75, 1.0, v75
	v_rcp_f32_e32 v75, v75
	v_add_f32_e32 v77, 1.0, v77
	v_rcp_f32_e32 v77, v77
	v_mul_f32_e32 v74, v75, v74
	v_lshlrev_b32_e32 v75, 16, v185
	v_mul_f32_e32 v70, v74, v70
	v_mul_f32_e32 v74, v77, v76
	v_mul_f32_e32 v76, 0xbfb8aa3b, v75
	v_and_b32_e32 v77, 0xffff0000, v185
	v_exp_f32_e32 v76, v76
	v_mul_f32_e32 v78, 0xbfb8aa3b, v77
	v_exp_f32_e32 v78, v78
	v_mul_f32_e32 v71, v74, v71
	v_add_f32_e32 v74, 1.0, v76
	v_rcp_f32_e32 v74, v74
	v_add_f32_e32 v76, 1.0, v78
	v_rcp_f32_e32 v76, v76
	v_cvt_pk_bf16_f32 v70, v70, v71
	v_mul_f32_e32 v71, v74, v75
	v_mul_f32_e32 v71, v71, v72
	v_mul_f32_e32 v72, v76, v77
	v_mul_f32_e32 v72, v72, v73
	v_cvt_pk_bf16_f32 v71, v71, v72
	global_store_dwordx2 v[198:199], v[70:71], off offset:192
	v_lshlrev_b32_e32 v70, 16, v182
	v_mul_f32_e32 v71, 0xbfb8aa3b, v70
	v_and_b32_e32 v72, 0xffff0000, v182
	v_exp_f32_e32 v71, v71
	v_mul_f32_e32 v73, 0xbfb8aa3b, v72
	v_exp_f32_e32 v73, v73
	v_add_f32_e32 v71, 1.0, v71
	v_rcp_f32_e32 v71, v71
	v_add_f32_e32 v73, 1.0, v73
	v_rcp_f32_e32 v73, v73
	v_mul_f32_e32 v0, v71, v70
	v_mul_f32_e32 v0, v0, v66
	v_mul_f32_e32 v66, v73, v72
	v_mul_f32_e32 v66, v66, v67
	v_cvt_pk_bf16_f32 v66, v0, v66
	v_lshlrev_b32_e32 v0, 16, v183
	v_mul_f32_e32 v67, 0xbfb8aa3b, v0
	v_exp_f32_e32 v67, v67
	v_and_b32_e32 v70, 0xffff0000, v183
	ds_bpermute_b32 v72, v204, v207
	v_mul_f32_e32 v71, 0xbfb8aa3b, v70
	v_exp_f32_e32 v71, v71
	v_add_f32_e32 v67, 1.0, v67
	v_rcp_f32_e32 v67, v67
	s_waitcnt lgkmcnt(0)
	v_add_f32_e32 v72, v207, v72
	v_add_f32_e32 v71, 1.0, v71
	ds_bpermute_b32 v73, v205, v72
	v_rcp_f32_e32 v71, v71
	v_mul_f32_e32 v0, v67, v0
	v_exp_f32_e32 v67, v209
	v_mul_f32_e32 v0, v0, v68
	v_mul_f32_e32 v68, v71, v70
	s_waitcnt lgkmcnt(0)
	v_add_f32_e32 v70, v72, v73
	v_add_f32_e32 v70, v70, v67
	v_div_scale_f32 v71, s[0:1], v70, v70, 1.0
	v_rcp_f32_e32 v72, v71
	v_mul_f32_e32 v67, v68, v69
	v_cvt_pk_bf16_f32 v67, v0, v67
	global_store_dwordx2 v[198:199], v[66:67], off offset:224
	v_fma_f32 v0, -v71, v72, 1.0
	v_fmac_f32_e32 v72, v0, v72
	v_div_scale_f32 v0, vcc, 1.0, v70, 1.0
	v_mul_f32_e32 v66, v0, v72
	v_fma_f32 v67, -v71, v66, v0
	v_fmac_f32_e32 v66, v67, v72
	v_fma_f32 v0, -v71, v66, v0
	v_div_fmas_f32 v0, v0, v72, v66
	v_lshlrev_b32_e32 v68, 16, v180
	v_div_fixup_f32 v0, v0, v70, 1.0
	v_mul_f32_e32 v69, 0xbfb8aa3b, v68
	v_and_b32_e32 v70, 0xffff0000, v180
	v_exp_f32_e32 v69, v69
	v_mul_f32_e32 v71, 0xbfb8aa3b, v70
	v_exp_f32_e32 v71, v71
	v_pk_mul_f32 v[62:63], v[62:63], v[0:1] op_sel_hi:[1,0]
	v_add_f32_e32 v69, 1.0, v69
	v_rcp_f32_e32 v69, v69
	v_add_f32_e32 v71, 1.0, v71
	v_rcp_f32_e32 v71, v71
	v_lshl_add_u64 v[66:67], s[46:47], 0, v[170:171]
	v_mul_f32_e32 v68, v69, v68
	v_lshlrev_b32_e32 v69, 16, v181
	v_mul_f32_e32 v62, v68, v62
	v_mul_f32_e32 v68, v71, v70
	v_mul_f32_e32 v70, 0xbfb8aa3b, v69
	v_and_b32_e32 v71, 0xffff0000, v181
	v_exp_f32_e32 v70, v70
	v_mul_f32_e32 v72, 0xbfb8aa3b, v71
	v_exp_f32_e32 v72, v72
	v_mul_f32_e32 v63, v68, v63
	v_add_f32_e32 v68, 1.0, v70
	v_rcp_f32_e32 v68, v68
	v_add_f32_e32 v70, 1.0, v72
	v_rcp_f32_e32 v70, v70
	v_pk_mul_f32 v[64:65], v[64:65], v[0:1] op_sel_hi:[1,0]
	v_cvt_pk_bf16_f32 v62, v62, v63
	v_mul_f32_e32 v63, v68, v69
	v_lshl_add_u64 v[66:67], v[66:67], 1, v[172:173]
	v_mul_f32_e32 v63, v63, v64
	v_mul_f32_e32 v64, v70, v71
	v_mul_f32_e32 v64, v64, v65
	v_cvt_pk_bf16_f32 v63, v63, v64
	global_store_dwordx2 v[66:67], v[62:63], off offset:256
	v_lshlrev_b32_e32 v62, 16, v178
	v_mul_f32_e32 v63, 0xbfb8aa3b, v62
	v_and_b32_e32 v64, 0xffff0000, v178
	v_exp_f32_e32 v63, v63
	v_mul_f32_e32 v65, 0xbfb8aa3b, v64
	v_exp_f32_e32 v65, v65
	v_pk_mul_f32 v[58:59], v[58:59], v[0:1] op_sel_hi:[1,0]
	v_add_f32_e32 v63, 1.0, v63
	v_rcp_f32_e32 v63, v63
	v_add_f32_e32 v65, 1.0, v65
	v_rcp_f32_e32 v65, v65
	v_pk_mul_f32 v[60:61], v[60:61], v[0:1] op_sel_hi:[1,0]
	v_mul_f32_e32 v62, v63, v62
	v_lshlrev_b32_e32 v63, 16, v179
	v_mul_f32_e32 v58, v62, v58
	v_mul_f32_e32 v62, v65, v64
	v_mul_f32_e32 v64, 0xbfb8aa3b, v63
	v_and_b32_e32 v65, 0xffff0000, v179
	v_exp_f32_e32 v64, v64
	v_mul_f32_e32 v68, 0xbfb8aa3b, v65
	v_exp_f32_e32 v68, v68
	v_mul_f32_e32 v59, v62, v59
	v_add_f32_e32 v62, 1.0, v64
	v_rcp_f32_e32 v62, v62
	v_add_f32_e32 v64, 1.0, v68
	v_rcp_f32_e32 v64, v64
	v_cvt_pk_bf16_f32 v58, v58, v59
	v_mul_f32_e32 v59, v62, v63
	v_mul_f32_e32 v59, v59, v60
	v_mul_f32_e32 v60, v64, v65
	v_mul_f32_e32 v60, v60, v61
	v_cvt_pk_bf16_f32 v59, v59, v60
	global_store_dwordx2 v[66:67], v[58:59], off offset:288
	v_lshlrev_b32_e32 v58, 16, v176
	v_mul_f32_e32 v59, 0xbfb8aa3b, v58
	v_and_b32_e32 v60, 0xffff0000, v176
	v_exp_f32_e32 v59, v59
	v_mul_f32_e32 v61, 0xbfb8aa3b, v60
	v_exp_f32_e32 v61, v61
	v_pk_mul_f32 v[54:55], v[54:55], v[0:1] op_sel_hi:[1,0]
	v_add_f32_e32 v59, 1.0, v59
	v_rcp_f32_e32 v59, v59
	v_add_f32_e32 v61, 1.0, v61
	v_rcp_f32_e32 v61, v61
	v_pk_mul_f32 v[56:57], v[56:57], v[0:1] op_sel_hi:[1,0]
	v_mul_f32_e32 v58, v59, v58
; __device__ __forceinline__ unsigned cvt_pk_bf16(float lo, float hi) { unsigned r; asm("v_cvt_pk_bf16_f32 %0, %1, %2" : "=v"(r) : "v"(lo), "v"(hi)); return r; }
; __device__ __forceinline__ float silu_f(float x) { return x * __builtin_amdgcn_rcpf(1.f + __builtin_amdgcn_exp2f(-LOG2E * x)); }
; __device__ __forceinline__ void attn_phase(const Params& p, LAS unsigned char* lds, int li, int tid, int G, bf16_t* __restrict__ dst, const bf16_t* __restrict__ ZGA) {
;     ...
; #pragma unroll
;         for (int mb = 0; mb < 3; ++mb) {
;             const int hh = mb, r = 16 * w + lq;
;             const size_t tok = (size_t)(t0 + r); const int hcol = (3 * hk + hh) * 128 + 4 * g;
;             float lt = lrun[mb]; lt += __shfl_xor(lt, 16); lt += __shfl_xor(lt, 32);
;             lt += __builtin_amdgcn_exp2f(BS[hh * 260 + 257]);
;             const float inv = 1.f / lt;
; #pragma unroll
;             for (int db = 0; db < 8; ++db) {
;                 const f32x4 o = oacc[mb][db] * inv;
;                 u32x2 wv; wv.x = cvt_pk_bf16(o[0] * silu_f(bf_lo(gv[mb][db].x)), o[1] * silu_f(bf_hi(gv[mb][db].x))); wv.y = cvt_pk_bf16(o[2] * silu_f(bf_lo(gv[mb][db].y)), o[3] * silu_f(bf_hi(gv[mb][db].y)));
;                 *(u32x2*)(dst + tok * 2048 + hcol + 16 * db) = wv;
;             }
;         }
	v_lshlrev_b32_e32 v59, 16, v177
	v_mul_f32_e32 v54, v58, v54
	v_mul_f32_e32 v58, v61, v60
	v_mul_f32_e32 v60, 0xbfb8aa3b, v59
	v_and_b32_e32 v61, 0xffff0000, v177
	v_exp_f32_e32 v60, v60
	v_mul_f32_e32 v62, 0xbfb8aa3b, v61
	v_exp_f32_e32 v62, v62
	v_mul_f32_e32 v55, v58, v55
	v_add_f32_e32 v58, 1.0, v60
	v_rcp_f32_e32 v58, v58
	v_add_f32_e32 v60, 1.0, v62
	v_rcp_f32_e32 v60, v60
	v_cvt_pk_bf16_f32 v54, v54, v55
	v_mul_f32_e32 v55, v58, v59
	v_mul_f32_e32 v55, v55, v56
	v_mul_f32_e32 v56, v60, v61
	v_mul_f32_e32 v56, v56, v57
	v_cvt_pk_bf16_f32 v55, v55, v56
	global_store_dwordx2 v[66:67], v[54:55], off offset:320
	v_lshlrev_b32_e32 v54, 16, v174
	v_mul_f32_e32 v55, 0xbfb8aa3b, v54
	v_and_b32_e32 v56, 0xffff0000, v174
	v_exp_f32_e32 v55, v55
	v_mul_f32_e32 v57, 0xbfb8aa3b, v56
	v_exp_f32_e32 v57, v57
	v_pk_mul_f32 v[50:51], v[50:51], v[0:1] op_sel_hi:[1,0]
	v_add_f32_e32 v55, 1.0, v55
	v_rcp_f32_e32 v55, v55
	v_add_f32_e32 v57, 1.0, v57
	v_rcp_f32_e32 v57, v57
	v_pk_mul_f32 v[52:53], v[52:53], v[0:1] op_sel_hi:[1,0]
	v_mul_f32_e32 v54, v55, v54
	v_lshlrev_b32_e32 v55, 16, v175
	v_mul_f32_e32 v50, v54, v50
	v_mul_f32_e32 v54, v57, v56
	v_mul_f32_e32 v56, 0xbfb8aa3b, v55
	v_and_b32_e32 v57, 0xffff0000, v175
	v_exp_f32_e32 v56, v56
	v_mul_f32_e32 v58, 0xbfb8aa3b, v57
	v_exp_f32_e32 v58, v58
	v_mul_f32_e32 v51, v54, v51
	v_add_f32_e32 v54, 1.0, v56
	v_rcp_f32_e32 v54, v54
	v_add_f32_e32 v56, 1.0, v58
	v_rcp_f32_e32 v56, v56
	v_cvt_pk_bf16_f32 v50, v50, v51
	v_mul_f32_e32 v51, v54, v55
	v_mul_f32_e32 v51, v51, v52
	v_mul_f32_e32 v52, v56, v57
	v_mul_f32_e32 v52, v52, v53
	v_cvt_pk_bf16_f32 v51, v51, v52
	global_store_dwordx2 v[66:67], v[50:51], off offset:352
	v_lshlrev_b32_e32 v50, 16, v168
	v_mul_f32_e32 v51, 0xbfb8aa3b, v50
	v_and_b32_e32 v52, 0xffff0000, v168
	v_exp_f32_e32 v51, v51
	v_mul_f32_e32 v53, 0xbfb8aa3b, v52
	v_exp_f32_e32 v53, v53
	v_pk_mul_f32 v[46:47], v[46:47], v[0:1] op_sel_hi:[1,0]
	v_add_f32_e32 v51, 1.0, v51
	v_rcp_f32_e32 v51, v51
	v_add_f32_e32 v53, 1.0, v53
	v_rcp_f32_e32 v53, v53
	v_pk_mul_f32 v[48:49], v[48:49], v[0:1] op_sel_hi:[1,0]
	v_mul_f32_e32 v50, v51, v50
	v_lshlrev_b32_e32 v51, 16, v169
	v_mul_f32_e32 v46, v50, v46
	v_mul_f32_e32 v50, v53, v52
	v_mul_f32_e32 v52, 0xbfb8aa3b, v51
	v_and_b32_e32 v53, 0xffff0000, v169
	v_exp_f32_e32 v52, v52
	v_mul_f32_e32 v54, 0xbfb8aa3b, v53
	v_exp_f32_e32 v54, v54
	v_mul_f32_e32 v47, v50, v47
	v_add_f32_e32 v50, 1.0, v52
	v_rcp_f32_e32 v50, v50
	v_add_f32_e32 v52, 1.0, v54
	v_rcp_f32_e32 v52, v52
	v_cvt_pk_bf16_f32 v46, v46, v47
	v_mul_f32_e32 v47, v50, v51
	v_mul_f32_e32 v47, v47, v48
	v_mul_f32_e32 v48, v52, v53
	v_mul_f32_e32 v48, v48, v49
	v_cvt_pk_bf16_f32 v47, v47, v48
	global_store_dwordx2 v[66:67], v[46:47], off offset:384
	v_lshlrev_b32_e32 v46, 16, v166
	v_mul_f32_e32 v47, 0xbfb8aa3b, v46
	v_and_b32_e32 v48, 0xffff0000, v166
	v_exp_f32_e32 v47, v47
	v_mul_f32_e32 v49, 0xbfb8aa3b, v48
	v_exp_f32_e32 v49, v49
	v_pk_mul_f32 v[42:43], v[42:43], v[0:1] op_sel_hi:[1,0]
	v_add_f32_e32 v47, 1.0, v47
	v_rcp_f32_e32 v47, v47
	v_add_f32_e32 v49, 1.0, v49
	v_rcp_f32_e32 v49, v49
	v_pk_mul_f32 v[44:45], v[44:45], v[0:1] op_sel_hi:[1,0]
	v_mul_f32_e32 v46, v47, v46
	v_lshlrev_b32_e32 v47, 16, v167
	v_mul_f32_e32 v42, v46, v42
	v_mul_f32_e32 v46, v49, v48
	v_mul_f32_e32 v48, 0xbfb8aa3b, v47
	v_and_b32_e32 v49, 0xffff0000, v167
	v_exp_f32_e32 v48, v48
	v_mul_f32_e32 v50, 0xbfb8aa3b, v49
	v_exp_f32_e32 v50, v50
	v_mul_f32_e32 v43, v46, v43
	v_add_f32_e32 v46, 1.0, v48
	v_rcp_f32_e32 v46, v46
	v_add_f32_e32 v48, 1.0, v50
	v_rcp_f32_e32 v48, v48
	v_cvt_pk_bf16_f32 v42, v42, v43
	v_mul_f32_e32 v43, v46, v47
	v_mul_f32_e32 v43, v43, v44
	v_mul_f32_e32 v44, v48, v49
	v_mul_f32_e32 v44, v44, v45
	v_cvt_pk_bf16_f32 v43, v43, v44
	global_store_dwordx2 v[66:67], v[42:43], off offset:416
	v_lshlrev_b32_e32 v42, 16, v164
	v_mul_f32_e32 v43, 0xbfb8aa3b, v42
	v_and_b32_e32 v44, 0xffff0000, v164
	v_exp_f32_e32 v43, v43
	v_mul_f32_e32 v45, 0xbfb8aa3b, v44
	v_exp_f32_e32 v45, v45
	v_pk_mul_f32 v[38:39], v[38:39], v[0:1] op_sel_hi:[1,0]
	v_add_f32_e32 v43, 1.0, v43
	v_rcp_f32_e32 v43, v43
	v_add_f32_e32 v45, 1.0, v45
	v_rcp_f32_e32 v45, v45
	v_pk_mul_f32 v[40:41], v[40:41], v[0:1] op_sel_hi:[1,0]
	v_mul_f32_e32 v42, v43, v42
	v_lshlrev_b32_e32 v43, 16, v165
	v_mul_f32_e32 v38, v42, v38
	v_mul_f32_e32 v42, v45, v44
	v_mul_f32_e32 v44, 0xbfb8aa3b, v43
	v_and_b32_e32 v45, 0xffff0000, v165
	v_exp_f32_e32 v44, v44
	v_mul_f32_e32 v46, 0xbfb8aa3b, v45
	v_exp_f32_e32 v46, v46
	v_mul_f32_e32 v39, v42, v39
	v_add_f32_e32 v42, 1.0, v44
	v_rcp_f32_e32 v42, v42
	v_add_f32_e32 v44, 1.0, v46
	v_rcp_f32_e32 v44, v44
	v_cvt_pk_bf16_f32 v38, v38, v39
	v_mul_f32_e32 v39, v42, v43
	v_mul_f32_e32 v39, v39, v40
	v_mul_f32_e32 v40, v44, v45
	v_mul_f32_e32 v40, v40, v41
	v_cvt_pk_bf16_f32 v39, v39, v40
	global_store_dwordx2 v[66:67], v[38:39], off offset:448
	v_lshlrev_b32_e32 v38, 16, v162
	v_mul_f32_e32 v39, 0xbfb8aa3b, v38
	v_and_b32_e32 v40, 0xffff0000, v162
	v_exp_f32_e32 v39, v39
	v_mul_f32_e32 v41, 0xbfb8aa3b, v40
	v_exp_f32_e32 v41, v41
	v_pk_mul_f32 v[36:37], v[36:37], v[0:1] op_sel_hi:[1,0]
	v_add_f32_e32 v39, 1.0, v39
	v_rcp_f32_e32 v39, v39
	v_add_f32_e32 v41, 1.0, v41
	v_rcp_f32_e32 v41, v41
	v_pk_mul_f32 v[34:35], v[34:35], v[0:1] op_sel_hi:[1,0]
	v_mul_f32_e32 v0, v39, v38
	v_mul_f32_e32 v0, v0, v34
	v_mul_f32_e32 v34, v41, v40
	v_mul_f32_e32 v34, v34, v35
	v_cvt_pk_bf16_f32 v34, v0, v34
	v_lshlrev_b32_e32 v0, 16, v163
	v_mul_f32_e32 v35, 0xbfb8aa3b, v0
	v_exp_f32_e32 v35, v35
	v_and_b32_e32 v38, 0xffff0000, v163
	ds_bpermute_b32 v40, v204, v206
	v_mul_f32_e32 v39, 0xbfb8aa3b, v38
	v_exp_f32_e32 v39, v39
	v_add_f32_e32 v35, 1.0, v35
	v_rcp_f32_e32 v35, v35
	s_waitcnt lgkmcnt(0)
; __device__ __forceinline__ unsigned cvt_pk_bf16(float lo, float hi) { unsigned r; asm("v_cvt_pk_bf16_f32 %0, %1, %2" : "=v"(r) : "v"(lo), "v"(hi)); return r; }
; __device__ __forceinline__ float silu_f(float x) { return x * __builtin_amdgcn_rcpf(1.f + __builtin_amdgcn_exp2f(-LOG2E * x)); }
; __device__ __forceinline__ void attn_phase(const Params& p, LAS unsigned char* lds, int li, int tid, int G, bf16_t* __restrict__ dst, const bf16_t* __restrict__ ZGA) {
;     ...
; #pragma unroll
;         for (int mb = 0; mb < 3; ++mb) {
;             const int hh = mb, r = 16 * w + lq;
;             const size_t tok = (size_t)(t0 + r); const int hcol = (3 * hk + hh) * 128 + 4 * g;
;             float lt = lrun[mb]; lt += __shfl_xor(lt, 16); lt += __shfl_xor(lt, 32);
;             lt += __builtin_amdgcn_exp2f(BS[hh * 260 + 257]);
;             const float inv = 1.f / lt;
; #pragma unroll
;             for (int db = 0; db < 8; ++db) {
;                 const f32x4 o = oacc[mb][db] * inv;
;                 u32x2 wv; wv.x = cvt_pk_bf16(o[0] * silu_f(bf_lo(gv[mb][db].x)), o[1] * silu_f(bf_hi(gv[mb][db].x))); wv.y = cvt_pk_bf16(o[2] * silu_f(bf_lo(gv[mb][db].y)), o[3] * silu_f(bf_hi(gv[mb][db].y)));
;                 *(u32x2*)(dst + tok * 2048 + hcol + 16 * db) = wv;
;             }
;         }
	v_add_f32_e32 v40, v206, v40
	v_add_f32_e32 v39, 1.0, v39
	ds_bpermute_b32 v41, v205, v40
	v_rcp_f32_e32 v39, v39
	v_mul_f32_e32 v0, v35, v0
	v_exp_f32_e32 v35, v208
	v_mul_f32_e32 v0, v0, v36
	v_mul_f32_e32 v36, v39, v38
	s_waitcnt lgkmcnt(0)
	v_add_f32_e32 v38, v40, v41
	v_add_f32_e32 v38, v38, v35
	v_div_scale_f32 v39, s[0:1], v38, v38, 1.0
	v_rcp_f32_e32 v40, v39
	v_mul_f32_e32 v35, v36, v37
	v_cvt_pk_bf16_f32 v35, v0, v35
	global_store_dwordx2 v[66:67], v[34:35], off offset:480
	v_fma_f32 v0, -v39, v40, 1.0
	v_fmac_f32_e32 v40, v0, v40
	v_div_scale_f32 v0, vcc, 1.0, v38, 1.0
	v_mul_f32_e32 v34, v0, v40
	v_fma_f32 v35, -v39, v34, v0
	v_fmac_f32_e32 v34, v35, v40
	v_fma_f32 v0, -v39, v34, v0
	v_div_fmas_f32 v0, v0, v40, v34
	v_lshlrev_b32_e32 v34, 16, v160
	v_mul_f32_e32 v35, 0xbfb8aa3b, v34
	v_and_b32_e32 v36, 0xffff0000, v160
	v_exp_f32_e32 v35, v35
	v_mul_f32_e32 v37, 0xbfb8aa3b, v36
	v_exp_f32_e32 v37, v37
	v_div_fixup_f32 v0, v0, v38, 1.0
	v_add_f32_e32 v35, 1.0, v35
	v_rcp_f32_e32 v35, v35
	v_add_f32_e32 v37, 1.0, v37
	v_rcp_f32_e32 v37, v37
	v_pk_mul_f32 v[30:31], v[30:31], v[0:1] op_sel_hi:[1,0]
	v_mul_f32_e32 v34, v35, v34
	v_lshlrev_b32_e32 v35, 16, v161
	v_mul_f32_e32 v30, v34, v30
	v_mul_f32_e32 v34, v37, v36
	v_mul_f32_e32 v36, 0xbfb8aa3b, v35
	v_and_b32_e32 v37, 0xffff0000, v161
	v_exp_f32_e32 v36, v36
	v_mul_f32_e32 v38, 0xbfb8aa3b, v37
	v_exp_f32_e32 v38, v38
	v_mul_f32_e32 v31, v34, v31
	v_add_f32_e32 v34, 1.0, v36
	v_rcp_f32_e32 v34, v34
	v_add_f32_e32 v36, 1.0, v38
	v_rcp_f32_e32 v36, v36
	v_pk_mul_f32 v[32:33], v[32:33], v[0:1] op_sel_hi:[1,0]
	v_cvt_pk_bf16_f32 v30, v30, v31
	v_mul_f32_e32 v31, v34, v35
	v_mul_f32_e32 v31, v31, v32
	v_mul_f32_e32 v32, v36, v37
	v_mul_f32_e32 v32, v32, v33
	v_cvt_pk_bf16_f32 v31, v31, v32
	global_store_dwordx2 v[66:67], v[30:31], off offset:512
	v_lshlrev_b32_e32 v30, 16, v158
	v_mul_f32_e32 v31, 0xbfb8aa3b, v30
	v_and_b32_e32 v32, 0xffff0000, v158
	v_exp_f32_e32 v31, v31
	v_mul_f32_e32 v33, 0xbfb8aa3b, v32
	v_exp_f32_e32 v33, v33
	v_pk_mul_f32 v[26:27], v[26:27], v[0:1] op_sel_hi:[1,0]
	v_add_f32_e32 v31, 1.0, v31
	v_rcp_f32_e32 v31, v31
	v_add_f32_e32 v33, 1.0, v33
	v_rcp_f32_e32 v33, v33
	v_pk_mul_f32 v[28:29], v[28:29], v[0:1] op_sel_hi:[1,0]
	v_mul_f32_e32 v30, v31, v30
	v_lshlrev_b32_e32 v31, 16, v159
	v_mul_f32_e32 v26, v30, v26
	v_mul_f32_e32 v30, v33, v32
	v_mul_f32_e32 v32, 0xbfb8aa3b, v31
	v_and_b32_e32 v33, 0xffff0000, v159
	v_exp_f32_e32 v32, v32
	v_mul_f32_e32 v34, 0xbfb8aa3b, v33
	v_exp_f32_e32 v34, v34
	v_mul_f32_e32 v27, v30, v27
	v_add_f32_e32 v30, 1.0, v32
	v_rcp_f32_e32 v30, v30
	v_add_f32_e32 v32, 1.0, v34
	v_rcp_f32_e32 v32, v32
	v_cvt_pk_bf16_f32 v26, v26, v27
	v_mul_f32_e32 v27, v30, v31
	v_mul_f32_e32 v27, v27, v28
	v_mul_f32_e32 v28, v32, v33
	v_mul_f32_e32 v28, v28, v29
	v_cvt_pk_bf16_f32 v27, v27, v28
	global_store_dwordx2 v[66:67], v[26:27], off offset:544
	v_lshlrev_b32_e32 v26, 16, v156
	v_mul_f32_e32 v27, 0xbfb8aa3b, v26
	v_and_b32_e32 v28, 0xffff0000, v156
	v_exp_f32_e32 v27, v27
	v_mul_f32_e32 v29, 0xbfb8aa3b, v28
	v_exp_f32_e32 v29, v29
	v_pk_mul_f32 v[22:23], v[22:23], v[0:1] op_sel_hi:[1,0]
	v_add_f32_e32 v27, 1.0, v27
	v_rcp_f32_e32 v27, v27
	v_add_f32_e32 v29, 1.0, v29
	v_rcp_f32_e32 v29, v29
	v_pk_mul_f32 v[24:25], v[24:25], v[0:1] op_sel_hi:[1,0]
	v_mul_f32_e32 v26, v27, v26
	v_lshlrev_b32_e32 v27, 16, v157
	v_mul_f32_e32 v22, v26, v22
	v_mul_f32_e32 v26, v29, v28
	v_mul_f32_e32 v28, 0xbfb8aa3b, v27
	v_and_b32_e32 v29, 0xffff0000, v157
	v_exp_f32_e32 v28, v28
	v_mul_f32_e32 v30, 0xbfb8aa3b, v29
	v_exp_f32_e32 v30, v30
	v_mul_f32_e32 v23, v26, v23
	v_add_f32_e32 v26, 1.0, v28
	v_rcp_f32_e32 v26, v26
	v_add_f32_e32 v28, 1.0, v30
	v_rcp_f32_e32 v28, v28
	v_cvt_pk_bf16_f32 v22, v22, v23
	v_mul_f32_e32 v23, v26, v27
	v_mul_f32_e32 v23, v23, v24
	v_mul_f32_e32 v24, v28, v29
	v_mul_f32_e32 v24, v24, v25
	v_cvt_pk_bf16_f32 v23, v23, v24
	global_store_dwordx2 v[66:67], v[22:23], off offset:576
	v_lshlrev_b32_e32 v22, 16, v154
	v_mul_f32_e32 v23, 0xbfb8aa3b, v22
	v_and_b32_e32 v24, 0xffff0000, v154
	v_exp_f32_e32 v23, v23
	v_mul_f32_e32 v25, 0xbfb8aa3b, v24
	v_exp_f32_e32 v25, v25
	v_pk_mul_f32 v[18:19], v[18:19], v[0:1] op_sel_hi:[1,0]
	v_add_f32_e32 v23, 1.0, v23
	v_rcp_f32_e32 v23, v23
	v_add_f32_e32 v25, 1.0, v25
	v_rcp_f32_e32 v25, v25
	v_pk_mul_f32 v[20:21], v[20:21], v[0:1] op_sel_hi:[1,0]
	v_mul_f32_e32 v22, v23, v22
	v_lshlrev_b32_e32 v23, 16, v155
	v_mul_f32_e32 v18, v22, v18
	v_mul_f32_e32 v22, v25, v24
	v_mul_f32_e32 v24, 0xbfb8aa3b, v23
	v_and_b32_e32 v25, 0xffff0000, v155
	v_exp_f32_e32 v24, v24
; __device__ __forceinline__ unsigned cvt_pk_bf16(float lo, float hi) { unsigned r; asm("v_cvt_pk_bf16_f32 %0, %1, %2" : "=v"(r) : "v"(lo), "v"(hi)); return r; }
; __device__ __forceinline__ float silu_f(float x) { return x * __builtin_amdgcn_rcpf(1.f + __builtin_amdgcn_exp2f(-LOG2E * x)); }
; __device__ __forceinline__ void attn_phase(const Params& p, LAS unsigned char* lds, int li, int tid, int G, bf16_t* __restrict__ dst, const bf16_t* __restrict__ ZGA) {
;     ...
; #pragma unroll
;         for (int mb = 0; mb < 3; ++mb) {
;             const int hh = mb, r = 16 * w + lq;
;             const size_t tok = (size_t)(t0 + r); const int hcol = (3 * hk + hh) * 128 + 4 * g;
;             float lt = lrun[mb]; lt += __shfl_xor(lt, 16); lt += __shfl_xor(lt, 32);
;             lt += __builtin_amdgcn_exp2f(BS[hh * 260 + 257]);
;             const float inv = 1.f / lt;
; #pragma unroll
;             for (int db = 0; db < 8; ++db) {
;                 const f32x4 o = oacc[mb][db] * inv;
;                 u32x2 wv; wv.x = cvt_pk_bf16(o[0] * silu_f(bf_lo(gv[mb][db].x)), o[1] * silu_f(bf_hi(gv[mb][db].x))); wv.y = cvt_pk_bf16(o[2] * silu_f(bf_lo(gv[mb][db].y)), o[3] * silu_f(bf_hi(gv[mb][db].y)));
;                 *(u32x2*)(dst + tok * 2048 + hcol + 16 * db) = wv;
;             }
;         }
	v_mul_f32_e32 v26, 0xbfb8aa3b, v25
	v_exp_f32_e32 v26, v26
	v_mul_f32_e32 v19, v22, v19
	v_add_f32_e32 v22, 1.0, v24
	v_rcp_f32_e32 v22, v22
	v_add_f32_e32 v24, 1.0, v26
	v_rcp_f32_e32 v24, v24
	v_cvt_pk_bf16_f32 v18, v18, v19
	v_mul_f32_e32 v19, v22, v23
	v_mul_f32_e32 v19, v19, v20
	v_mul_f32_e32 v20, v24, v25
	v_mul_f32_e32 v20, v20, v21
	v_cvt_pk_bf16_f32 v19, v19, v20
	global_store_dwordx2 v[66:67], v[18:19], off offset:608
	v_lshlrev_b32_e32 v18, 16, v152
	v_mul_f32_e32 v19, 0xbfb8aa3b, v18
	v_and_b32_e32 v20, 0xffff0000, v152
	v_exp_f32_e32 v19, v19
	v_mul_f32_e32 v21, 0xbfb8aa3b, v20
	v_exp_f32_e32 v21, v21
	v_pk_mul_f32 v[14:15], v[14:15], v[0:1] op_sel_hi:[1,0]
	v_add_f32_e32 v19, 1.0, v19
	v_rcp_f32_e32 v19, v19
	v_add_f32_e32 v21, 1.0, v21
	v_rcp_f32_e32 v21, v21
	v_pk_mul_f32 v[16:17], v[16:17], v[0:1] op_sel_hi:[1,0]
	v_mul_f32_e32 v18, v19, v18
	v_lshlrev_b32_e32 v19, 16, v153
	v_mul_f32_e32 v14, v18, v14
	v_mul_f32_e32 v18, v21, v20
	v_mul_f32_e32 v20, 0xbfb8aa3b, v19
	v_and_b32_e32 v21, 0xffff0000, v153
	v_exp_f32_e32 v20, v20
	v_mul_f32_e32 v22, 0xbfb8aa3b, v21
	v_exp_f32_e32 v22, v22
	v_mul_f32_e32 v15, v18, v15
	v_add_f32_e32 v18, 1.0, v20
	v_rcp_f32_e32 v18, v18
	v_add_f32_e32 v20, 1.0, v22
	v_rcp_f32_e32 v20, v20
	v_cvt_pk_bf16_f32 v14, v14, v15
	v_mul_f32_e32 v15, v18, v19
	v_mul_f32_e32 v15, v15, v16
	v_mul_f32_e32 v16, v20, v21
	v_mul_f32_e32 v16, v16, v17
	v_cvt_pk_bf16_f32 v15, v15, v16
	global_store_dwordx2 v[66:67], v[14:15], off offset:640
	v_lshlrev_b32_e32 v14, 16, v150
	v_mul_f32_e32 v15, 0xbfb8aa3b, v14
	v_and_b32_e32 v16, 0xffff0000, v150
	v_exp_f32_e32 v15, v15
	v_mul_f32_e32 v17, 0xbfb8aa3b, v16
	v_exp_f32_e32 v17, v17
	v_pk_mul_f32 v[10:11], v[10:11], v[0:1] op_sel_hi:[1,0]
	v_add_f32_e32 v15, 1.0, v15
	v_rcp_f32_e32 v15, v15
	v_add_f32_e32 v17, 1.0, v17
	v_rcp_f32_e32 v17, v17
	v_pk_mul_f32 v[12:13], v[12:13], v[0:1] op_sel_hi:[1,0]
	v_mul_f32_e32 v14, v15, v14
	v_lshlrev_b32_e32 v15, 16, v151
	v_mul_f32_e32 v10, v14, v10
	v_mul_f32_e32 v14, v17, v16
	v_mul_f32_e32 v16, 0xbfb8aa3b, v15
	v_and_b32_e32 v17, 0xffff0000, v151
	v_exp_f32_e32 v16, v16
	v_mul_f32_e32 v18, 0xbfb8aa3b, v17
	v_exp_f32_e32 v18, v18
	v_mul_f32_e32 v11, v14, v11
	v_add_f32_e32 v14, 1.0, v16
	v_rcp_f32_e32 v14, v14
	v_add_f32_e32 v16, 1.0, v18
	v_rcp_f32_e32 v16, v16
	v_cvt_pk_bf16_f32 v10, v10, v11
	v_mul_f32_e32 v11, v14, v15
	v_mul_f32_e32 v11, v11, v12
	v_mul_f32_e32 v12, v16, v17
	v_mul_f32_e32 v12, v12, v13
	v_cvt_pk_bf16_f32 v11, v11, v12
	global_store_dwordx2 v[66:67], v[10:11], off offset:672
	v_lshlrev_b32_e32 v10, 16, v148
	v_mul_f32_e32 v11, 0xbfb8aa3b, v10
	v_and_b32_e32 v12, 0xffff0000, v148
	v_exp_f32_e32 v11, v11
	v_mul_f32_e32 v13, 0xbfb8aa3b, v12
	v_exp_f32_e32 v13, v13
	v_pk_mul_f32 v[6:7], v[6:7], v[0:1] op_sel_hi:[1,0]
	v_add_f32_e32 v11, 1.0, v11
	v_rcp_f32_e32 v11, v11
	v_add_f32_e32 v13, 1.0, v13
	v_rcp_f32_e32 v13, v13
	v_pk_mul_f32 v[8:9], v[8:9], v[0:1] op_sel_hi:[1,0]
	v_mul_f32_e32 v10, v11, v10
	v_lshlrev_b32_e32 v11, 16, v149
	v_mul_f32_e32 v6, v10, v6
	v_mul_f32_e32 v10, v13, v12
	v_mul_f32_e32 v12, 0xbfb8aa3b, v11
	v_and_b32_e32 v13, 0xffff0000, v149
	v_exp_f32_e32 v12, v12
	v_mul_f32_e32 v14, 0xbfb8aa3b, v13
	v_exp_f32_e32 v14, v14
	v_mul_f32_e32 v7, v10, v7
	v_add_f32_e32 v10, 1.0, v12
	v_rcp_f32_e32 v10, v10
	v_add_f32_e32 v12, 1.0, v14
	v_rcp_f32_e32 v12, v12
	v_cvt_pk_bf16_f32 v6, v6, v7
	v_mul_f32_e32 v7, v10, v11
	v_mul_f32_e32 v7, v7, v8
	v_mul_f32_e32 v8, v12, v13
	v_mul_f32_e32 v8, v8, v9
	v_cvt_pk_bf16_f32 v7, v7, v8
	global_store_dwordx2 v[66:67], v[6:7], off offset:704
	v_lshlrev_b32_e32 v6, 16, v110
	v_mul_f32_e32 v7, 0xbfb8aa3b, v6
	v_and_b32_e32 v8, 0xffff0000, v110
	v_exp_f32_e32 v7, v7
	v_mul_f32_e32 v9, 0xbfb8aa3b, v8
	v_exp_f32_e32 v9, v9
	v_pk_mul_f32 v[4:5], v[4:5], v[0:1] op_sel_hi:[1,0]
	v_add_f32_e32 v7, 1.0, v7
	v_rcp_f32_e32 v7, v7
	v_add_f32_e32 v9, 1.0, v9
	v_rcp_f32_e32 v9, v9
	v_pk_mul_f32 v[2:3], v[2:3], v[0:1] op_sel_hi:[1,0]
	v_mul_f32_e32 v0, v7, v6
	v_mul_f32_e32 v0, v0, v2
	v_mul_f32_e32 v2, v9, v8
	v_lshlrev_b32_e32 v6, 16, v111
	v_and_b32_e32 v8, 0xffff0000, v111
	v_mul_f32_e32 v7, 0xbfb8aa3b, v6
	v_mul_f32_e32 v9, 0xbfb8aa3b, v8
	v_exp_f32_e32 v7, v7
	v_exp_f32_e32 v9, v9
	v_mul_f32_e32 v2, v2, v3
	v_cvt_pk_bf16_f32 v2, v0, v2
	v_add_f32_e32 v3, 1.0, v7
	v_add_f32_e32 v7, 1.0, v9
	v_rcp_f32_e32 v3, v3
	v_rcp_f32_e32 v7, v7
	v_mul_f32_e32 v0, v3, v6
	v_mul_f32_e32 v3, v7, v8
	v_mul_f32_e32 v3, v3, v5
	v_mul_f32_e32 v0, v0, v4
	v_cvt_pk_bf16_f32 v3, v0, v3
	global_store_dwordx2 v[66:67], v[2:3], off offset:736
	s_cbranch_scc1 .LBB0_367

; __device__ __forceinline__ void attn_phase(const Params& p, LAS unsigned char* lds, int li, int tid, int G, bf16_t* __restrict__ dst, const bf16_t* __restrict__ ZGA) {
;     ...
;     for (int kround = 0; kround < icnt; ++kround) {
;         const int item = ibase + kround * istep;
;         const int nitem = (kround + 1 < icnt) ? item + istep : -1;
;         int l = tid & 63; asm volatile("" : "+v"(l));
;         const int lq = l & 15, g = l >> 4;
;         const int tb = item >> 2, hk = item & 3;
;         const int nblk = tb < 128 ? 16 : 32, nbi = tb < 128 ? (tb & 15) : ((tb - 128) & 31);
;         const int t0 = tb * 128;
;         const bool has0 = nbi > 0, has2 = nbi < nblk - 1;
;         const int nkb = 1 + (has0 ? 1 : 0) + (has2 ? 1 : 0);
;         if (hk != curhk) {
;             __syncthreads();
;             const float* bt = (const float*)(ws + OFF_BIAS) + (size_t)(li * 12 + 3 * hk) * 260; for (int i = 64 * w + l; i < 3 * 260; i += 512) BS[i] = bt[i];
;             curhk = hk;
;         }
;         bf16x8 Qf[3][4];
;         {
;             const float* qg = p.q_gain + li * 128; const float* kg = p.k_gain + li * 128;
; #pragma unroll
;             for (int mb = 0; mb < 3; ++mb) {
;                 u32x4 raw[4]; float ss = 0.f;
; #pragma unroll
;                 for (int ks = 0; ks < 4; ++ks) { raw[ks] = qraw[mb][ks];
; #pragma unroll
;                     for (int e = 0; e < 4; ++e) { const float a = bf_lo(raw[ks][e]), b = bf_hi(raw[ks][e]); ss += a * a + b * b; } }
;                 ss += __shfl_xor(ss, 16); ss += __shfl_xor(ss, 32);
;                 const float rq = rsqrtf(ss * (1.f / 128.f) + EPS) * (0.08838834764831845f * LOG2E);
; #pragma unroll
;                 for (int ks = 0; ks < 4; ++ks) {
;                     const f32x4 g0 = *(const f32x4*)(qg + 32 * ks + 8 * g) * *(const f32x4*)(kg + 32 * ks + 8 * g), g1 = *(const f32x4*)(qg + 32 * ks + 8 * g + 4) * *(const f32x4*)(kg + 32 * ks + 8 * g + 4);
;                     u32x4 o;
;                     o.x = cvt_pk_bf16(bf_lo(raw[ks].x) * rq * g0[0], bf_hi(raw[ks].x) * rq * g0[1]);
;                     o.y = cvt_pk_bf16(bf_lo(raw[ks].y) * rq * g0[2], bf_hi(raw[ks].y) * rq * g0[3]);
;                     o.z = cvt_pk_bf16(bf_lo(raw[ks].z) * rq * g1[0], bf_hi(raw[ks].z) * rq * g1[1]);
;                     o.w = cvt_pk_bf16(bf_lo(raw[ks].w) * rq * g1[2], bf_hi(raw[ks].w) * rq * g1[3]);
.LBB0_323:
	s_waitcnt vmcnt(0)
	s_bitcmp1_b32 s35, 6
	s_cbranch_scc0 .Laprio0_top
	s_setprio 1
.Laprio0_top:
	v_and_b32_e32 v27, 0xffff0000, v136
	v_and_b32_e32 v95, 0xffff0000, v137
	v_lshlrev_b32_e32 v26, 16, v136
	v_mul_f32_e32 v6, v27, v27
	v_lshlrev_b32_e32 v94, 16, v137
	v_mul_f32_e32 v7, v95, v95
	v_fmac_f32_e32 v6, v26, v26
	v_fmac_f32_e32 v7, v94, v94
	v_and_b32_e32 v97, 0xffff0000, v138
	v_and_b32_e32 v3, 64, v202
	v_add_f32_e32 v6, v6, v7
	v_lshlrev_b32_e32 v96, 16, v138
	v_mul_f32_e32 v7, v97, v97
	v_ashrrev_i32_e32 v38, 4, v0
	v_xor_b32_e32 v2, 16, v202
	v_add_u32_e32 v39, 64, v3
	v_fmac_f32_e32 v7, v96, v96
	v_and_b32_e32 v111, 0xffff0000, v139
	v_cmp_lt_i32_e32 vcc, v2, v39
	v_lshlrev_b32_e32 v172, 3, v38
	v_add_f32_e32 v6, v7, v6
	v_lshlrev_b32_e32 v110, 16, v139
	v_mul_f32_e32 v7, v111, v111
	v_cndmask_b32_e32 v2, v202, v2, vcc
	v_ashrrev_i32_e32 v173, 31, v172
	v_fmac_f32_e32 v7, v110, v110
	v_lshlrev_b32_e32 v136, 16, v106
	v_and_b32_e32 v106, 0xffff0000, v106
	v_lshlrev_b32_e32 v204, 2, v2
	v_lshlrev_b64 v[2:3], 2, v[172:173]
	v_add_f32_e32 v6, v7, v6
	v_mul_f32_e32 v7, v106, v106
	s_waitcnt lgkmcnt(0)
	v_lshl_add_u64 v[4:5], s[8:9], 0, v[2:3]
	v_fmac_f32_e32 v7, v136, v136
	v_lshl_add_u64 v[2:3], s[10:11], 0, v[2:3]
	v_add_f32_e32 v14, v7, v6
	global_load_dwordx4 v[6:9], v[4:5], off offset:16
	global_load_dwordx4 v[10:13], v[4:5], off
	global_load_dwordx4 v[16:19], v[2:3], off offset:16
	global_load_dwordx4 v[20:23], v[2:3], off
	global_load_dwordx4 v[28:31], v[4:5], off offset:144
	global_load_dwordx4 v[40:43], v[4:5], off offset:128
	global_load_dwordx4 v[44:47], v[2:3], off offset:144
	global_load_dwordx4 v[48:51], v[2:3], off offset:128
	global_load_dwordx4 v[52:55], v[4:5], off offset:272
	global_load_dwordx4 v[56:59], v[4:5], off offset:256
	global_load_dwordx4 v[60:63], v[2:3], off offset:272
	global_load_dwordx4 v[64:67], v[2:3], off offset:256
	global_load_dwordx4 v[68:71], v[4:5], off offset:400
	global_load_dwordx4 v[72:75], v[4:5], off offset:384
	global_load_dwordx4 v[76:79], v[2:3], off offset:400
	global_load_dwordx4 v[80:83], v[2:3], off offset:384
	v_lshlrev_b32_e32 v137, 16, v107
	v_and_b32_e32 v107, 0xffff0000, v107
	v_mul_f32_e32 v15, v107, v107
	v_fmac_f32_e32 v15, v137, v137
	v_lshlrev_b32_e32 v138, 16, v108
	v_and_b32_e32 v108, 0xffff0000, v108
	v_add_f32_e32 v14, v15, v14
	v_mul_f32_e32 v15, v108, v108
	v_fmac_f32_e32 v15, v138, v138
	v_lshlrev_b32_e32 v139, 16, v109
	v_and_b32_e32 v109, 0xffff0000, v109
	v_add_f32_e32 v14, v15, v14
	v_mul_f32_e32 v15, v109, v109
	v_fmac_f32_e32 v15, v139, v139
	v_and_b32_e32 v85, 0xffff0000, v103
	v_and_b32_e32 v84, 0xffff0000, v102
	v_add_f32_e32 v24, v15, v14
	v_lshlrev_b32_e32 v33, 16, v103
	v_lshlrev_b32_e32 v32, 16, v102
	v_pk_mul_f32 v[14:15], v[84:85], v[84:85]
	v_and_b32_e32 v89, 0xffff0000, v105
	v_pk_fma_f32 v[14:15], v[32:33], v[32:33], v[14:15]
	v_and_b32_e32 v88, 0xffff0000, v104
	v_add_f32_e32 v14, v14, v24
	v_add_f32_e32 v24, v15, v14
	v_lshlrev_b32_e32 v87, 16, v105
	v_lshlrev_b32_e32 v86, 16, v104
	v_pk_mul_f32 v[14:15], v[88:89], v[88:89]
	v_and_b32_e32 v93, 0xffff0000, v99
	v_pk_fma_f32 v[14:15], v[86:87], v[86:87], v[14:15]
	v_and_b32_e32 v92, 0xffff0000, v98
	v_add_f32_e32 v14, v14, v24
	v_add_f32_e32 v24, v15, v14
	v_lshlrev_b32_e32 v91, 16, v99
	v_lshlrev_b32_e32 v90, 16, v98
	v_pk_mul_f32 v[14:15], v[92:93], v[92:93]
	v_and_b32_e32 v35, 0xffff0000, v101
	v_pk_fma_f32 v[14:15], v[90:91], v[90:91], v[14:15]
	v_and_b32_e32 v34, 0xffff0000, v100
	v_add_f32_e32 v14, v14, v24
	v_add_f32_e32 v24, v15, v14
	v_lshlrev_b32_e32 v37, 16, v101
	v_lshlrev_b32_e32 v36, 16, v100
	v_pk_mul_f32 v[14:15], v[34:35], v[34:35]
	s_add_i32 s95, s95, 1
	v_pk_fma_f32 v[14:15], v[36:37], v[36:37], v[14:15]
	s_add_i32 s0, s34, s2
	v_add_f32_e32 v14, v14, v24
	v_add_f32_e32 v14, v15, v14
	ds_bpermute_b32 v15, v204, v14
	v_xor_b32_e32 v24, 32, v202
	v_cmp_lt_i32_e32 vcc, v24, v39
	s_cmp_lt_i32 s95, s14
	s_cselect_b32 s97, s0, -1
	v_cndmask_b32_e32 v24, v202, v24, vcc
	v_lshlrev_b32_e32 v205, 2, v24
	s_waitcnt lgkmcnt(0)
	v_add_f32_e32 v14, v14, v15
	ds_bpermute_b32 v15, v205, v14
	s_ashr_i32 s38, s34, 2
	s_cmpk_lt_i32 s38, 0x80
	s_cselect_b32 s0, 15, 31
	s_and_b32 s1, s0, s38
	s_waitcnt lgkmcnt(0)
	v_add_f32_e32 v14, v14, v15
	v_fmamk_f32 v14, v14, 0x3c000000, v201
	v_mul_f32_e32 v15, 0x4b800000, v14
	v_cmp_gt_f32_e32 vcc, s87, v14
	s_cmp_lg_u32 s1, s0
	s_cselect_b64 s[4:5], -1, 0
	v_cndmask_b32_e32 v14, v14, v15, vcc
	v_rsq_f32_e32 v2, v14
	s_cmp_lg_u32 s1, 0
	s_cselect_b64 s[48:49], -1, 0
	s_and_b64 s[18:19], s[48:49], exec
	v_mul_f32_e32 v3, 0x45800000, v2
	v_cndmask_b32_e32 v2, v2, v3, vcc
	v_mul_f32_e32 v148, 0x3e0293ee, v2
	s_waitcnt vmcnt(12)
	v_pk_mul_f32 v[24:25], v[10:11], v[20:21]
	v_mul_f32_e32 v4, v148, v26
	v_mul_f32_e32 v5, v148, v27
	v_mul_f32_e32 v4, v24, v4
	v_mul_f32_e32 v5, v25, v5
	v_pk_mul_f32 v[14:15], v[12:13], v[22:23]
	v_pk_mul_f32 v[2:3], v[8:9], v[18:19]
	v_pk_mul_f32 v[8:9], v[6:7], v[16:17]
	v_cvt_pk_bf16_f32 v98, v4, v5
	v_mul_f32_e32 v4, v148, v94
	v_mul_f32_e32 v5, v148, v95
	s_waitcnt vmcnt(8)
	v_pk_mul_f32 v[26:27], v[40:41], v[48:49]
	v_mul_f32_e32 v6, v148, v136
	v_mul_f32_e32 v7, v148, v106
	v_mul_f32_e32 v4, v14, v4
	v_mul_f32_e32 v5, v15, v5
	v_mul_f32_e32 v6, v6, v26
	v_mul_f32_e32 v7, v7, v27
	v_cvt_pk_bf16_f32 v99, v4, v5
	v_mul_f32_e32 v4, v148, v96
	v_mul_f32_e32 v5, v148, v97
	v_pk_mul_f32 v[16:17], v[42:43], v[50:51]
	v_cvt_pk_bf16_f32 v102, v6, v7
	v_mul_f32_e32 v6, v148, v137
	v_mul_f32_e32 v7, v148, v107
	v_mul_f32_e32 v4, v8, v4
	v_mul_f32_e32 v5, v9, v5
	v_pk_mul_f32 v[10:11], v[28:29], v[44:45]
	v_mul_f32_e32 v6, v6, v16
	v_mul_f32_e32 v7, v7, v17
	s_waitcnt vmcnt(4)
; __device__ __forceinline__ unsigned cvt_pk_bf16(float lo, float hi) { unsigned r; asm("v_cvt_pk_bf16_f32 %0, %1, %2" : "=v"(r) : "v"(lo), "v"(hi)); return r; }
; __device__ __forceinline__ void attn_phase(const Params& p, LAS unsigned char* lds, int li, int tid, int G, bf16_t* __restrict__ dst, const bf16_t* __restrict__ ZGA) {
;     ...
;         bf16x8 Qf[3][4];
;         {
;             const float* qg = p.q_gain + li * 128; const float* kg = p.k_gain + li * 128;
; #pragma unroll
;             for (int mb = 0; mb < 3; ++mb) {
;                 u32x4 raw[4]; float ss = 0.f;
; #pragma unroll
;                 for (int ks = 0; ks < 4; ++ks) { raw[ks] = qraw[mb][ks];
; #pragma unroll
;                     for (int e = 0; e < 4; ++e) { const float a = bf_lo(raw[ks][e]), b = bf_hi(raw[ks][e]); ss += a * a + b * b; } }
;                 ss += __shfl_xor(ss, 16); ss += __shfl_xor(ss, 32);
;                 const float rq = rsqrtf(ss * (1.f / 128.f) + EPS) * (0.08838834764831845f * LOG2E);
; #pragma unroll
;                 for (int ks = 0; ks < 4; ++ks) {
;                     const f32x4 g0 = *(const f32x4*)(qg + 32 * ks + 8 * g) * *(const f32x4*)(kg + 32 * ks + 8 * g), g1 = *(const f32x4*)(qg + 32 * ks + 8 * g + 4) * *(const f32x4*)(kg + 32 * ks + 8 * g + 4);
;                     u32x4 o;
;                     o.x = cvt_pk_bf16(bf_lo(raw[ks].x) * rq * g0[0], bf_hi(raw[ks].x) * rq * g0[1]);
;                     o.y = cvt_pk_bf16(bf_lo(raw[ks].y) * rq * g0[2], bf_hi(raw[ks].y) * rq * g0[3]);
;                     o.z = cvt_pk_bf16(bf_lo(raw[ks].z) * rq * g1[0], bf_hi(raw[ks].z) * rq * g1[1]);
;                     o.w = cvt_pk_bf16(bf_lo(raw[ks].w) * rq * g1[2], bf_hi(raw[ks].w) * rq * g1[3]);
;                     Qf[mb][ks] = __builtin_bit_cast(bf16x8, o);
;                 }
	v_pk_mul_f32 v[28:29], v[56:57], v[64:65]
	v_mul_f32_e32 v20, v148, v32
	v_cvt_pk_bf16_f32 v100, v4, v5
	v_mul_f32_e32 v4, v148, v110
	v_mul_f32_e32 v5, v148, v111
	v_cvt_pk_bf16_f32 v103, v6, v7
	v_mul_f32_e32 v6, v148, v138
	v_mul_f32_e32 v7, v148, v108
	v_mul_f32_e32 v20, v20, v28
	v_mul_f32_e32 v21, v148, v84
	v_mul_f32_e32 v4, v2, v4
	v_mul_f32_e32 v5, v3, v5
	v_mul_f32_e32 v6, v6, v10
	v_mul_f32_e32 v7, v7, v11
	v_mul_f32_e32 v21, v21, v29
	v_cvt_pk_bf16_f32 v106, v20, v21
	v_mul_f32_e32 v20, v148, v33
	s_waitcnt vmcnt(0)
	v_pk_mul_f32 v[32:33], v[72:73], v[80:81]
	v_mul_f32_e32 v40, v148, v90
	v_cvt_pk_bf16_f32 v101, v4, v5
	v_pk_mul_f32 v[4:5], v[30:31], v[46:47]
	v_cvt_pk_bf16_f32 v104, v6, v7
	v_mul_f32_e32 v6, v148, v139
	v_mul_f32_e32 v7, v148, v109
	v_mul_f32_e32 v40, v40, v32
	v_mul_f32_e32 v41, v148, v92
	v_mul_f32_e32 v6, v6, v4
	v_mul_f32_e32 v7, v7, v5
	v_pk_mul_f32 v[22:23], v[74:75], v[82:83]
	v_mul_f32_e32 v41, v41, v33
	v_cvt_pk_bf16_f32 v110, v40, v41
	v_mul_f32_e32 v40, v148, v91
	v_cvt_pk_bf16_f32 v105, v6, v7
	v_pk_mul_f32 v[18:19], v[58:59], v[66:67]
	v_pk_mul_f32 v[6:7], v[54:55], v[62:63]
	v_pk_mul_f32 v[12:13], v[52:53], v[60:61]
	v_mul_f32_e32 v58, v40, v22
	v_mul_f32_e32 v40, v148, v93
	v_and_b32_e32 v61, 0xffff0000, v124
	v_and_b32_e32 v63, 0xffff0000, v125
	v_mul_f32_e32 v59, v40, v23
	v_lshlrev_b32_e32 v60, 16, v124
	v_mul_f32_e32 v40, v61, v61
	v_lshlrev_b32_e32 v62, 16, v125
	v_mul_f32_e32 v41, v63, v63
	v_mul_f32_e32 v21, v148, v85
	v_fmac_f32_e32 v40, v60, v60
	v_fmac_f32_e32 v41, v62, v62
	v_and_b32_e32 v65, 0xffff0000, v126
	v_mul_f32_e32 v20, v20, v18
	v_mul_f32_e32 v21, v21, v19
	v_add_f32_e32 v40, v40, v41
	v_lshlrev_b32_e32 v64, 16, v126
	v_mul_f32_e32 v41, v65, v65
	v_cvt_pk_bf16_f32 v107, v20, v21
	v_mul_f32_e32 v20, v148, v86
	v_mul_f32_e32 v21, v148, v88
	v_fmac_f32_e32 v41, v64, v64
	v_and_b32_e32 v67, 0xffff0000, v127
	v_mul_f32_e32 v20, v20, v12
	v_mul_f32_e32 v21, v21, v13
	v_add_f32_e32 v40, v41, v40
	v_lshlrev_b32_e32 v66, 16, v127
	v_mul_f32_e32 v41, v67, v67
	v_cvt_pk_bf16_f32 v108, v20, v21
	v_mul_f32_e32 v20, v148, v87
	v_mul_f32_e32 v21, v148, v89
	v_pk_mul_f32 v[30:31], v[68:69], v[76:77]
	v_fmac_f32_e32 v41, v66, v66
	v_and_b32_e32 v69, 0xffff0000, v120
	v_mul_f32_e32 v20, v20, v6
	v_mul_f32_e32 v21, v21, v7
	v_add_f32_e32 v40, v41, v40
	v_lshlrev_b32_e32 v68, 16, v120
	v_mul_f32_e32 v41, v69, v69
	v_cvt_pk_bf16_f32 v109, v20, v21
	v_pk_mul_f32 v[20:21], v[70:71], v[78:79]
	v_fmac_f32_e32 v41, v68, v68
	v_and_b32_e32 v71, 0xffff0000, v121
	v_add_f32_e32 v40, v41, v40
	v_lshlrev_b32_e32 v70, 16, v121
	v_mul_f32_e32 v41, v71, v71
	v_fmac_f32_e32 v41, v70, v70
	v_and_b32_e32 v73, 0xffff0000, v122
	v_add_f32_e32 v40, v41, v40
	v_lshlrev_b32_e32 v72, 16, v122
	v_mul_f32_e32 v41, v73, v73
	v_fmac_f32_e32 v41, v72, v72
	v_and_b32_e32 v75, 0xffff0000, v123
	v_add_f32_e32 v40, v41, v40
	v_lshlrev_b32_e32 v74, 16, v123
	v_mul_f32_e32 v41, v75, v75
	v_fmac_f32_e32 v41, v74, v74
	v_and_b32_e32 v43, 0xffff0000, v117
	v_and_b32_e32 v42, 0xffff0000, v116
	v_add_f32_e32 v46, v41, v40
	v_lshlrev_b32_e32 v41, 16, v117
	v_lshlrev_b32_e32 v40, 16, v116
	v_pk_mul_f32 v[44:45], v[42:43], v[42:43]
	v_and_b32_e32 v47, 0xffff0000, v119
	v_pk_fma_f32 v[44:45], v[40:41], v[40:41], v[44:45]
	v_and_b32_e32 v51, 0xffff0000, v113
	v_add_f32_e32 v44, v44, v46
	v_and_b32_e32 v46, 0xffff0000, v118
	v_add_f32_e32 v50, v45, v44
	v_lshlrev_b32_e32 v45, 16, v119
	v_lshlrev_b32_e32 v44, 16, v118
	v_pk_mul_f32 v[48:49], v[46:47], v[46:47]
	v_and_b32_e32 v55, 0xffff0000, v115
	v_pk_fma_f32 v[48:49], v[44:45], v[44:45], v[48:49]
	v_mul_f32_e32 v36, v148, v36
	v_add_f32_e32 v48, v48, v50
	v_and_b32_e32 v50, 0xffff0000, v112
	v_add_f32_e32 v54, v49, v48
	v_lshlrev_b32_e32 v49, 16, v113
	v_lshlrev_b32_e32 v48, 16, v112
	v_pk_mul_f32 v[52:53], v[50:51], v[50:51]
	v_mul_f32_e32 v36, v36, v30
	v_pk_fma_f32 v[52:53], v[48:49], v[48:49], v[52:53]
	v_mul_f32_e32 v34, v148, v34
	v_add_f32_e32 v52, v52, v54
	v_and_b32_e32 v54, 0xffff0000, v114
	v_add_f32_e32 v76, v53, v52
	v_lshlrev_b32_e32 v53, 16, v115
	v_lshlrev_b32_e32 v52, 16, v114
	v_pk_mul_f32 v[56:57], v[54:55], v[54:55]
	v_mul_f32_e32 v34, v34, v31
	v_pk_fma_f32 v[56:57], v[52:53], v[52:53], v[56:57]
	v_cvt_pk_bf16_f32 v112, v36, v34
	v_mul_f32_e32 v34, v148, v37
	v_add_f32_e32 v56, v56, v76
	v_add_f32_e32 v56, v57, v56
	ds_bpermute_b32 v57, v204, v56
	v_mul_f32_e32 v34, v34, v20
	v_mul_f32_e32 v35, v148, v35
	v_mul_f32_e32 v35, v35, v21
	v_cvt_pk_bf16_f32 v113, v34, v35
	s_waitcnt lgkmcnt(0)
	v_add_f32_e32 v56, v56, v57
	ds_bpermute_b32 v57, v205, v56
	v_cvt_pk_bf16_f32 v111, v58, v59
	v_and_b32_e32 v76, 0xffff0000, v131
	s_cselect_b32 s1, 2, 1
	s_cmp_lg_u64 s[4:5], 0
	s_waitcnt lgkmcnt(0)
; __device__ __forceinline__ unsigned cvt_pk_bf16(float lo, float hi) { unsigned r; asm("v_cvt_pk_bf16_f32 %0, %1, %2" : "=v"(r) : "v"(lo), "v"(hi)); return r; }
; __device__ __forceinline__ void attn_phase(const Params& p, LAS unsigned char* lds, int li, int tid, int G, bf16_t* __restrict__ dst, const bf16_t* __restrict__ ZGA) {
;     ...
;         bf16x8 Qf[3][4];
;         {
;             const float* qg = p.q_gain + li * 128; const float* kg = p.k_gain + li * 128;
; #pragma unroll
;             for (int mb = 0; mb < 3; ++mb) {
;                 u32x4 raw[4]; float ss = 0.f;
; #pragma unroll
;                 for (int ks = 0; ks < 4; ++ks) { raw[ks] = qraw[mb][ks];
; #pragma unroll
;                     for (int e = 0; e < 4; ++e) { const float a = bf_lo(raw[ks][e]), b = bf_hi(raw[ks][e]); ss += a * a + b * b; } }
;                 ss += __shfl_xor(ss, 16); ss += __shfl_xor(ss, 32);
;                 const float rq = rsqrtf(ss * (1.f / 128.f) + EPS) * (0.08838834764831845f * LOG2E);
; #pragma unroll
;                 for (int ks = 0; ks < 4; ++ks) {
;                     const f32x4 g0 = *(const f32x4*)(qg + 32 * ks + 8 * g) * *(const f32x4*)(kg + 32 * ks + 8 * g), g1 = *(const f32x4*)(qg + 32 * ks + 8 * g + 4) * *(const f32x4*)(kg + 32 * ks + 8 * g + 4);
;                     u32x4 o;
;                     o.x = cvt_pk_bf16(bf_lo(raw[ks].x) * rq * g0[0], bf_hi(raw[ks].x) * rq * g0[1]);
;                     o.y = cvt_pk_bf16(bf_lo(raw[ks].y) * rq * g0[2], bf_hi(raw[ks].y) * rq * g0[3]);
;                     o.z = cvt_pk_bf16(bf_lo(raw[ks].z) * rq * g1[0], bf_hi(raw[ks].z) * rq * g1[1]);
;                     o.w = cvt_pk_bf16(bf_lo(raw[ks].w) * rq * g1[2], bf_hi(raw[ks].w) * rq * g1[3]);
;                     Qf[mb][ks] = __builtin_bit_cast(bf16x8, o);
;                 }
	v_add_f32_e32 v36, v56, v57
	v_fmamk_f32 v36, v36, 0x3c000000, v201
	v_mul_f32_e32 v37, 0x4b800000, v36
	v_cmp_gt_f32_e32 vcc, s87, v36
	s_addc_u32 s39, s1, 0
	s_cmp_gt_i32 s97, -1
	v_cndmask_b32_e32 v36, v36, v37, vcc
	v_rsq_f32_e32 v36, v36
	v_and_b32_e32 v37, 0xffff0000, v145
	s_cselect_b64 s[50:51], -1, 0
	s_lshl_b32 s1, s97, 5
	v_mul_f32_e32 v34, 0x45800000, v36
	v_cndmask_b32_e32 v34, v36, v34, vcc
	v_mul_f32_e32 v58, 0x3e0293ee, v34
	v_mul_f32_e32 v34, v58, v60
	v_mul_f32_e32 v34, v24, v34
	v_mul_f32_e32 v35, v58, v61
	v_mul_f32_e32 v35, v25, v35
	v_cvt_pk_bf16_f32 v114, v34, v35
	v_mul_f32_e32 v34, v58, v62
	v_mul_f32_e32 v34, v14, v34
	v_mul_f32_e32 v35, v58, v63
	v_mul_f32_e32 v35, v15, v35
	v_cvt_pk_bf16_f32 v115, v34, v35
	v_mul_f32_e32 v34, v58, v64
	v_mul_f32_e32 v34, v8, v34
	v_mul_f32_e32 v35, v58, v65
	v_mul_f32_e32 v35, v9, v35
	v_cvt_pk_bf16_f32 v116, v34, v35
	v_mul_f32_e32 v34, v58, v66
	v_mul_f32_e32 v34, v2, v34
	v_mul_f32_e32 v35, v58, v67
	v_mul_f32_e32 v35, v3, v35
	v_cvt_pk_bf16_f32 v117, v34, v35
	v_mul_f32_e32 v34, v58, v68
	v_mul_f32_e32 v34, v26, v34
	v_mul_f32_e32 v35, v58, v69
	v_mul_f32_e32 v35, v27, v35
	v_cvt_pk_bf16_f32 v118, v34, v35
	v_mul_f32_e32 v34, v58, v70
	v_mul_f32_e32 v34, v16, v34
	v_mul_f32_e32 v35, v58, v71
	v_mul_f32_e32 v35, v17, v35
	v_cvt_pk_bf16_f32 v119, v34, v35
	v_mul_f32_e32 v34, v58, v72
	v_mul_f32_e32 v34, v10, v34
	v_mul_f32_e32 v35, v58, v73
	v_mul_f32_e32 v35, v11, v35
	v_cvt_pk_bf16_f32 v120, v34, v35
	v_mul_f32_e32 v34, v58, v74
	v_mul_f32_e32 v34, v4, v34
	v_mul_f32_e32 v35, v58, v75
	v_mul_f32_e32 v35, v5, v35
	v_cvt_pk_bf16_f32 v121, v34, v35
	v_mul_f32_e32 v34, v58, v40
	v_mul_f32_e32 v34, v28, v34
	v_mul_f32_e32 v35, v58, v42
	v_mul_f32_e32 v35, v29, v35
	v_cvt_pk_bf16_f32 v122, v34, v35
	v_mul_f32_e32 v34, v58, v41
	v_mul_f32_e32 v34, v18, v34
	v_mul_f32_e32 v35, v58, v43
	v_mul_f32_e32 v35, v19, v35
	v_cvt_pk_bf16_f32 v123, v34, v35
	v_mul_f32_e32 v34, v58, v44
	v_mul_f32_e32 v34, v12, v34
	v_mul_f32_e32 v35, v58, v46
	v_mul_f32_e32 v35, v13, v35
	v_cvt_pk_bf16_f32 v124, v34, v35
	v_mul_f32_e32 v34, v58, v45
	v_mul_f32_e32 v34, v6, v34
	v_mul_f32_e32 v35, v58, v47
	v_mul_f32_e32 v35, v7, v35
	v_cvt_pk_bf16_f32 v125, v34, v35
	v_mul_f32_e32 v34, v58, v48
	v_mul_f32_e32 v34, v32, v34
	v_mul_f32_e32 v35, v58, v50
	v_mul_f32_e32 v35, v33, v35
	v_cvt_pk_bf16_f32 v126, v34, v35
	v_mul_f32_e32 v34, v58, v49
	v_mul_f32_e32 v59, v22, v34
	v_mul_f32_e32 v34, v58, v51
	v_and_b32_e32 v62, 0xffff0000, v132
	v_and_b32_e32 v64, 0xffff0000, v133
	v_mul_f32_e32 v60, v23, v34
	v_lshlrev_b32_e32 v61, 16, v132
	v_mul_f32_e32 v34, v62, v62
	v_lshlrev_b32_e32 v63, 16, v133
	v_mul_f32_e32 v35, v64, v64
	v_fmac_f32_e32 v34, v61, v61
	v_fmac_f32_e32 v35, v63, v63
	v_and_b32_e32 v66, 0xffff0000, v134
	v_add_f32_e32 v34, v34, v35
	v_lshlrev_b32_e32 v65, 16, v134
	v_mul_f32_e32 v35, v66, v66
	v_fmac_f32_e32 v35, v65, v65
	v_and_b32_e32 v68, 0xffff0000, v135
	v_add_f32_e32 v34, v35, v34
	v_lshlrev_b32_e32 v67, 16, v135
	v_mul_f32_e32 v35, v68, v68
	v_fmac_f32_e32 v35, v67, v67
	v_and_b32_e32 v70, 0xffff0000, v128
	v_add_f32_e32 v34, v35, v34
	v_lshlrev_b32_e32 v69, 16, v128
	v_mul_f32_e32 v35, v70, v70
	v_fmac_f32_e32 v35, v69, v69
	v_and_b32_e32 v72, 0xffff0000, v129
	v_add_f32_e32 v34, v35, v34
	v_lshlrev_b32_e32 v71, 16, v129
	v_mul_f32_e32 v35, v72, v72
	v_fmac_f32_e32 v35, v71, v71
	v_and_b32_e32 v74, 0xffff0000, v130
	v_add_f32_e32 v34, v35, v34
	v_lshlrev_b32_e32 v73, 16, v130
	v_mul_f32_e32 v35, v74, v74
	v_fmac_f32_e32 v35, v73, v73
	v_add_f32_e32 v34, v35, v34
	v_lshlrev_b32_e32 v75, 16, v131
	v_mul_f32_e32 v35, v76, v76
	v_fmac_f32_e32 v35, v75, v75
	v_and_b32_e32 v36, 0xffff0000, v144
	v_add_f32_e32 v42, v35, v34
	v_lshlrev_b32_e32 v35, 16, v145
	v_lshlrev_b32_e32 v34, 16, v144
	v_pk_mul_f32 v[40:41], v[36:37], v[36:37]
	v_and_b32_e32 v43, 0xffff0000, v147
	v_pk_fma_f32 v[40:41], v[34:35], v[34:35], v[40:41]
	v_and_b32_e32 v47, 0xffff0000, v141
	v_add_f32_e32 v40, v40, v42
	v_and_b32_e32 v42, 0xffff0000, v146
	v_add_f32_e32 v46, v41, v40
	v_lshlrev_b32_e32 v41, 16, v147
	v_lshlrev_b32_e32 v40, 16, v146
	v_pk_mul_f32 v[44:45], v[42:43], v[42:43]
	v_and_b32_e32 v51, 0xffff0000, v143
	v_pk_fma_f32 v[44:45], v[40:41], v[40:41], v[44:45]
	v_mul_f32_e32 v52, v58, v52
	v_add_f32_e32 v44, v44, v46
	v_and_b32_e32 v46, 0xffff0000, v140
	v_add_f32_e32 v50, v45, v44
	v_lshlrev_b32_e32 v45, 16, v141
	v_lshlrev_b32_e32 v44, 16, v140
	v_pk_mul_f32 v[48:49], v[46:47], v[46:47]
	v_mul_f32_e32 v52, v30, v52
	v_pk_fma_f32 v[48:49], v[44:45], v[44:45], v[48:49]
	v_mul_f32_e32 v54, v58, v54
	v_add_f32_e32 v48, v48, v50
	v_and_b32_e32 v50, 0xffff0000, v142
	v_add_f32_e32 v77, v49, v48
	v_lshlrev_b32_e32 v49, 16, v143
	v_lshlrev_b32_e32 v48, 16, v142
	v_pk_mul_f32 v[56:57], v[50:51], v[50:51]
	v_mul_f32_e32 v54, v31, v54
	v_pk_fma_f32 v[56:57], v[48:49], v[48:49], v[56:57]
	v_cvt_pk_bf16_f32 v128, v52, v54
	v_mul_f32_e32 v52, v58, v53
	v_add_f32_e32 v56, v56, v77
	v_add_f32_e32 v56, v57, v56
	ds_bpermute_b32 v57, v204, v56
	v_mul_f32_e32 v52, v20, v52
	s_and_b32 s41, s1, 0x7fffff80
	s_lshl_b32 s1, s97, 7
	s_and_b32 s28, s1, 0x180
	s_waitcnt lgkmcnt(0)
	v_add_f32_e32 v56, v56, v57
	ds_bpermute_b32 v57, v205, v56
	s_lshl_b32 s1, s28, 1
	s_add_u32 s52, s22, s1
	s_addc_u32 s53, s23, 0
	s_lshl_b32 s1, s41, 1
	s_waitcnt lgkmcnt(0)
; #define LAS __attribute__((address_space(3)))
; __device__ __forceinline__ unsigned cvt_pk_bf16(float lo, float hi) { unsigned r; asm("v_cvt_pk_bf16_f32 %0, %1, %2" : "=v"(r) : "v"(lo), "v"(hi)); return r; }
; __device__ __forceinline__ void attn_phase(const Params& p, LAS unsigned char* lds, int li, int tid, int G, bf16_t* __restrict__ dst, const bf16_t* __restrict__ ZGA) {
;     ...
;             for (int mb = 0; mb < 3; ++mb) {
;                 u32x4 raw[4]; float ss = 0.f;
; #pragma unroll
;                 for (int ks = 0; ks < 4; ++ks) { raw[ks] = qraw[mb][ks];
; #pragma unroll
;                     for (int e = 0; e < 4; ++e) { const float a = bf_lo(raw[ks][e]), b = bf_hi(raw[ks][e]); ss += a * a + b * b; } }
;                 ss += __shfl_xor(ss, 16); ss += __shfl_xor(ss, 32);
;                 const float rq = rsqrtf(ss * (1.f / 128.f) + EPS) * (0.08838834764831845f * LOG2E);
; #pragma unroll
;                 for (int ks = 0; ks < 4; ++ks) {
;                     const f32x4 g0 = *(const f32x4*)(qg + 32 * ks + 8 * g) * *(const f32x4*)(kg + 32 * ks + 8 * g), g1 = *(const f32x4*)(qg + 32 * ks + 8 * g + 4) * *(const f32x4*)(kg + 32 * ks + 8 * g + 4);
;                     u32x4 o;
;                     o.x = cvt_pk_bf16(bf_lo(raw[ks].x) * rq * g0[0], bf_hi(raw[ks].x) * rq * g0[1]);
;                     o.y = cvt_pk_bf16(bf_lo(raw[ks].y) * rq * g0[2], bf_hi(raw[ks].y) * rq * g0[3]);
;                     o.z = cvt_pk_bf16(bf_lo(raw[ks].z) * rq * g1[0], bf_hi(raw[ks].z) * rq * g1[1]);
;                     o.w = cvt_pk_bf16(bf_lo(raw[ks].w) * rq * g1[2], bf_hi(raw[ks].w) * rq * g1[3]);
;                     Qf[mb][ks] = __builtin_bit_cast(bf16x8, o);
;                 }
;             }
;         }
;         f32x4 oacc[3][8];
;         float lrun[3];
; #pragma unroll
;         for (int mb = 0; mb < 3; ++mb) {
;             lrun[mb] = 0.f;
; #pragma unroll
;             for (int db = 0; db < 8; ++db) oacc[mb][db] = (f32x4){0.f, 0.f, 0.f, 0.f};
;         }
;     ...
;                 const int key = 16 * w + (l >> 2), part = l & 3;
;                 u32x4 v[4]; float ss = 0.f;
; #pragma unroll
;                 for (int i = 0; i < 4; ++i) { v[i] = *(const LAS u32x4*)(KS + key * 256 + (((4 * part + i) ^ (key & 15)) << 4));
	v_add_f32_e32 v53, v56, v57
	v_fmamk_f32 v53, v53, 0x3c000000, v201
	v_mul_f32_e32 v54, 0x4b800000, v53
	v_cmp_gt_f32_e32 vcc, s87, v53
	s_add_u32 s54, s24, s1
	v_and_b32_e32 v208, 15, v0
	v_cndmask_b32_e32 v53, v53, v54, vcc
	v_rsq_f32_e32 v53, v53
	v_mul_f32_e32 v54, v58, v55
	v_mul_f32_e32 v54, v21, v54
	v_cvt_pk_bf16_f32 v129, v52, v54
	v_mul_f32_e32 v52, 0x45800000, v53
	v_cndmask_b32_e32 v52, v53, v52, vcc
	v_mul_f32_e32 v52, 0x3e0293ee, v52
	v_mul_f32_e32 v53, v52, v61
	v_mul_f32_e32 v24, v24, v53
	v_mul_f32_e32 v53, v52, v62
	v_mul_f32_e32 v25, v25, v53
	v_cvt_pk_bf16_f32 v130, v24, v25
	v_mul_f32_e32 v24, v52, v63
	v_mul_f32_e32 v14, v14, v24
	v_mul_f32_e32 v24, v52, v64
	v_mul_f32_e32 v15, v15, v24
	v_cvt_pk_bf16_f32 v131, v14, v15
	v_mul_f32_e32 v14, v52, v65
	v_mul_f32_e32 v8, v8, v14
	v_mul_f32_e32 v14, v52, v66
	v_mul_f32_e32 v9, v9, v14
	v_cvt_pk_bf16_f32 v132, v8, v9
	v_mul_f32_e32 v8, v52, v67
	v_mul_f32_e32 v2, v2, v8
	v_mul_f32_e32 v8, v52, v68
	v_mul_f32_e32 v3, v3, v8
	v_cvt_pk_bf16_f32 v133, v2, v3
	v_mul_f32_e32 v2, v52, v69
	v_mul_f32_e32 v2, v26, v2
	v_mul_f32_e32 v3, v52, v70
	v_mul_f32_e32 v3, v27, v3
	v_cvt_pk_bf16_f32 v134, v2, v3
	v_mul_f32_e32 v2, v52, v71
	v_mul_f32_e32 v2, v16, v2
	v_mul_f32_e32 v3, v52, v72
	v_mul_f32_e32 v3, v17, v3
	v_cvt_pk_bf16_f32 v135, v2, v3
	v_mul_f32_e32 v2, v52, v73
	v_mul_f32_e32 v2, v10, v2
	v_mul_f32_e32 v3, v52, v74
	v_mul_f32_e32 v3, v11, v3
	v_cvt_pk_bf16_f32 v136, v2, v3
	v_mul_f32_e32 v2, v52, v75
	v_mul_f32_e32 v2, v4, v2
	v_mul_f32_e32 v3, v52, v76
	v_mul_f32_e32 v3, v5, v3
	v_cvt_pk_bf16_f32 v137, v2, v3
	v_mul_f32_e32 v2, v52, v34
	v_mul_f32_e32 v2, v28, v2
	v_mul_f32_e32 v3, v52, v36
	v_mul_f32_e32 v3, v29, v3
	v_cvt_pk_bf16_f32 v138, v2, v3
	v_mul_f32_e32 v2, v52, v35
	v_mul_f32_e32 v2, v18, v2
	v_mul_f32_e32 v3, v52, v37
	v_mul_f32_e32 v3, v19, v3
	v_cvt_pk_bf16_f32 v139, v2, v3
	v_mul_f32_e32 v2, v52, v40
	v_mul_f32_e32 v2, v12, v2
	v_mul_f32_e32 v3, v52, v42
	v_mul_f32_e32 v3, v13, v3
	v_cvt_pk_bf16_f32 v140, v2, v3
	v_mul_f32_e32 v2, v52, v41
	v_mul_f32_e32 v2, v6, v2
	v_mul_f32_e32 v3, v52, v43
	v_mul_f32_e32 v3, v7, v3
	v_cvt_pk_bf16_f32 v141, v2, v3
	v_mul_f32_e32 v2, v52, v44
	v_mul_f32_e32 v2, v32, v2
	v_mul_f32_e32 v3, v52, v46
	v_mul_f32_e32 v3, v33, v3
	v_cvt_pk_bf16_f32 v142, v2, v3
	v_mul_f32_e32 v2, v52, v45
	v_mul_f32_e32 v2, v22, v2
	v_mul_f32_e32 v3, v52, v47
	v_mul_f32_e32 v3, v23, v3
	v_cvt_pk_bf16_f32 v143, v2, v3
	v_mul_f32_e32 v2, v52, v48
	v_mul_f32_e32 v2, v30, v2
	v_mul_f32_e32 v3, v52, v50
	v_mul_f32_e32 v3, v31, v3
	v_cvt_pk_bf16_f32 v144, v2, v3
	v_mul_f32_e32 v2, v52, v49
	v_mul_f32_e32 v2, v20, v2
	v_mul_f32_e32 v3, v52, v51
	v_mul_f32_e32 v3, v21, v3
	v_cvt_pk_bf16_f32 v145, v2, v3
	v_ashrrev_i32_e32 v2, 2, v0
	v_add_lshl_u32 v171, v2, s35, 8
	v_lshlrev_b32_e32 v3, 2, v0
	v_and_b32_e32 v2, 15, v2
	v_and_b32_e32 v4, 12, v3
	v_bitop3_b32 v3, v3, v2, 12 bitop3:0x6c
	v_lshlrev_b32_e32 v177, 4, v3
	v_bitop3_b32 v3, v4, v2, 1 bitop3:0x36
	v_lshlrev_b32_e32 v178, 4, v3
	v_bitop3_b32 v3, v4, v2, 2 bitop3:0x36
	v_bitop3_b32 v2, v4, v2, 3 bitop3:0x36
	v_lshlrev_b32_e32 v180, 4, v2
	v_xor_b32_e32 v2, 1, v202
	v_cmp_lt_i32_e32 vcc, v2, v39
	s_addc_u32 s55, s25, 0
	s_lshl_b32 s1, s34, 5
	v_cndmask_b32_e32 v2, v202, v2, vcc
	v_lshlrev_b32_e32 v181, 2, v2
	v_xor_b32_e32 v2, 2, v202
	v_cmp_lt_i32_e32 vcc, v2, v39
	v_lshlrev_b32_e32 v179, 4, v3
	v_add_u32_e32 v3, 4, v38
	v_cndmask_b32_e32 v2, v202, v2, vcc
	s_and_b32 s29, s1, 0xffffff80
	s_lshl_b32 s1, s34, 7
	v_lshlrev_b32_e32 v174, 8, v208
	v_lshlrev_b32_e32 v182, 2, v2
	v_bitop3_b32 v2, v38, v0, 15 bitop3:0x78
	v_bitop3_b32 v3, v3, v0, 15 bitop3:0x78
	v_add_u32_e32 v4, 8, v38
	v_add_u32_e32 v5, 12, v38
	s_and_b32 s1, s1, 0x180
	v_lshlrev_b32_e32 v170, 2, v38
	v_ashrrev_i32_e32 v176, 5, v0
	v_bitop3_b32 v4, v4, v0, 15 bitop3:0x78
	v_bitop3_b32 v0, v5, v0, 15 bitop3:0x78
	v_lshl_add_u32 v184, v2, 4, v174
	v_lshl_add_u32 v185, v3, 4, v174
	v_mov_b32_e32 v2, v1
	v_mov_b32_e32 v3, v1
	v_cvt_pk_bf16_f32 v127, v59, v60
	s_lshl_b32 s4, s1, 1
	v_add_u32_e32 v5, s85, v170
	v_lshl_add_u32 v187, v0, 4, v174
	v_mov_b32_e32 v0, v1
	v_mov_b64_e32 v[80:81], v[2:3]
	v_mov_b64_e32 v[84:85], v[2:3]
	v_mov_b64_e32 v[88:89], v[2:3]
	v_mov_b64_e32 v[92:93], v[2:3]
	v_mov_b64_e32 v[96:97], v[2:3]
	v_mov_b64_e32 v[76:77], v[2:3]
	v_mov_b64_e32 v[72:73], v[2:3]
	v_mov_b64_e32 v[68:69], v[2:3]
	v_mov_b64_e32 v[64:65], v[2:3]
	v_mov_b64_e32 v[60:61], v[2:3]
	v_mov_b64_e32 v[56:57], v[2:3]
	v_mov_b64_e32 v[52:53], v[2:3]
	v_mov_b64_e32 v[48:49], v[2:3]
	v_mov_b64_e32 v[44:45], v[2:3]
	v_mov_b64_e32 v[40:41], v[2:3]
	v_mov_b64_e32 v[36:37], v[2:3]
	v_mov_b64_e32 v[32:33], v[2:3]
	v_mov_b64_e32 v[28:29], v[2:3]
	v_mov_b64_e32 v[24:25], v[2:3]
	v_mov_b64_e32 v[20:21], v[2:3]
	v_mov_b64_e32 v[16:17], v[2:3]
	v_mov_b64_e32 v[12:13], v[2:3]
	v_mov_b64_e32 v[8:9], v[2:3]
	s_add_u32 s56, s22, s4
	v_sub_u32_e32 v183, v5, v208
	v_lshl_add_u32 v186, v4, 4, v174
	v_mov_b64_e32 v[78:79], v[0:1]
	v_mov_b64_e32 v[82:83], v[0:1]
	v_mov_b64_e32 v[86:87], v[0:1]
	v_mov_b64_e32 v[90:91], v[0:1]
	v_mov_b64_e32 v[94:95], v[0:1]
	v_mov_b64_e32 v[74:75], v[0:1]
	v_mov_b64_e32 v[70:71], v[0:1]
	v_mov_b64_e32 v[66:67], v[0:1]
	v_mov_b64_e32 v[62:63], v[0:1]
	v_mov_b64_e32 v[58:59], v[0:1]
	v_mov_b64_e32 v[54:55], v[0:1]
	v_mov_b64_e32 v[50:51], v[0:1]
	v_mov_b64_e32 v[46:47], v[0:1]
	v_mov_b64_e32 v[42:43], v[0:1]
	v_mov_b64_e32 v[38:39], v[0:1]
	v_mov_b64_e32 v[34:35], v[0:1]
	v_mov_b64_e32 v[30:31], v[0:1]
	v_mov_b64_e32 v[26:27], v[0:1]
	v_mov_b64_e32 v[22:23], v[0:1]
	v_mov_b64_e32 v[18:19], v[0:1]
	v_mov_b64_e32 v[14:15], v[0:1]
	v_mov_b64_e32 v[10:11], v[0:1]
	v_mov_b64_e32 v[6:7], v[0:1]
	v_mov_b64_e32 v[4:5], v[2:3]
	s_mov_b32 s0, 0
	s_addc_u32 s57, s23, 0
	v_and_b32_e32 v175, 8, v172
	v_mov_b32_e32 v206, 0
	v_mov_b32_e32 v207, 0
	v_mov_b32_e32 v209, 0
	v_mov_b64_e32 v[2:3], v[0:1]

; __device__ __forceinline__ void attn_phase(const Params& p, LAS unsigned char* lds, int li, int tid, int G, bf16_t* __restrict__ dst, const bf16_t* __restrict__ ZGA) {
;     ...
;         u32x2 gv[3][8];
; #pragma unroll
;         for (int mb = 0; mb < 3; ++mb) {
;             const int hh = mb, r = 16 * w + lq;
;             const bf16_t* gp = ZGA + (size_t)(t0 + r) * 1536 + (3 * hk + hh) * 128 + 4 * g;
; #pragma unroll
;             for (int db = 0; db < 8; ++db) gv[mb][db] = *(const u32x2*)(gp + 16 * db);
;         }
;         load_q(nitem >= 0 ? nitem : item, lq, g);
; #pragma unroll
;         for (int mb = 0; mb < 3; ++mb) {
;             const int hh = mb, r = 16 * w + lq;
;             const size_t tok = (size_t)(t0 + r); const int hcol = (3 * hk + hh) * 128 + 4 * g;
;             float lt = lrun[mb]; lt += __shfl_xor(lt, 16); lt += __shfl_xor(lt, 32);
;             lt += __builtin_amdgcn_exp2f(BS[hh * 260 + 257]);
;             const float inv = 1.f / lt;
; #pragma unroll
;             for (int db = 0; db < 8; ++db) {
;                 const f32x4 o = oacc[mb][db] * inv;
.LBB0_1060:
	s_setprio 0
	s_lshl_b32 s0, s39, 7
	s_add_i32 s0, s0, s89
	v_or_b32_e32 v198, s0, v208
	v_mov_b64_e32 v[98:99], s[54:55]
	s_movk_i32 s0, 0xc00
	v_mad_i64_i32 v[98:99], s[0:1], v198, s0, v[98:99]
	v_ashrrev_i32_e32 v171, 31, v170
	s_mulk_i32 s56, 0x180
	v_lshl_add_u64 v[98:99], v[170:171], 1, v[98:99]
	s_lshl_b32 s0, s56, 1
	s_mov_b32 s1, s57
	v_lshl_add_u64 v[98:99], v[98:99], 0, s[0:1]
	global_load_dwordx2 v[196:197], v[98:99], off
	global_load_dwordx2 v[194:195], v[98:99], off offset:32
	global_load_dwordx2 v[192:193], v[98:99], off offset:64
	global_load_dwordx2 v[190:191], v[98:99], off offset:96
	global_load_dwordx2 v[188:189], v[98:99], off offset:128
	global_load_dwordx2 v[186:187], v[98:99], off offset:160
	global_load_dwordx2 v[184:185], v[98:99], off offset:192
	global_load_dwordx2 v[182:183], v[98:99], off offset:224
	global_load_dwordx2 v[180:181], v[98:99], off offset:256
	global_load_dwordx2 v[178:179], v[98:99], off offset:288
	global_load_dwordx2 v[176:177], v[98:99], off offset:320
	global_load_dwordx2 v[174:175], v[98:99], off offset:352
	global_load_dwordx2 v[168:169], v[98:99], off offset:384
	global_load_dwordx2 v[166:167], v[98:99], off offset:416
	global_load_dwordx2 v[164:165], v[98:99], off offset:448
	global_load_dwordx2 v[162:163], v[98:99], off offset:480
	global_load_dwordx2 v[160:161], v[98:99], off offset:512
	global_load_dwordx2 v[158:159], v[98:99], off offset:544
	global_load_dwordx2 v[156:157], v[98:99], off offset:576
	global_load_dwordx2 v[154:155], v[98:99], off offset:608
	global_load_dwordx2 v[152:153], v[98:99], off offset:640
	global_load_dwordx2 v[150:151], v[98:99], off offset:672
	global_load_dwordx2 v[148:149], v[98:99], off offset:704
	global_load_dwordx2 v[146:147], v[98:99], off offset:736
	s_cmp_lt_i32 s38, 0
	s_cselect_b32 s0, s34, s38
	s_and_b32 s1, s0, 3
	s_lshl_b32 s0, s0, 5
	s_and_b32 s0, s0, 0xffffff80
	s_add_i32 s0, s0, s89
	v_or_b32_e32 v98, s0, v208
	v_ashrrev_i32_e32 v99, 31, v98
	v_lshlrev_b64 v[98:99], 12, v[98:99]
	v_lshl_add_u64 v[98:99], s[12:13], 0, v[98:99]
	s_mul_i32 s0, s1, 0x300
	s_mov_b32 s1, s57
	ds_bpermute_b32 v0, v204, v209
	v_lshl_add_u64 v[98:99], v[98:99], 0, s[0:1]
	v_lshl_add_u64 v[138:139], v[172:173], 1, v[98:99]
	v_mov_b32_e32 v140, s80
	global_load_dwordx4 v[110:113], v[138:139], off
	global_load_dwordx4 v[106:109], v[138:139], off offset:64
	global_load_dwordx4 v[102:105], v[138:139], off offset:128
	global_load_dwordx4 v[98:101], v[138:139], off offset:192
	global_load_dwordx4 v[134:137], v[138:139], off offset:256
	global_load_dwordx4 v[130:133], v[138:139], off offset:320
	global_load_dwordx4 v[126:129], v[138:139], off offset:384
	global_load_dwordx4 v[122:125], v[138:139], off offset:448
	global_load_dwordx4 v[118:121], v[138:139], off offset:512
	global_load_dwordx4 v[114:117], v[138:139], off offset:576
	ds_read_b32 v140, v140
	s_waitcnt lgkmcnt(0)
	v_add_f32_e32 v0, v209, v0
	ds_bpermute_b32 v172, v205, v0
	v_ashrrev_i32_e32 v199, 31, v198
	v_mov_b32_e32 v141, s14
	v_exp_f32_e32 v173, v140
	v_mov_b32_e32 v142, s15
	s_waitcnt lgkmcnt(0)
	v_add_f32_e32 v0, v0, v172
	ds_read_b32 v209, v141
	ds_read_b32 v208, v142
	v_add_f32_e32 v0, v0, v173
	v_div_scale_f32 v210, s[0:1], v0, v0, 1.0
	v_rcp_f32_e32 v211, v210
	v_lshlrev_b64 v[172:173], 12, v[198:199]
	v_add_u32_e32 v198, s56, v170
	v_lshl_add_u64 v[172:173], s[28:29], 0, v[172:173]
	v_fma_f32 v199, -v210, v211, 1.0
	v_fmac_f32_e32 v211, v199, v211
	v_div_scale_f32 v199, vcc, 1.0, v0, 1.0
	v_mul_f32_e32 v212, v199, v211
	v_fma_f32 v213, -v210, v212, v199
	v_fmac_f32_e32 v212, v213, v211
	v_fma_f32 v199, -v210, v212, v199
	v_div_fmas_f32 v199, v199, v211, v212
	v_div_fixup_f32 v0, v199, v0, 1.0
	v_pk_mul_f32 v[94:95], v[94:95], v[0:1] op_sel_hi:[1,0]
	v_ashrrev_i32_e32 v199, 31, v198
	v_pk_mul_f32 v[96:97], v[96:97], v[0:1] op_sel_hi:[1,0]
	v_lshl_add_u64 v[198:199], v[198:199], 1, v[172:173]
	global_load_dwordx4 v[142:145], v[138:139], off offset:640
	s_nop 0
	global_load_dwordx4 v[138:141], v[138:139], off offset:704
	v_pk_mul_f32 v[90:91], v[90:91], v[0:1] op_sel_hi:[1,0]
	v_pk_mul_f32 v[92:93], v[92:93], v[0:1] op_sel_hi:[1,0]
	v_pk_mul_f32 v[86:87], v[86:87], v[0:1] op_sel_hi:[1,0]
	v_pk_mul_f32 v[88:89], v[88:89], v[0:1] op_sel_hi:[1,0]
	v_pk_mul_f32 v[82:83], v[82:83], v[0:1] op_sel_hi:[1,0]
	v_pk_mul_f32 v[84:85], v[84:85], v[0:1] op_sel_hi:[1,0]
	v_pk_mul_f32 v[78:79], v[78:79], v[0:1] op_sel_hi:[1,0]
	s_waitcnt vmcnt(0)
; __device__ __forceinline__ unsigned cvt_pk_bf16(float lo, float hi) { unsigned r; asm("v_cvt_pk_bf16_f32 %0, %1, %2" : "=v"(r) : "v"(lo), "v"(hi)); return r; }
; __device__ __forceinline__ float silu_f(float x) { return x * __builtin_amdgcn_rcpf(1.f + __builtin_amdgcn_exp2f(-LOG2E * x)); }
; __device__ __forceinline__ void attn_phase(const Params& p, LAS unsigned char* lds, int li, int tid, int G, bf16_t* __restrict__ dst, const bf16_t* __restrict__ ZGA) {
;     ...
; #pragma unroll
;         for (int mb = 0; mb < 3; ++mb) {
;             const int hh = mb, r = 16 * w + lq;
;             const size_t tok = (size_t)(t0 + r); const int hcol = (3 * hk + hh) * 128 + 4 * g;
;             float lt = lrun[mb]; lt += __shfl_xor(lt, 16); lt += __shfl_xor(lt, 32);
;             lt += __builtin_amdgcn_exp2f(BS[hh * 260 + 257]);
;             const float inv = 1.f / lt;
; #pragma unroll
;             for (int db = 0; db < 8; ++db) {
;                 const f32x4 o = oacc[mb][db] * inv;
;                 u32x2 wv; wv.x = cvt_pk_bf16(o[0] * silu_f(bf_lo(gv[mb][db].x)), o[1] * silu_f(bf_hi(gv[mb][db].x))); wv.y = cvt_pk_bf16(o[2] * silu_f(bf_lo(gv[mb][db].y)), o[3] * silu_f(bf_hi(gv[mb][db].y)));
;                 *(u32x2*)(dst + tok * 2048 + hcol + 16 * db) = wv;
;             }
;         }
	v_lshlrev_b32_e32 v210, 16, v196
	v_mul_f32_e32 v211, 0xbfb8aa3b, v210
	v_exp_f32_e32 v211, v211
	v_and_b32_e32 v196, 0xffff0000, v196
	v_mul_f32_e32 v212, 0xbfb8aa3b, v196
	v_exp_f32_e32 v212, v212
	v_add_f32_e32 v211, 1.0, v211
	v_rcp_f32_e32 v211, v211
	v_pk_mul_f32 v[80:81], v[80:81], v[0:1] op_sel_hi:[1,0]
	v_add_f32_e32 v212, 1.0, v212
	v_rcp_f32_e32 v212, v212
	v_mul_f32_e32 v210, v211, v210
	v_mul_f32_e32 v94, v210, v94
	v_lshlrev_b32_e32 v210, 16, v197
	v_mul_f32_e32 v211, 0xbfb8aa3b, v210
	v_and_b32_e32 v197, 0xffff0000, v197
	v_mul_f32_e32 v196, v212, v196
	v_exp_f32_e32 v211, v211
	v_mul_f32_e32 v212, 0xbfb8aa3b, v197
	v_exp_f32_e32 v212, v212
	v_mul_f32_e32 v95, v196, v95
	v_add_f32_e32 v196, 1.0, v211
	v_rcp_f32_e32 v196, v196
	v_add_f32_e32 v211, 1.0, v212
	v_rcp_f32_e32 v211, v211
	v_cvt_pk_bf16_f32 v94, v94, v95
	v_mul_f32_e32 v95, v196, v210
	v_mul_f32_e32 v95, v95, v96
	v_mul_f32_e32 v96, v211, v197
	v_mul_f32_e32 v96, v96, v97
	v_cvt_pk_bf16_f32 v95, v95, v96
	global_store_dwordx2 v[198:199], v[94:95], off
	v_lshlrev_b32_e32 v94, 16, v194
	v_mul_f32_e32 v95, 0xbfb8aa3b, v94
	v_and_b32_e32 v96, 0xffff0000, v194
	v_exp_f32_e32 v95, v95
	v_mul_f32_e32 v97, 0xbfb8aa3b, v96
	v_exp_f32_e32 v97, v97
	v_pk_mul_f32 v[74:75], v[74:75], v[0:1] op_sel_hi:[1,0]
	v_add_f32_e32 v95, 1.0, v95
	v_rcp_f32_e32 v95, v95
	v_add_f32_e32 v97, 1.0, v97
	v_rcp_f32_e32 v97, v97
	v_pk_mul_f32 v[76:77], v[76:77], v[0:1] op_sel_hi:[1,0]
	v_mul_f32_e32 v94, v95, v94
	v_lshlrev_b32_e32 v95, 16, v195
	v_mul_f32_e32 v90, v94, v90
	v_mul_f32_e32 v94, v97, v96
	v_mul_f32_e32 v96, 0xbfb8aa3b, v95
	v_and_b32_e32 v97, 0xffff0000, v195
	v_exp_f32_e32 v96, v96
	v_mul_f32_e32 v194, 0xbfb8aa3b, v97
	v_exp_f32_e32 v194, v194
	v_mul_f32_e32 v91, v94, v91
	v_add_f32_e32 v94, 1.0, v96
	v_rcp_f32_e32 v94, v94
	v_add_f32_e32 v96, 1.0, v194
	v_rcp_f32_e32 v96, v96
	v_cvt_pk_bf16_f32 v90, v90, v91
	v_mul_f32_e32 v91, v94, v95
	v_mul_f32_e32 v91, v91, v92
	v_mul_f32_e32 v92, v96, v97
	v_mul_f32_e32 v92, v92, v93
	v_cvt_pk_bf16_f32 v91, v91, v92
	global_store_dwordx2 v[198:199], v[90:91], off offset:32
	v_lshlrev_b32_e32 v90, 16, v192
	v_mul_f32_e32 v91, 0xbfb8aa3b, v90
	v_and_b32_e32 v92, 0xffff0000, v192
	v_exp_f32_e32 v91, v91
	v_mul_f32_e32 v93, 0xbfb8aa3b, v92
	v_exp_f32_e32 v93, v93
	v_pk_mul_f32 v[70:71], v[70:71], v[0:1] op_sel_hi:[1,0]
	v_add_f32_e32 v91, 1.0, v91
	v_rcp_f32_e32 v91, v91
	v_add_f32_e32 v93, 1.0, v93
	v_rcp_f32_e32 v93, v93
	v_pk_mul_f32 v[72:73], v[72:73], v[0:1] op_sel_hi:[1,0]
	v_mul_f32_e32 v90, v91, v90
	v_lshlrev_b32_e32 v91, 16, v193
	v_mul_f32_e32 v86, v90, v86
	v_mul_f32_e32 v90, v93, v92
	v_mul_f32_e32 v92, 0xbfb8aa3b, v91
	v_and_b32_e32 v93, 0xffff0000, v193
	v_exp_f32_e32 v92, v92
	v_mul_f32_e32 v94, 0xbfb8aa3b, v93
	v_exp_f32_e32 v94, v94
	v_mul_f32_e32 v87, v90, v87
	v_add_f32_e32 v90, 1.0, v92
	v_rcp_f32_e32 v90, v90
	v_add_f32_e32 v92, 1.0, v94
	v_rcp_f32_e32 v92, v92
	v_cvt_pk_bf16_f32 v86, v86, v87
	v_mul_f32_e32 v87, v90, v91
	v_mul_f32_e32 v87, v87, v88
	v_mul_f32_e32 v88, v92, v93
	v_mul_f32_e32 v88, v88, v89
	v_cvt_pk_bf16_f32 v87, v87, v88
	global_store_dwordx2 v[198:199], v[86:87], off offset:64
	v_lshlrev_b32_e32 v86, 16, v190
	v_mul_f32_e32 v87, 0xbfb8aa3b, v86
	v_and_b32_e32 v88, 0xffff0000, v190
	v_exp_f32_e32 v87, v87
	v_mul_f32_e32 v89, 0xbfb8aa3b, v88
	v_exp_f32_e32 v89, v89
	v_pk_mul_f32 v[68:69], v[68:69], v[0:1] op_sel_hi:[1,0]
	v_add_f32_e32 v87, 1.0, v87
	v_rcp_f32_e32 v87, v87
	v_add_f32_e32 v89, 1.0, v89
	v_rcp_f32_e32 v89, v89
	v_pk_mul_f32 v[66:67], v[66:67], v[0:1] op_sel_hi:[1,0]
	v_mul_f32_e32 v86, v87, v86
	v_lshlrev_b32_e32 v87, 16, v191
	v_mul_f32_e32 v82, v86, v82
	v_mul_f32_e32 v86, v89, v88
	v_mul_f32_e32 v88, 0xbfb8aa3b, v87
	v_and_b32_e32 v89, 0xffff0000, v191
	v_exp_f32_e32 v88, v88
	v_mul_f32_e32 v90, 0xbfb8aa3b, v89
	v_exp_f32_e32 v90, v90
	v_mul_f32_e32 v83, v86, v83
	v_add_f32_e32 v86, 1.0, v88
	v_rcp_f32_e32 v86, v86
	v_add_f32_e32 v88, 1.0, v90
	v_rcp_f32_e32 v88, v88
	v_cvt_pk_bf16_f32 v82, v82, v83
	v_mul_f32_e32 v83, v86, v87
	v_mul_f32_e32 v83, v83, v84
	v_mul_f32_e32 v84, v88, v89
	v_mul_f32_e32 v84, v84, v85
	v_cvt_pk_bf16_f32 v83, v83, v84
	global_store_dwordx2 v[198:199], v[82:83], off offset:96
	v_lshlrev_b32_e32 v82, 16, v188
	v_mul_f32_e32 v83, 0xbfb8aa3b, v82
	v_and_b32_e32 v84, 0xffff0000, v188
	v_exp_f32_e32 v83, v83
	v_mul_f32_e32 v85, 0xbfb8aa3b, v84
	v_exp_f32_e32 v85, v85
	s_add_i32 s23, s23, s82
	v_add_f32_e32 v83, 1.0, v83
	v_rcp_f32_e32 v83, v83
	v_add_f32_e32 v85, 1.0, v85
	v_rcp_f32_e32 v85, v85
	s_cmp_eq_u32 s26, s21
	v_mul_f32_e32 v82, v83, v82
	v_lshlrev_b32_e32 v83, 16, v189
	v_mul_f32_e32 v78, v82, v78
	v_mul_f32_e32 v82, v85, v84
	v_mul_f32_e32 v84, 0xbfb8aa3b, v83
	v_and_b32_e32 v85, 0xffff0000, v189
	v_exp_f32_e32 v84, v84
	v_mul_f32_e32 v86, 0xbfb8aa3b, v85
	v_exp_f32_e32 v86, v86
	v_mul_f32_e32 v79, v82, v79
	v_add_f32_e32 v82, 1.0, v84
	v_rcp_f32_e32 v82, v82
	v_add_f32_e32 v84, 1.0, v86
	v_rcp_f32_e32 v84, v84
	v_cvt_pk_bf16_f32 v78, v78, v79
	v_mul_f32_e32 v79, v82, v83
	v_mul_f32_e32 v79, v79, v80
	v_mul_f32_e32 v80, v84, v85
	v_mul_f32_e32 v80, v80, v81
	v_cvt_pk_bf16_f32 v79, v79, v80
	global_store_dwordx2 v[198:199], v[78:79], off offset:128
	v_lshlrev_b32_e32 v78, 16, v186
	v_mul_f32_e32 v79, 0xbfb8aa3b, v78
	v_and_b32_e32 v80, 0xffff0000, v186
	v_exp_f32_e32 v79, v79
	v_mul_f32_e32 v81, 0xbfb8aa3b, v80
	v_exp_f32_e32 v81, v81
	v_add_f32_e32 v79, 1.0, v79
	v_rcp_f32_e32 v79, v79
	v_add_f32_e32 v81, 1.0, v81
	v_rcp_f32_e32 v81, v81
	v_mul_f32_e32 v78, v79, v78
	v_lshlrev_b32_e32 v79, 16, v187
	v_mul_f32_e32 v74, v78, v74
	v_mul_f32_e32 v78, v81, v80
; __device__ __forceinline__ unsigned cvt_pk_bf16(float lo, float hi) { unsigned r; asm("v_cvt_pk_bf16_f32 %0, %1, %2" : "=v"(r) : "v"(lo), "v"(hi)); return r; }
; __device__ __forceinline__ float silu_f(float x) { return x * __builtin_amdgcn_rcpf(1.f + __builtin_amdgcn_exp2f(-LOG2E * x)); }
; __device__ __forceinline__ void attn_phase(const Params& p, LAS unsigned char* lds, int li, int tid, int G, bf16_t* __restrict__ dst, const bf16_t* __restrict__ ZGA) {
;     ...
; #pragma unroll
;         for (int mb = 0; mb < 3; ++mb) {
;             const int hh = mb, r = 16 * w + lq;
;             const size_t tok = (size_t)(t0 + r); const int hcol = (3 * hk + hh) * 128 + 4 * g;
;             float lt = lrun[mb]; lt += __shfl_xor(lt, 16); lt += __shfl_xor(lt, 32);
;             lt += __builtin_amdgcn_exp2f(BS[hh * 260 + 257]);
;             const float inv = 1.f / lt;
; #pragma unroll
;             for (int db = 0; db < 8; ++db) {
;                 const f32x4 o = oacc[mb][db] * inv;
;                 u32x2 wv; wv.x = cvt_pk_bf16(o[0] * silu_f(bf_lo(gv[mb][db].x)), o[1] * silu_f(bf_hi(gv[mb][db].x))); wv.y = cvt_pk_bf16(o[2] * silu_f(bf_lo(gv[mb][db].y)), o[3] * silu_f(bf_hi(gv[mb][db].y)));
;                 *(u32x2*)(dst + tok * 2048 + hcol + 16 * db) = wv;
;             }
;         }
	v_mul_f32_e32 v80, 0xbfb8aa3b, v79
	v_and_b32_e32 v81, 0xffff0000, v187
	v_exp_f32_e32 v80, v80
	v_mul_f32_e32 v82, 0xbfb8aa3b, v81
	v_exp_f32_e32 v82, v82
	v_mul_f32_e32 v75, v78, v75
	v_add_f32_e32 v78, 1.0, v80
	v_rcp_f32_e32 v78, v78
	v_add_f32_e32 v80, 1.0, v82
	v_rcp_f32_e32 v80, v80
	v_cvt_pk_bf16_f32 v74, v74, v75
	v_mul_f32_e32 v75, v78, v79
	v_mul_f32_e32 v75, v75, v76
	v_mul_f32_e32 v76, v80, v81
	v_mul_f32_e32 v76, v76, v77
	v_cvt_pk_bf16_f32 v75, v75, v76
	global_store_dwordx2 v[198:199], v[74:75], off offset:160
	v_lshlrev_b32_e32 v74, 16, v184
	v_mul_f32_e32 v75, 0xbfb8aa3b, v74
	v_and_b32_e32 v76, 0xffff0000, v184
	v_exp_f32_e32 v75, v75
	v_mul_f32_e32 v77, 0xbfb8aa3b, v76
	v_exp_f32_e32 v77, v77
	v_add_f32_e32 v75, 1.0, v75
	v_rcp_f32_e32 v75, v75
	v_add_f32_e32 v77, 1.0, v77
	v_rcp_f32_e32 v77, v77
	v_mul_f32_e32 v74, v75, v74
	v_lshlrev_b32_e32 v75, 16, v185
	v_mul_f32_e32 v70, v74, v70
	v_mul_f32_e32 v74, v77, v76
	v_mul_f32_e32 v76, 0xbfb8aa3b, v75
	v_and_b32_e32 v77, 0xffff0000, v185
	v_exp_f32_e32 v76, v76
	v_mul_f32_e32 v78, 0xbfb8aa3b, v77
	v_exp_f32_e32 v78, v78
	v_mul_f32_e32 v71, v74, v71
	v_add_f32_e32 v74, 1.0, v76
	v_rcp_f32_e32 v74, v74
	v_add_f32_e32 v76, 1.0, v78
	v_rcp_f32_e32 v76, v76
	v_cvt_pk_bf16_f32 v70, v70, v71
	v_mul_f32_e32 v71, v74, v75
	v_mul_f32_e32 v71, v71, v72
	v_mul_f32_e32 v72, v76, v77
	v_mul_f32_e32 v72, v72, v73
	v_cvt_pk_bf16_f32 v71, v71, v72
	global_store_dwordx2 v[198:199], v[70:71], off offset:192
	v_lshlrev_b32_e32 v70, 16, v182
	v_mul_f32_e32 v71, 0xbfb8aa3b, v70
	v_and_b32_e32 v72, 0xffff0000, v182
	v_exp_f32_e32 v71, v71
	v_mul_f32_e32 v73, 0xbfb8aa3b, v72
	v_exp_f32_e32 v73, v73
	v_add_f32_e32 v71, 1.0, v71
	v_rcp_f32_e32 v71, v71
	v_add_f32_e32 v73, 1.0, v73
	v_rcp_f32_e32 v73, v73
	v_mul_f32_e32 v0, v71, v70
	v_mul_f32_e32 v0, v0, v66
	v_mul_f32_e32 v66, v73, v72
	v_mul_f32_e32 v66, v66, v67
	v_cvt_pk_bf16_f32 v66, v0, v66
	v_lshlrev_b32_e32 v0, 16, v183
	v_mul_f32_e32 v67, 0xbfb8aa3b, v0
	v_exp_f32_e32 v67, v67
	v_and_b32_e32 v70, 0xffff0000, v183
	ds_bpermute_b32 v72, v204, v207
	v_mul_f32_e32 v71, 0xbfb8aa3b, v70
	v_exp_f32_e32 v71, v71
	v_add_f32_e32 v67, 1.0, v67
	v_rcp_f32_e32 v67, v67
	s_waitcnt lgkmcnt(0)
	v_add_f32_e32 v72, v207, v72
	v_add_f32_e32 v71, 1.0, v71
	ds_bpermute_b32 v73, v205, v72
	v_rcp_f32_e32 v71, v71
	v_mul_f32_e32 v0, v67, v0
	v_exp_f32_e32 v67, v209
	v_mul_f32_e32 v0, v0, v68
	v_mul_f32_e32 v68, v71, v70
	s_waitcnt lgkmcnt(0)
	v_add_f32_e32 v70, v72, v73
	v_add_f32_e32 v70, v70, v67
	v_div_scale_f32 v71, s[0:1], v70, v70, 1.0
	v_rcp_f32_e32 v72, v71
	v_mul_f32_e32 v67, v68, v69
	v_cvt_pk_bf16_f32 v67, v0, v67
	global_store_dwordx2 v[198:199], v[66:67], off offset:224
	v_fma_f32 v0, -v71, v72, 1.0
	v_fmac_f32_e32 v72, v0, v72
	v_div_scale_f32 v0, vcc, 1.0, v70, 1.0
	v_mul_f32_e32 v66, v0, v72
	v_fma_f32 v67, -v71, v66, v0
	v_fmac_f32_e32 v66, v67, v72
	v_fma_f32 v0, -v71, v66, v0
	v_div_fmas_f32 v0, v0, v72, v66
	v_lshlrev_b32_e32 v68, 16, v180
	v_div_fixup_f32 v0, v0, v70, 1.0
	v_mul_f32_e32 v69, 0xbfb8aa3b, v68
	v_and_b32_e32 v70, 0xffff0000, v180
	v_exp_f32_e32 v69, v69
	v_mul_f32_e32 v71, 0xbfb8aa3b, v70
	v_exp_f32_e32 v71, v71
	v_pk_mul_f32 v[62:63], v[62:63], v[0:1] op_sel_hi:[1,0]
	v_add_f32_e32 v69, 1.0, v69
	v_rcp_f32_e32 v69, v69
	v_add_f32_e32 v71, 1.0, v71
	v_rcp_f32_e32 v71, v71
	v_lshl_add_u64 v[66:67], s[56:57], 0, v[170:171]
	v_mul_f32_e32 v68, v69, v68
	v_lshlrev_b32_e32 v69, 16, v181
	v_mul_f32_e32 v62, v68, v62
	v_mul_f32_e32 v68, v71, v70
	v_mul_f32_e32 v70, 0xbfb8aa3b, v69
	v_and_b32_e32 v71, 0xffff0000, v181
	v_exp_f32_e32 v70, v70
	v_mul_f32_e32 v72, 0xbfb8aa3b, v71
	v_exp_f32_e32 v72, v72
	v_mul_f32_e32 v63, v68, v63
	v_add_f32_e32 v68, 1.0, v70
	v_rcp_f32_e32 v68, v68
	v_add_f32_e32 v70, 1.0, v72
	v_rcp_f32_e32 v70, v70
	v_pk_mul_f32 v[64:65], v[64:65], v[0:1] op_sel_hi:[1,0]
	v_cvt_pk_bf16_f32 v62, v62, v63
	v_mul_f32_e32 v63, v68, v69
	v_lshl_add_u64 v[66:67], v[66:67], 1, v[172:173]
	v_mul_f32_e32 v63, v63, v64
	v_mul_f32_e32 v64, v70, v71
	v_mul_f32_e32 v64, v64, v65
	v_cvt_pk_bf16_f32 v63, v63, v64
	global_store_dwordx2 v[66:67], v[62:63], off offset:256
	v_lshlrev_b32_e32 v62, 16, v178
	v_mul_f32_e32 v63, 0xbfb8aa3b, v62
	v_and_b32_e32 v64, 0xffff0000, v178
	v_exp_f32_e32 v63, v63
	v_mul_f32_e32 v65, 0xbfb8aa3b, v64
	v_exp_f32_e32 v65, v65
	v_pk_mul_f32 v[58:59], v[58:59], v[0:1] op_sel_hi:[1,0]
	v_add_f32_e32 v63, 1.0, v63
	v_rcp_f32_e32 v63, v63
	v_add_f32_e32 v65, 1.0, v65
	v_rcp_f32_e32 v65, v65
	v_pk_mul_f32 v[60:61], v[60:61], v[0:1] op_sel_hi:[1,0]
	v_mul_f32_e32 v62, v63, v62
	v_lshlrev_b32_e32 v63, 16, v179
	v_mul_f32_e32 v58, v62, v58
	v_mul_f32_e32 v62, v65, v64
	v_mul_f32_e32 v64, 0xbfb8aa3b, v63
	v_and_b32_e32 v65, 0xffff0000, v179
	v_exp_f32_e32 v64, v64
	v_mul_f32_e32 v68, 0xbfb8aa3b, v65
	v_exp_f32_e32 v68, v68
	v_mul_f32_e32 v59, v62, v59
	v_add_f32_e32 v62, 1.0, v64
	v_rcp_f32_e32 v62, v62
	v_add_f32_e32 v64, 1.0, v68
	v_rcp_f32_e32 v64, v64
	v_cvt_pk_bf16_f32 v58, v58, v59
	v_mul_f32_e32 v59, v62, v63
	v_mul_f32_e32 v59, v59, v60
	v_mul_f32_e32 v60, v64, v65
	v_mul_f32_e32 v60, v60, v61
	v_cvt_pk_bf16_f32 v59, v59, v60
	global_store_dwordx2 v[66:67], v[58:59], off offset:288
	v_lshlrev_b32_e32 v58, 16, v176
	v_mul_f32_e32 v59, 0xbfb8aa3b, v58
	v_and_b32_e32 v60, 0xffff0000, v176
	v_exp_f32_e32 v59, v59
	v_mul_f32_e32 v61, 0xbfb8aa3b, v60
	v_exp_f32_e32 v61, v61
	v_pk_mul_f32 v[54:55], v[54:55], v[0:1] op_sel_hi:[1,0]
	v_add_f32_e32 v59, 1.0, v59
	v_rcp_f32_e32 v59, v59
	v_add_f32_e32 v61, 1.0, v61
	v_rcp_f32_e32 v61, v61
	v_pk_mul_f32 v[56:57], v[56:57], v[0:1] op_sel_hi:[1,0]
	v_mul_f32_e32 v58, v59, v58
; __device__ __forceinline__ unsigned cvt_pk_bf16(float lo, float hi) { unsigned r; asm("v_cvt_pk_bf16_f32 %0, %1, %2" : "=v"(r) : "v"(lo), "v"(hi)); return r; }
; __device__ __forceinline__ float silu_f(float x) { return x * __builtin_amdgcn_rcpf(1.f + __builtin_amdgcn_exp2f(-LOG2E * x)); }
; __device__ __forceinline__ void attn_phase(const Params& p, LAS unsigned char* lds, int li, int tid, int G, bf16_t* __restrict__ dst, const bf16_t* __restrict__ ZGA) {
;     ...
; #pragma unroll
;         for (int mb = 0; mb < 3; ++mb) {
;             const int hh = mb, r = 16 * w + lq;
;             const size_t tok = (size_t)(t0 + r); const int hcol = (3 * hk + hh) * 128 + 4 * g;
;             float lt = lrun[mb]; lt += __shfl_xor(lt, 16); lt += __shfl_xor(lt, 32);
;             lt += __builtin_amdgcn_exp2f(BS[hh * 260 + 257]);
;             const float inv = 1.f / lt;
; #pragma unroll
;             for (int db = 0; db < 8; ++db) {
;                 const f32x4 o = oacc[mb][db] * inv;
;                 u32x2 wv; wv.x = cvt_pk_bf16(o[0] * silu_f(bf_lo(gv[mb][db].x)), o[1] * silu_f(bf_hi(gv[mb][db].x))); wv.y = cvt_pk_bf16(o[2] * silu_f(bf_lo(gv[mb][db].y)), o[3] * silu_f(bf_hi(gv[mb][db].y)));
;                 *(u32x2*)(dst + tok * 2048 + hcol + 16 * db) = wv;
;             }
;         }
	v_lshlrev_b32_e32 v59, 16, v177
	v_mul_f32_e32 v54, v58, v54
	v_mul_f32_e32 v58, v61, v60
	v_mul_f32_e32 v60, 0xbfb8aa3b, v59
	v_and_b32_e32 v61, 0xffff0000, v177
	v_exp_f32_e32 v60, v60
	v_mul_f32_e32 v62, 0xbfb8aa3b, v61
	v_exp_f32_e32 v62, v62
	v_mul_f32_e32 v55, v58, v55
	v_add_f32_e32 v58, 1.0, v60
	v_rcp_f32_e32 v58, v58
	v_add_f32_e32 v60, 1.0, v62
	v_rcp_f32_e32 v60, v60
	v_cvt_pk_bf16_f32 v54, v54, v55
	v_mul_f32_e32 v55, v58, v59
	v_mul_f32_e32 v55, v55, v56
	v_mul_f32_e32 v56, v60, v61
	v_mul_f32_e32 v56, v56, v57
	v_cvt_pk_bf16_f32 v55, v55, v56
	global_store_dwordx2 v[66:67], v[54:55], off offset:320
	v_lshlrev_b32_e32 v54, 16, v174
	v_mul_f32_e32 v55, 0xbfb8aa3b, v54
	v_and_b32_e32 v56, 0xffff0000, v174
	v_exp_f32_e32 v55, v55
	v_mul_f32_e32 v57, 0xbfb8aa3b, v56
	v_exp_f32_e32 v57, v57
	v_pk_mul_f32 v[50:51], v[50:51], v[0:1] op_sel_hi:[1,0]
	v_add_f32_e32 v55, 1.0, v55
	v_rcp_f32_e32 v55, v55
	v_add_f32_e32 v57, 1.0, v57
	v_rcp_f32_e32 v57, v57
	v_pk_mul_f32 v[52:53], v[52:53], v[0:1] op_sel_hi:[1,0]
	v_mul_f32_e32 v54, v55, v54
	v_lshlrev_b32_e32 v55, 16, v175
	v_mul_f32_e32 v50, v54, v50
	v_mul_f32_e32 v54, v57, v56
	v_mul_f32_e32 v56, 0xbfb8aa3b, v55
	v_and_b32_e32 v57, 0xffff0000, v175
	v_exp_f32_e32 v56, v56
	v_mul_f32_e32 v58, 0xbfb8aa3b, v57
	v_exp_f32_e32 v58, v58
	v_mul_f32_e32 v51, v54, v51
	v_add_f32_e32 v54, 1.0, v56
	v_rcp_f32_e32 v54, v54
	v_add_f32_e32 v56, 1.0, v58
	v_rcp_f32_e32 v56, v56
	v_cvt_pk_bf16_f32 v50, v50, v51
	v_mul_f32_e32 v51, v54, v55
	v_mul_f32_e32 v51, v51, v52
	v_mul_f32_e32 v52, v56, v57
	v_mul_f32_e32 v52, v52, v53
	v_cvt_pk_bf16_f32 v51, v51, v52
	global_store_dwordx2 v[66:67], v[50:51], off offset:352
	v_lshlrev_b32_e32 v50, 16, v168
	v_mul_f32_e32 v51, 0xbfb8aa3b, v50
	v_and_b32_e32 v52, 0xffff0000, v168
	v_exp_f32_e32 v51, v51
	v_mul_f32_e32 v53, 0xbfb8aa3b, v52
	v_exp_f32_e32 v53, v53
	v_pk_mul_f32 v[46:47], v[46:47], v[0:1] op_sel_hi:[1,0]
	v_add_f32_e32 v51, 1.0, v51
	v_rcp_f32_e32 v51, v51
	v_add_f32_e32 v53, 1.0, v53
	v_rcp_f32_e32 v53, v53
	v_pk_mul_f32 v[48:49], v[48:49], v[0:1] op_sel_hi:[1,0]
	v_mul_f32_e32 v50, v51, v50
	v_lshlrev_b32_e32 v51, 16, v169
	v_mul_f32_e32 v46, v50, v46
	v_mul_f32_e32 v50, v53, v52
	v_mul_f32_e32 v52, 0xbfb8aa3b, v51
	v_and_b32_e32 v53, 0xffff0000, v169
	v_exp_f32_e32 v52, v52
	v_mul_f32_e32 v54, 0xbfb8aa3b, v53
	v_exp_f32_e32 v54, v54
	v_mul_f32_e32 v47, v50, v47
	v_add_f32_e32 v50, 1.0, v52
	v_rcp_f32_e32 v50, v50
	v_add_f32_e32 v52, 1.0, v54
	v_rcp_f32_e32 v52, v52
	v_cvt_pk_bf16_f32 v46, v46, v47
	v_mul_f32_e32 v47, v50, v51
	v_mul_f32_e32 v47, v47, v48
	v_mul_f32_e32 v48, v52, v53
	v_mul_f32_e32 v48, v48, v49
	v_cvt_pk_bf16_f32 v47, v47, v48
	global_store_dwordx2 v[66:67], v[46:47], off offset:384
	v_lshlrev_b32_e32 v46, 16, v166
	v_mul_f32_e32 v47, 0xbfb8aa3b, v46
	v_and_b32_e32 v48, 0xffff0000, v166
	v_exp_f32_e32 v47, v47
	v_mul_f32_e32 v49, 0xbfb8aa3b, v48
	v_exp_f32_e32 v49, v49
	v_pk_mul_f32 v[42:43], v[42:43], v[0:1] op_sel_hi:[1,0]
	v_add_f32_e32 v47, 1.0, v47
	v_rcp_f32_e32 v47, v47
	v_add_f32_e32 v49, 1.0, v49
	v_rcp_f32_e32 v49, v49
	v_pk_mul_f32 v[44:45], v[44:45], v[0:1] op_sel_hi:[1,0]
	v_mul_f32_e32 v46, v47, v46
	v_lshlrev_b32_e32 v47, 16, v167
	v_mul_f32_e32 v42, v46, v42
	v_mul_f32_e32 v46, v49, v48
	v_mul_f32_e32 v48, 0xbfb8aa3b, v47
	v_and_b32_e32 v49, 0xffff0000, v167
	v_exp_f32_e32 v48, v48
	v_mul_f32_e32 v50, 0xbfb8aa3b, v49
	v_exp_f32_e32 v50, v50
	v_mul_f32_e32 v43, v46, v43
	v_add_f32_e32 v46, 1.0, v48
	v_rcp_f32_e32 v46, v46
	v_add_f32_e32 v48, 1.0, v50
	v_rcp_f32_e32 v48, v48
	v_cvt_pk_bf16_f32 v42, v42, v43
	v_mul_f32_e32 v43, v46, v47
	v_mul_f32_e32 v43, v43, v44
	v_mul_f32_e32 v44, v48, v49
	v_mul_f32_e32 v44, v44, v45
	v_cvt_pk_bf16_f32 v43, v43, v44
	global_store_dwordx2 v[66:67], v[42:43], off offset:416
	v_lshlrev_b32_e32 v42, 16, v164
	v_mul_f32_e32 v43, 0xbfb8aa3b, v42
	v_and_b32_e32 v44, 0xffff0000, v164
	v_exp_f32_e32 v43, v43
	v_mul_f32_e32 v45, 0xbfb8aa3b, v44
	v_exp_f32_e32 v45, v45
	v_pk_mul_f32 v[38:39], v[38:39], v[0:1] op_sel_hi:[1,0]
	v_add_f32_e32 v43, 1.0, v43
	v_rcp_f32_e32 v43, v43
	v_add_f32_e32 v45, 1.0, v45
	v_rcp_f32_e32 v45, v45
	v_pk_mul_f32 v[40:41], v[40:41], v[0:1] op_sel_hi:[1,0]
	v_mul_f32_e32 v42, v43, v42
	v_lshlrev_b32_e32 v43, 16, v165
	v_mul_f32_e32 v38, v42, v38
	v_mul_f32_e32 v42, v45, v44
	v_mul_f32_e32 v44, 0xbfb8aa3b, v43
	v_and_b32_e32 v45, 0xffff0000, v165
	v_exp_f32_e32 v44, v44
	v_mul_f32_e32 v46, 0xbfb8aa3b, v45
	v_exp_f32_e32 v46, v46
	v_mul_f32_e32 v39, v42, v39
	v_add_f32_e32 v42, 1.0, v44
	v_rcp_f32_e32 v42, v42
	v_add_f32_e32 v44, 1.0, v46
	v_rcp_f32_e32 v44, v44
	v_cvt_pk_bf16_f32 v38, v38, v39
	v_mul_f32_e32 v39, v42, v43
	v_mul_f32_e32 v39, v39, v40
	v_mul_f32_e32 v40, v44, v45
	v_mul_f32_e32 v40, v40, v41
	v_cvt_pk_bf16_f32 v39, v39, v40
	global_store_dwordx2 v[66:67], v[38:39], off offset:448
	v_lshlrev_b32_e32 v38, 16, v162
	v_mul_f32_e32 v39, 0xbfb8aa3b, v38
	v_and_b32_e32 v40, 0xffff0000, v162
	v_exp_f32_e32 v39, v39
	v_mul_f32_e32 v41, 0xbfb8aa3b, v40
	v_exp_f32_e32 v41, v41
	v_pk_mul_f32 v[36:37], v[36:37], v[0:1] op_sel_hi:[1,0]
	v_add_f32_e32 v39, 1.0, v39
	v_rcp_f32_e32 v39, v39
	v_add_f32_e32 v41, 1.0, v41
	v_rcp_f32_e32 v41, v41
	v_pk_mul_f32 v[34:35], v[34:35], v[0:1] op_sel_hi:[1,0]
	v_mul_f32_e32 v0, v39, v38
	v_mul_f32_e32 v0, v0, v34
	v_mul_f32_e32 v34, v41, v40
	v_mul_f32_e32 v34, v34, v35
	v_cvt_pk_bf16_f32 v34, v0, v34
	v_lshlrev_b32_e32 v0, 16, v163
	v_mul_f32_e32 v35, 0xbfb8aa3b, v0
	v_exp_f32_e32 v35, v35
	v_and_b32_e32 v38, 0xffff0000, v163
	ds_bpermute_b32 v40, v204, v206
	v_mul_f32_e32 v39, 0xbfb8aa3b, v38
	v_exp_f32_e32 v39, v39
	v_add_f32_e32 v35, 1.0, v35
	v_rcp_f32_e32 v35, v35
	s_waitcnt lgkmcnt(0)
; __device__ __forceinline__ unsigned cvt_pk_bf16(float lo, float hi) { unsigned r; asm("v_cvt_pk_bf16_f32 %0, %1, %2" : "=v"(r) : "v"(lo), "v"(hi)); return r; }
; __device__ __forceinline__ float silu_f(float x) { return x * __builtin_amdgcn_rcpf(1.f + __builtin_amdgcn_exp2f(-LOG2E * x)); }
; __device__ __forceinline__ void attn_phase(const Params& p, LAS unsigned char* lds, int li, int tid, int G, bf16_t* __restrict__ dst, const bf16_t* __restrict__ ZGA) {
;     ...
; #pragma unroll
;         for (int mb = 0; mb < 3; ++mb) {
;             const int hh = mb, r = 16 * w + lq;
;             const size_t tok = (size_t)(t0 + r); const int hcol = (3 * hk + hh) * 128 + 4 * g;
;             float lt = lrun[mb]; lt += __shfl_xor(lt, 16); lt += __shfl_xor(lt, 32);
;             lt += __builtin_amdgcn_exp2f(BS[hh * 260 + 257]);
;             const float inv = 1.f / lt;
; #pragma unroll
;             for (int db = 0; db < 8; ++db) {
;                 const f32x4 o = oacc[mb][db] * inv;
;                 u32x2 wv; wv.x = cvt_pk_bf16(o[0] * silu_f(bf_lo(gv[mb][db].x)), o[1] * silu_f(bf_hi(gv[mb][db].x))); wv.y = cvt_pk_bf16(o[2] * silu_f(bf_lo(gv[mb][db].y)), o[3] * silu_f(bf_hi(gv[mb][db].y)));
;                 *(u32x2*)(dst + tok * 2048 + hcol + 16 * db) = wv;
;             }
;         }
	v_add_f32_e32 v40, v206, v40
	v_add_f32_e32 v39, 1.0, v39
	ds_bpermute_b32 v41, v205, v40
	v_rcp_f32_e32 v39, v39
	v_mul_f32_e32 v0, v35, v0
	v_exp_f32_e32 v35, v208
	v_mul_f32_e32 v0, v0, v36
	v_mul_f32_e32 v36, v39, v38
	s_waitcnt lgkmcnt(0)
	v_add_f32_e32 v38, v40, v41
	v_add_f32_e32 v38, v38, v35
	v_div_scale_f32 v39, s[0:1], v38, v38, 1.0
	v_rcp_f32_e32 v40, v39
	v_mul_f32_e32 v35, v36, v37
	v_cvt_pk_bf16_f32 v35, v0, v35
	global_store_dwordx2 v[66:67], v[34:35], off offset:480
	v_fma_f32 v0, -v39, v40, 1.0
	v_fmac_f32_e32 v40, v0, v40
	v_div_scale_f32 v0, vcc, 1.0, v38, 1.0
	v_mul_f32_e32 v34, v0, v40
	v_fma_f32 v35, -v39, v34, v0
	v_fmac_f32_e32 v34, v35, v40
	v_fma_f32 v0, -v39, v34, v0
	v_div_fmas_f32 v0, v0, v40, v34
	v_lshlrev_b32_e32 v34, 16, v160
	v_mul_f32_e32 v35, 0xbfb8aa3b, v34
	v_and_b32_e32 v36, 0xffff0000, v160
	v_exp_f32_e32 v35, v35
	v_mul_f32_e32 v37, 0xbfb8aa3b, v36
	v_exp_f32_e32 v37, v37
	v_div_fixup_f32 v0, v0, v38, 1.0
	v_add_f32_e32 v35, 1.0, v35
	v_rcp_f32_e32 v35, v35
	v_add_f32_e32 v37, 1.0, v37
	v_rcp_f32_e32 v37, v37
	v_pk_mul_f32 v[30:31], v[30:31], v[0:1] op_sel_hi:[1,0]
	v_mul_f32_e32 v34, v35, v34
	v_lshlrev_b32_e32 v35, 16, v161
	v_mul_f32_e32 v30, v34, v30
	v_mul_f32_e32 v34, v37, v36
	v_mul_f32_e32 v36, 0xbfb8aa3b, v35
	v_and_b32_e32 v37, 0xffff0000, v161
	v_exp_f32_e32 v36, v36
	v_mul_f32_e32 v38, 0xbfb8aa3b, v37
	v_exp_f32_e32 v38, v38
	v_mul_f32_e32 v31, v34, v31
	v_add_f32_e32 v34, 1.0, v36
	v_rcp_f32_e32 v34, v34
	v_add_f32_e32 v36, 1.0, v38
	v_rcp_f32_e32 v36, v36
	v_pk_mul_f32 v[32:33], v[32:33], v[0:1] op_sel_hi:[1,0]
	v_cvt_pk_bf16_f32 v30, v30, v31
	v_mul_f32_e32 v31, v34, v35
	v_mul_f32_e32 v31, v31, v32
	v_mul_f32_e32 v32, v36, v37
	v_mul_f32_e32 v32, v32, v33
	v_cvt_pk_bf16_f32 v31, v31, v32
	global_store_dwordx2 v[66:67], v[30:31], off offset:512
	v_lshlrev_b32_e32 v30, 16, v158
	v_mul_f32_e32 v31, 0xbfb8aa3b, v30
	v_and_b32_e32 v32, 0xffff0000, v158
	v_exp_f32_e32 v31, v31
	v_mul_f32_e32 v33, 0xbfb8aa3b, v32
	v_exp_f32_e32 v33, v33
	v_pk_mul_f32 v[26:27], v[26:27], v[0:1] op_sel_hi:[1,0]
	v_add_f32_e32 v31, 1.0, v31
	v_rcp_f32_e32 v31, v31
	v_add_f32_e32 v33, 1.0, v33
	v_rcp_f32_e32 v33, v33
	v_pk_mul_f32 v[28:29], v[28:29], v[0:1] op_sel_hi:[1,0]
	v_mul_f32_e32 v30, v31, v30
	v_lshlrev_b32_e32 v31, 16, v159
	v_mul_f32_e32 v26, v30, v26
	v_mul_f32_e32 v30, v33, v32
	v_mul_f32_e32 v32, 0xbfb8aa3b, v31
	v_and_b32_e32 v33, 0xffff0000, v159
	v_exp_f32_e32 v32, v32
	v_mul_f32_e32 v34, 0xbfb8aa3b, v33
	v_exp_f32_e32 v34, v34
	v_mul_f32_e32 v27, v30, v27
	v_add_f32_e32 v30, 1.0, v32
	v_rcp_f32_e32 v30, v30
	v_add_f32_e32 v32, 1.0, v34
	v_rcp_f32_e32 v32, v32
	v_cvt_pk_bf16_f32 v26, v26, v27
	v_mul_f32_e32 v27, v30, v31
	v_mul_f32_e32 v27, v27, v28
	v_mul_f32_e32 v28, v32, v33
	v_mul_f32_e32 v28, v28, v29
	v_cvt_pk_bf16_f32 v27, v27, v28
	global_store_dwordx2 v[66:67], v[26:27], off offset:544
	v_lshlrev_b32_e32 v26, 16, v156
	v_mul_f32_e32 v27, 0xbfb8aa3b, v26
	v_and_b32_e32 v28, 0xffff0000, v156
	v_exp_f32_e32 v27, v27
	v_mul_f32_e32 v29, 0xbfb8aa3b, v28
	v_exp_f32_e32 v29, v29
	v_pk_mul_f32 v[22:23], v[22:23], v[0:1] op_sel_hi:[1,0]
	v_add_f32_e32 v27, 1.0, v27
	v_rcp_f32_e32 v27, v27
	v_add_f32_e32 v29, 1.0, v29
	v_rcp_f32_e32 v29, v29
	v_pk_mul_f32 v[24:25], v[24:25], v[0:1] op_sel_hi:[1,0]
	v_mul_f32_e32 v26, v27, v26
	v_lshlrev_b32_e32 v27, 16, v157
	v_mul_f32_e32 v22, v26, v22
	v_mul_f32_e32 v26, v29, v28
	v_mul_f32_e32 v28, 0xbfb8aa3b, v27
	v_and_b32_e32 v29, 0xffff0000, v157
	v_exp_f32_e32 v28, v28
	v_mul_f32_e32 v30, 0xbfb8aa3b, v29
	v_exp_f32_e32 v30, v30
	v_mul_f32_e32 v23, v26, v23
	v_add_f32_e32 v26, 1.0, v28
	v_rcp_f32_e32 v26, v26
	v_add_f32_e32 v28, 1.0, v30
	v_rcp_f32_e32 v28, v28
	v_cvt_pk_bf16_f32 v22, v22, v23
	v_mul_f32_e32 v23, v26, v27
	v_mul_f32_e32 v23, v23, v24
	v_mul_f32_e32 v24, v28, v29
	v_mul_f32_e32 v24, v24, v25
	v_cvt_pk_bf16_f32 v23, v23, v24
	global_store_dwordx2 v[66:67], v[22:23], off offset:576
	v_lshlrev_b32_e32 v22, 16, v154
	v_mul_f32_e32 v23, 0xbfb8aa3b, v22
	v_and_b32_e32 v24, 0xffff0000, v154
	v_exp_f32_e32 v23, v23
	v_mul_f32_e32 v25, 0xbfb8aa3b, v24
	v_exp_f32_e32 v25, v25
	v_pk_mul_f32 v[18:19], v[18:19], v[0:1] op_sel_hi:[1,0]
	v_add_f32_e32 v23, 1.0, v23
	v_rcp_f32_e32 v23, v23
	v_add_f32_e32 v25, 1.0, v25
	v_rcp_f32_e32 v25, v25
	v_pk_mul_f32 v[20:21], v[20:21], v[0:1] op_sel_hi:[1,0]
	v_mul_f32_e32 v22, v23, v22
	v_lshlrev_b32_e32 v23, 16, v155
	v_mul_f32_e32 v18, v22, v18
	v_mul_f32_e32 v22, v25, v24
	v_mul_f32_e32 v24, 0xbfb8aa3b, v23
	v_and_b32_e32 v25, 0xffff0000, v155
	v_exp_f32_e32 v24, v24
; __device__ __forceinline__ unsigned cvt_pk_bf16(float lo, float hi) { unsigned r; asm("v_cvt_pk_bf16_f32 %0, %1, %2" : "=v"(r) : "v"(lo), "v"(hi)); return r; }
; __device__ __forceinline__ float silu_f(float x) { return x * __builtin_amdgcn_rcpf(1.f + __builtin_amdgcn_exp2f(-LOG2E * x)); }
; __device__ __forceinline__ void attn_phase(const Params& p, LAS unsigned char* lds, int li, int tid, int G, bf16_t* __restrict__ dst, const bf16_t* __restrict__ ZGA) {
;     ...
; #pragma unroll
;         for (int mb = 0; mb < 3; ++mb) {
;             const int hh = mb, r = 16 * w + lq;
;             const size_t tok = (size_t)(t0 + r); const int hcol = (3 * hk + hh) * 128 + 4 * g;
;             float lt = lrun[mb]; lt += __shfl_xor(lt, 16); lt += __shfl_xor(lt, 32);
;             lt += __builtin_amdgcn_exp2f(BS[hh * 260 + 257]);
;             const float inv = 1.f / lt;
; #pragma unroll
;             for (int db = 0; db < 8; ++db) {
;                 const f32x4 o = oacc[mb][db] * inv;
;                 u32x2 wv; wv.x = cvt_pk_bf16(o[0] * silu_f(bf_lo(gv[mb][db].x)), o[1] * silu_f(bf_hi(gv[mb][db].x))); wv.y = cvt_pk_bf16(o[2] * silu_f(bf_lo(gv[mb][db].y)), o[3] * silu_f(bf_hi(gv[mb][db].y)));
;                 *(u32x2*)(dst + tok * 2048 + hcol + 16 * db) = wv;
;             }
;         }
	v_mul_f32_e32 v26, 0xbfb8aa3b, v25
	v_exp_f32_e32 v26, v26
	v_mul_f32_e32 v19, v22, v19
	v_add_f32_e32 v22, 1.0, v24
	v_rcp_f32_e32 v22, v22
	v_add_f32_e32 v24, 1.0, v26
	v_rcp_f32_e32 v24, v24
	v_cvt_pk_bf16_f32 v18, v18, v19
	v_mul_f32_e32 v19, v22, v23
	v_mul_f32_e32 v19, v19, v20
	v_mul_f32_e32 v20, v24, v25
	v_mul_f32_e32 v20, v20, v21
	v_cvt_pk_bf16_f32 v19, v19, v20
	global_store_dwordx2 v[66:67], v[18:19], off offset:608
	v_lshlrev_b32_e32 v18, 16, v152
	v_mul_f32_e32 v19, 0xbfb8aa3b, v18
	v_and_b32_e32 v20, 0xffff0000, v152
	v_exp_f32_e32 v19, v19
	v_mul_f32_e32 v21, 0xbfb8aa3b, v20
	v_exp_f32_e32 v21, v21
	v_pk_mul_f32 v[14:15], v[14:15], v[0:1] op_sel_hi:[1,0]
	v_add_f32_e32 v19, 1.0, v19
	v_rcp_f32_e32 v19, v19
	v_add_f32_e32 v21, 1.0, v21
	v_rcp_f32_e32 v21, v21
	v_pk_mul_f32 v[16:17], v[16:17], v[0:1] op_sel_hi:[1,0]
	v_mul_f32_e32 v18, v19, v18
	v_lshlrev_b32_e32 v19, 16, v153
	v_mul_f32_e32 v14, v18, v14
	v_mul_f32_e32 v18, v21, v20
	v_mul_f32_e32 v20, 0xbfb8aa3b, v19
	v_and_b32_e32 v21, 0xffff0000, v153
	v_exp_f32_e32 v20, v20
	v_mul_f32_e32 v22, 0xbfb8aa3b, v21
	v_exp_f32_e32 v22, v22
	v_mul_f32_e32 v15, v18, v15
	v_add_f32_e32 v18, 1.0, v20
	v_rcp_f32_e32 v18, v18
	v_add_f32_e32 v20, 1.0, v22
	v_rcp_f32_e32 v20, v20
	v_cvt_pk_bf16_f32 v14, v14, v15
	v_mul_f32_e32 v15, v18, v19
	v_mul_f32_e32 v15, v15, v16
	v_mul_f32_e32 v16, v20, v21
	v_mul_f32_e32 v16, v16, v17
	v_cvt_pk_bf16_f32 v15, v15, v16
	global_store_dwordx2 v[66:67], v[14:15], off offset:640
	v_lshlrev_b32_e32 v14, 16, v150
	v_mul_f32_e32 v15, 0xbfb8aa3b, v14
	v_and_b32_e32 v16, 0xffff0000, v150
	v_exp_f32_e32 v15, v15
	v_mul_f32_e32 v17, 0xbfb8aa3b, v16
	v_exp_f32_e32 v17, v17
	v_pk_mul_f32 v[10:11], v[10:11], v[0:1] op_sel_hi:[1,0]
	v_add_f32_e32 v15, 1.0, v15
	v_rcp_f32_e32 v15, v15
	v_add_f32_e32 v17, 1.0, v17
	v_rcp_f32_e32 v17, v17
	v_pk_mul_f32 v[12:13], v[12:13], v[0:1] op_sel_hi:[1,0]
	v_mul_f32_e32 v14, v15, v14
	v_lshlrev_b32_e32 v15, 16, v151
	v_mul_f32_e32 v10, v14, v10
	v_mul_f32_e32 v14, v17, v16
	v_mul_f32_e32 v16, 0xbfb8aa3b, v15
	v_and_b32_e32 v17, 0xffff0000, v151
	v_exp_f32_e32 v16, v16
	v_mul_f32_e32 v18, 0xbfb8aa3b, v17
	v_exp_f32_e32 v18, v18
	v_mul_f32_e32 v11, v14, v11
	v_add_f32_e32 v14, 1.0, v16
	v_rcp_f32_e32 v14, v14
	v_add_f32_e32 v16, 1.0, v18
	v_rcp_f32_e32 v16, v16
	v_cvt_pk_bf16_f32 v10, v10, v11
	v_mul_f32_e32 v11, v14, v15
	v_mul_f32_e32 v11, v11, v12
	v_mul_f32_e32 v12, v16, v17
	v_mul_f32_e32 v12, v12, v13
	v_cvt_pk_bf16_f32 v11, v11, v12
	global_store_dwordx2 v[66:67], v[10:11], off offset:672
	v_lshlrev_b32_e32 v10, 16, v148
	v_mul_f32_e32 v11, 0xbfb8aa3b, v10
	v_and_b32_e32 v12, 0xffff0000, v148
	v_exp_f32_e32 v11, v11
	v_mul_f32_e32 v13, 0xbfb8aa3b, v12
	v_exp_f32_e32 v13, v13
	v_pk_mul_f32 v[6:7], v[6:7], v[0:1] op_sel_hi:[1,0]
	v_add_f32_e32 v11, 1.0, v11
	v_rcp_f32_e32 v11, v11
	v_add_f32_e32 v13, 1.0, v13
	v_rcp_f32_e32 v13, v13
	v_pk_mul_f32 v[8:9], v[8:9], v[0:1] op_sel_hi:[1,0]
	v_mul_f32_e32 v10, v11, v10
	v_lshlrev_b32_e32 v11, 16, v149
	v_mul_f32_e32 v6, v10, v6
	v_mul_f32_e32 v10, v13, v12
	v_mul_f32_e32 v12, 0xbfb8aa3b, v11
	v_and_b32_e32 v13, 0xffff0000, v149
	v_exp_f32_e32 v12, v12
	v_mul_f32_e32 v14, 0xbfb8aa3b, v13
	v_exp_f32_e32 v14, v14
	v_mul_f32_e32 v7, v10, v7
	v_add_f32_e32 v10, 1.0, v12
	v_rcp_f32_e32 v10, v10
	v_add_f32_e32 v12, 1.0, v14
	v_rcp_f32_e32 v12, v12
	v_cvt_pk_bf16_f32 v6, v6, v7
	v_mul_f32_e32 v7, v10, v11
	v_mul_f32_e32 v7, v7, v8
	v_mul_f32_e32 v8, v12, v13
	v_mul_f32_e32 v8, v8, v9
	v_cvt_pk_bf16_f32 v7, v7, v8
	global_store_dwordx2 v[66:67], v[6:7], off offset:704
	v_lshlrev_b32_e32 v6, 16, v146
	v_mul_f32_e32 v7, 0xbfb8aa3b, v6
	v_and_b32_e32 v8, 0xffff0000, v146
	v_exp_f32_e32 v7, v7
	v_mul_f32_e32 v9, 0xbfb8aa3b, v8
	v_exp_f32_e32 v9, v9
	v_pk_mul_f32 v[4:5], v[4:5], v[0:1] op_sel_hi:[1,0]
	v_add_f32_e32 v7, 1.0, v7
	v_rcp_f32_e32 v7, v7
	v_add_f32_e32 v9, 1.0, v9
	v_rcp_f32_e32 v9, v9
	v_pk_mul_f32 v[2:3], v[2:3], v[0:1] op_sel_hi:[1,0]
	v_mul_f32_e32 v0, v7, v6
	v_mul_f32_e32 v0, v0, v2
	v_mul_f32_e32 v2, v9, v8
	v_lshlrev_b32_e32 v6, 16, v147
	v_and_b32_e32 v8, 0xffff0000, v147
	v_mul_f32_e32 v7, 0xbfb8aa3b, v6
	v_mul_f32_e32 v9, 0xbfb8aa3b, v8
	v_exp_f32_e32 v7, v7
	v_exp_f32_e32 v9, v9
	v_mul_f32_e32 v2, v2, v3
	v_cvt_pk_bf16_f32 v2, v0, v2
	v_add_f32_e32 v3, 1.0, v7
	v_add_f32_e32 v7, 1.0, v9
	v_rcp_f32_e32 v3, v3
	v_rcp_f32_e32 v7, v7
	v_mul_f32_e32 v0, v3, v6
	v_mul_f32_e32 v3, v7, v8
	v_mul_f32_e32 v3, v3, v5
	v_mul_f32_e32 v0, v0, v4
	v_cvt_pk_bf16_f32 v3, v0, v3
	global_store_dwordx2 v[66:67], v[2:3], off offset:736
	s_cbranch_scc1 .LBB0_1120

; __device__ __forceinline__ void attn_phase(const Params& p, LAS unsigned char* lds, int li, int tid, int G, bf16_t* __restrict__ dst, const bf16_t* __restrict__ ZGA) {
;     ...
;     for (int kround = 0; kround < icnt; ++kround) {
;         const int item = ibase + kround * istep;
;         const int nitem = (kround + 1 < icnt) ? item + istep : -1;
;         int l = tid & 63; asm volatile("" : "+v"(l));
;         const int lq = l & 15, g = l >> 4;
;         const int tb = item >> 2, hk = item & 3;
;         const int nblk = tb < 128 ? 16 : 32, nbi = tb < 128 ? (tb & 15) : ((tb - 128) & 31);
;         const int t0 = tb * 128;
;         const bool has0 = nbi > 0, has2 = nbi < nblk - 1;
;         const int nkb = 1 + (has0 ? 1 : 0) + (has2 ? 1 : 0);
;         if (hk != curhk) {
;             __syncthreads();
;             const float* bt = (const float*)(ws + OFF_BIAS) + (size_t)(li * 12 + 3 * hk) * 260; for (int i = 64 * w + l; i < 3 * 260; i += 512) BS[i] = bt[i];
;             curhk = hk;
;         }
;         bf16x8 Qf[3][4];
;         {
;             const float* qg = p.q_gain + li * 128; const float* kg = p.k_gain + li * 128;
; #pragma unroll
;             for (int mb = 0; mb < 3; ++mb) {
;                 u32x4 raw[4]; float ss = 0.f;
; #pragma unroll
;                 for (int ks = 0; ks < 4; ++ks) { raw[ks] = qraw[mb][ks];
; #pragma unroll
;                     for (int e = 0; e < 4; ++e) { const float a = bf_lo(raw[ks][e]), b = bf_hi(raw[ks][e]); ss += a * a + b * b; } }
;                 ss += __shfl_xor(ss, 16); ss += __shfl_xor(ss, 32);
;                 const float rq = rsqrtf(ss * (1.f / 128.f) + EPS) * (0.08838834764831845f * LOG2E);
; #pragma unroll
;                 for (int ks = 0; ks < 4; ++ks) {
;                     const f32x4 g0 = *(const f32x4*)(qg + 32 * ks + 8 * g) * *(const f32x4*)(kg + 32 * ks + 8 * g), g1 = *(const f32x4*)(qg + 32 * ks + 8 * g + 4) * *(const f32x4*)(kg + 32 * ks + 8 * g + 4);
;                     u32x4 o;
;                     o.x = cvt_pk_bf16(bf_lo(raw[ks].x) * rq * g0[0], bf_hi(raw[ks].x) * rq * g0[1]);
;                     o.y = cvt_pk_bf16(bf_lo(raw[ks].y) * rq * g0[2], bf_hi(raw[ks].y) * rq * g0[3]);
;                     o.z = cvt_pk_bf16(bf_lo(raw[ks].z) * rq * g1[0], bf_hi(raw[ks].z) * rq * g1[1]);
;                     o.w = cvt_pk_bf16(bf_lo(raw[ks].w) * rq * g1[2], bf_hi(raw[ks].w) * rq * g1[3]);
.LBB0_1076:
	s_waitcnt vmcnt(0)
	s_bitcmp1_b32 s89, 6
	s_cbranch_scc0 .Laprio1_top
	s_setprio 1
.Laprio1_top:
	v_and_b32_e32 v27, 0xffff0000, v110
	v_and_b32_e32 v95, 0xffff0000, v111
	v_lshlrev_b32_e32 v26, 16, v110
	v_mul_f32_e32 v6, v27, v27
	v_lshlrev_b32_e32 v94, 16, v111
	v_mul_f32_e32 v7, v95, v95
	v_fmac_f32_e32 v6, v26, v26
	v_fmac_f32_e32 v7, v94, v94
	v_and_b32_e32 v97, 0xffff0000, v112
	v_and_b32_e32 v3, 64, v202
	v_add_f32_e32 v6, v6, v7
	v_lshlrev_b32_e32 v96, 16, v112
	v_mul_f32_e32 v7, v97, v97
	v_ashrrev_i32_e32 v38, 4, v0
	v_xor_b32_e32 v2, 16, v202
	v_add_u32_e32 v39, 64, v3
	v_fmac_f32_e32 v7, v96, v96
	v_and_b32_e32 v111, 0xffff0000, v113
	v_cmp_lt_i32_e32 vcc, v2, v39
	v_lshlrev_b32_e32 v172, 3, v38
	v_add_f32_e32 v6, v7, v6
	v_lshlrev_b32_e32 v110, 16, v113
	v_mul_f32_e32 v7, v111, v111
	v_cndmask_b32_e32 v2, v202, v2, vcc
	v_ashrrev_i32_e32 v173, 31, v172
	v_fmac_f32_e32 v7, v110, v110
	v_lshlrev_b32_e32 v112, 16, v106
	v_and_b32_e32 v106, 0xffff0000, v106
	v_lshlrev_b32_e32 v204, 2, v2
	v_lshlrev_b64 v[2:3], 2, v[172:173]
	v_add_f32_e32 v6, v7, v6
	v_mul_f32_e32 v7, v106, v106
	s_waitcnt lgkmcnt(0)
	v_lshl_add_u64 v[4:5], s[16:17], 0, v[2:3]
	v_fmac_f32_e32 v7, v112, v112
	v_lshl_add_u64 v[2:3], s[18:19], 0, v[2:3]
	v_add_f32_e32 v14, v7, v6
	global_load_dwordx4 v[6:9], v[4:5], off offset:528
	global_load_dwordx4 v[10:13], v[4:5], off offset:512
	global_load_dwordx4 v[16:19], v[2:3], off offset:528
	global_load_dwordx4 v[20:23], v[2:3], off offset:512
	global_load_dwordx4 v[28:31], v[4:5], off offset:656
	global_load_dwordx4 v[40:43], v[4:5], off offset:640
	global_load_dwordx4 v[44:47], v[2:3], off offset:656
	global_load_dwordx4 v[48:51], v[2:3], off offset:640
	global_load_dwordx4 v[52:55], v[4:5], off offset:784
	global_load_dwordx4 v[56:59], v[4:5], off offset:768
	global_load_dwordx4 v[60:63], v[2:3], off offset:784
	global_load_dwordx4 v[64:67], v[2:3], off offset:768
	global_load_dwordx4 v[68:71], v[4:5], off offset:912
	global_load_dwordx4 v[72:75], v[4:5], off offset:896
	global_load_dwordx4 v[76:79], v[2:3], off offset:912
	global_load_dwordx4 v[80:83], v[2:3], off offset:896
	v_lshlrev_b32_e32 v113, 16, v107
	v_and_b32_e32 v107, 0xffff0000, v107
	v_mul_f32_e32 v15, v107, v107
	v_fmac_f32_e32 v15, v113, v113
	v_lshlrev_b32_e32 v146, 16, v108
	v_and_b32_e32 v108, 0xffff0000, v108
	v_add_f32_e32 v14, v15, v14
	v_mul_f32_e32 v15, v108, v108
	v_fmac_f32_e32 v15, v146, v146
	v_lshlrev_b32_e32 v147, 16, v109
	v_and_b32_e32 v109, 0xffff0000, v109
	v_add_f32_e32 v14, v15, v14
	v_mul_f32_e32 v15, v109, v109
	v_fmac_f32_e32 v15, v147, v147
	v_and_b32_e32 v85, 0xffff0000, v103
	v_and_b32_e32 v84, 0xffff0000, v102
	v_add_f32_e32 v24, v15, v14
	v_lshlrev_b32_e32 v33, 16, v103
	v_lshlrev_b32_e32 v32, 16, v102
	v_pk_mul_f32 v[14:15], v[84:85], v[84:85]
	v_and_b32_e32 v89, 0xffff0000, v105
	v_pk_fma_f32 v[14:15], v[32:33], v[32:33], v[14:15]
	v_and_b32_e32 v88, 0xffff0000, v104
	v_add_f32_e32 v14, v14, v24
	v_add_f32_e32 v24, v15, v14
	v_lshlrev_b32_e32 v87, 16, v105
	v_lshlrev_b32_e32 v86, 16, v104
	v_pk_mul_f32 v[14:15], v[88:89], v[88:89]
	v_and_b32_e32 v93, 0xffff0000, v99
	v_pk_fma_f32 v[14:15], v[86:87], v[86:87], v[14:15]
	v_and_b32_e32 v92, 0xffff0000, v98
	v_add_f32_e32 v14, v14, v24
	v_add_f32_e32 v24, v15, v14
	v_lshlrev_b32_e32 v91, 16, v99
	v_lshlrev_b32_e32 v90, 16, v98
	v_pk_mul_f32 v[14:15], v[92:93], v[92:93]
	v_and_b32_e32 v35, 0xffff0000, v101
	v_pk_fma_f32 v[14:15], v[90:91], v[90:91], v[14:15]
	v_and_b32_e32 v34, 0xffff0000, v100
	v_add_f32_e32 v14, v14, v24
	v_add_f32_e32 v24, v15, v14
	v_lshlrev_b32_e32 v37, 16, v101
	v_lshlrev_b32_e32 v36, 16, v100
	v_pk_mul_f32 v[14:15], v[34:35], v[34:35]
	s_add_i32 s26, s26, 1
	v_pk_fma_f32 v[14:15], v[36:37], v[36:37], v[14:15]
	s_add_i32 s0, s34, s82
	v_add_f32_e32 v14, v14, v24
	v_add_f32_e32 v14, v15, v14
	ds_bpermute_b32 v15, v204, v14
	v_xor_b32_e32 v24, 32, v202
	v_cmp_lt_i32_e32 vcc, v24, v39
	s_cmp_lt_i32 s26, s21
	s_cselect_b32 s38, s0, -1
	v_cndmask_b32_e32 v24, v202, v24, vcc
	v_lshlrev_b32_e32 v205, 2, v24
	s_waitcnt lgkmcnt(0)
	v_add_f32_e32 v14, v14, v15
	ds_bpermute_b32 v15, v205, v14
	s_ashr_i32 s39, s34, 2
	s_cmpk_lt_i32 s39, 0x80
	s_cselect_b32 s1, 15, 31
	s_and_b32 s0, s1, s39
	s_waitcnt lgkmcnt(0)
	v_add_f32_e32 v14, v14, v15
	v_fmamk_f32 v14, v14, 0x3c000000, v201
	v_mul_f32_e32 v15, 0x4b800000, v14
	v_cmp_gt_f32_e32 vcc, s7, v14
	s_cmp_lg_u32 s0, s1
	s_cselect_b64 s[8:9], -1, 0
	v_cndmask_b32_e32 v14, v14, v15, vcc
	v_rsq_f32_e32 v2, v14
	s_cmp_lg_u32 s0, 0
	s_cselect_b64 s[58:59], -1, 0
	s_and_b64 s[0:1], s[58:59], exec
	v_mul_f32_e32 v3, 0x45800000, v2
	v_cndmask_b32_e32 v2, v2, v3, vcc
	v_mul_f32_e32 v148, 0x3e0293ee, v2
	s_waitcnt vmcnt(12)
	v_pk_mul_f32 v[24:25], v[10:11], v[20:21]
	v_mul_f32_e32 v4, v148, v26
	v_mul_f32_e32 v5, v148, v27
	v_mul_f32_e32 v4, v24, v4
	v_mul_f32_e32 v5, v25, v5
	v_pk_mul_f32 v[14:15], v[12:13], v[22:23]
	v_pk_mul_f32 v[2:3], v[8:9], v[18:19]
	v_pk_mul_f32 v[8:9], v[6:7], v[16:17]
	v_cvt_pk_bf16_f32 v98, v4, v5
	v_mul_f32_e32 v4, v148, v94
	v_mul_f32_e32 v5, v148, v95
	s_waitcnt vmcnt(8)
	v_pk_mul_f32 v[26:27], v[40:41], v[48:49]
	v_mul_f32_e32 v6, v148, v112
	v_mul_f32_e32 v7, v148, v106
	v_mul_f32_e32 v4, v14, v4
	v_mul_f32_e32 v5, v15, v5
	v_mul_f32_e32 v6, v6, v26
	v_mul_f32_e32 v7, v7, v27
	v_cvt_pk_bf16_f32 v99, v4, v5
	v_mul_f32_e32 v4, v148, v96
	v_mul_f32_e32 v5, v148, v97
	v_pk_mul_f32 v[16:17], v[42:43], v[50:51]
	v_cvt_pk_bf16_f32 v102, v6, v7
	v_mul_f32_e32 v6, v148, v113
	v_mul_f32_e32 v7, v148, v107
	v_mul_f32_e32 v4, v8, v4
	v_mul_f32_e32 v5, v9, v5
	v_pk_mul_f32 v[10:11], v[28:29], v[44:45]
	v_mul_f32_e32 v6, v6, v16
	v_mul_f32_e32 v7, v7, v17
	s_waitcnt vmcnt(4)
; __device__ __forceinline__ unsigned cvt_pk_bf16(float lo, float hi) { unsigned r; asm("v_cvt_pk_bf16_f32 %0, %1, %2" : "=v"(r) : "v"(lo), "v"(hi)); return r; }
; __device__ __forceinline__ void attn_phase(const Params& p, LAS unsigned char* lds, int li, int tid, int G, bf16_t* __restrict__ dst, const bf16_t* __restrict__ ZGA) {
;     ...
;         bf16x8 Qf[3][4];
;         {
;             const float* qg = p.q_gain + li * 128; const float* kg = p.k_gain + li * 128;
; #pragma unroll
;             for (int mb = 0; mb < 3; ++mb) {
;                 u32x4 raw[4]; float ss = 0.f;
; #pragma unroll
;                 for (int ks = 0; ks < 4; ++ks) { raw[ks] = qraw[mb][ks];
; #pragma unroll
;                     for (int e = 0; e < 4; ++e) { const float a = bf_lo(raw[ks][e]), b = bf_hi(raw[ks][e]); ss += a * a + b * b; } }
;                 ss += __shfl_xor(ss, 16); ss += __shfl_xor(ss, 32);
;                 const float rq = rsqrtf(ss * (1.f / 128.f) + EPS) * (0.08838834764831845f * LOG2E);
; #pragma unroll
;                 for (int ks = 0; ks < 4; ++ks) {
;                     const f32x4 g0 = *(const f32x4*)(qg + 32 * ks + 8 * g) * *(const f32x4*)(kg + 32 * ks + 8 * g), g1 = *(const f32x4*)(qg + 32 * ks + 8 * g + 4) * *(const f32x4*)(kg + 32 * ks + 8 * g + 4);
;                     u32x4 o;
;                     o.x = cvt_pk_bf16(bf_lo(raw[ks].x) * rq * g0[0], bf_hi(raw[ks].x) * rq * g0[1]);
;                     o.y = cvt_pk_bf16(bf_lo(raw[ks].y) * rq * g0[2], bf_hi(raw[ks].y) * rq * g0[3]);
;                     o.z = cvt_pk_bf16(bf_lo(raw[ks].z) * rq * g1[0], bf_hi(raw[ks].z) * rq * g1[1]);
;                     o.w = cvt_pk_bf16(bf_lo(raw[ks].w) * rq * g1[2], bf_hi(raw[ks].w) * rq * g1[3]);
;                     Qf[mb][ks] = __builtin_bit_cast(bf16x8, o);
;                 }
	v_pk_mul_f32 v[28:29], v[56:57], v[64:65]
	v_mul_f32_e32 v20, v148, v32
	v_cvt_pk_bf16_f32 v100, v4, v5
	v_mul_f32_e32 v4, v148, v110
	v_mul_f32_e32 v5, v148, v111
	v_cvt_pk_bf16_f32 v103, v6, v7
	v_mul_f32_e32 v6, v148, v146
	v_mul_f32_e32 v7, v148, v108
	v_mul_f32_e32 v20, v20, v28
	v_mul_f32_e32 v21, v148, v84
	v_mul_f32_e32 v4, v2, v4
	v_mul_f32_e32 v5, v3, v5
	v_mul_f32_e32 v6, v6, v10
	v_mul_f32_e32 v7, v7, v11
	v_mul_f32_e32 v21, v21, v29
	v_cvt_pk_bf16_f32 v106, v20, v21
	v_mul_f32_e32 v20, v148, v33
	s_waitcnt vmcnt(0)
	v_pk_mul_f32 v[32:33], v[72:73], v[80:81]
	v_mul_f32_e32 v40, v148, v90
	v_cvt_pk_bf16_f32 v101, v4, v5
	v_pk_mul_f32 v[4:5], v[30:31], v[46:47]
	v_cvt_pk_bf16_f32 v104, v6, v7
	v_mul_f32_e32 v6, v148, v147
	v_mul_f32_e32 v7, v148, v109
	v_mul_f32_e32 v40, v40, v32
	v_mul_f32_e32 v41, v148, v92
	v_mul_f32_e32 v6, v6, v4
	v_mul_f32_e32 v7, v7, v5
	v_pk_mul_f32 v[22:23], v[74:75], v[82:83]
	v_mul_f32_e32 v41, v41, v33
	v_cvt_pk_bf16_f32 v110, v40, v41
	v_mul_f32_e32 v40, v148, v91
	v_cvt_pk_bf16_f32 v105, v6, v7
	v_pk_mul_f32 v[18:19], v[58:59], v[66:67]
	v_pk_mul_f32 v[6:7], v[54:55], v[62:63]
	v_pk_mul_f32 v[12:13], v[52:53], v[60:61]
	v_mul_f32_e32 v58, v40, v22
	v_mul_f32_e32 v40, v148, v93
	v_and_b32_e32 v61, 0xffff0000, v134
	v_and_b32_e32 v63, 0xffff0000, v135
	v_mul_f32_e32 v59, v40, v23
	v_lshlrev_b32_e32 v60, 16, v134
	v_mul_f32_e32 v40, v61, v61
	v_lshlrev_b32_e32 v62, 16, v135
	v_mul_f32_e32 v41, v63, v63
	v_mul_f32_e32 v21, v148, v85
	v_fmac_f32_e32 v40, v60, v60
	v_fmac_f32_e32 v41, v62, v62
	v_and_b32_e32 v65, 0xffff0000, v136
	v_mul_f32_e32 v20, v20, v18
	v_mul_f32_e32 v21, v21, v19
	v_add_f32_e32 v40, v40, v41
	v_lshlrev_b32_e32 v64, 16, v136
	v_mul_f32_e32 v41, v65, v65
	v_cvt_pk_bf16_f32 v107, v20, v21
	v_mul_f32_e32 v20, v148, v86
	v_mul_f32_e32 v21, v148, v88
	v_fmac_f32_e32 v41, v64, v64
	v_and_b32_e32 v67, 0xffff0000, v137
	v_mul_f32_e32 v20, v20, v12
	v_mul_f32_e32 v21, v21, v13
	v_add_f32_e32 v40, v41, v40
	v_lshlrev_b32_e32 v66, 16, v137
	v_mul_f32_e32 v41, v67, v67
	v_cvt_pk_bf16_f32 v108, v20, v21
	v_mul_f32_e32 v20, v148, v87
	v_mul_f32_e32 v21, v148, v89
	v_pk_mul_f32 v[30:31], v[68:69], v[76:77]
	v_fmac_f32_e32 v41, v66, v66
	v_and_b32_e32 v69, 0xffff0000, v130
	v_mul_f32_e32 v20, v20, v6
	v_mul_f32_e32 v21, v21, v7
	v_add_f32_e32 v40, v41, v40
	v_lshlrev_b32_e32 v68, 16, v130
	v_mul_f32_e32 v41, v69, v69
	v_cvt_pk_bf16_f32 v109, v20, v21
	v_pk_mul_f32 v[20:21], v[70:71], v[78:79]
	v_fmac_f32_e32 v41, v68, v68
	v_and_b32_e32 v71, 0xffff0000, v131
	v_add_f32_e32 v40, v41, v40
	v_lshlrev_b32_e32 v70, 16, v131
	v_mul_f32_e32 v41, v71, v71
	v_fmac_f32_e32 v41, v70, v70
	v_and_b32_e32 v73, 0xffff0000, v132
	v_add_f32_e32 v40, v41, v40
	v_lshlrev_b32_e32 v72, 16, v132
	v_mul_f32_e32 v41, v73, v73
	v_fmac_f32_e32 v41, v72, v72
	v_and_b32_e32 v75, 0xffff0000, v133
	v_add_f32_e32 v40, v41, v40
	v_lshlrev_b32_e32 v74, 16, v133
	v_mul_f32_e32 v41, v75, v75
	v_fmac_f32_e32 v41, v74, v74
	v_and_b32_e32 v43, 0xffff0000, v127
	v_and_b32_e32 v42, 0xffff0000, v126
	v_add_f32_e32 v46, v41, v40
	v_lshlrev_b32_e32 v41, 16, v127
	v_lshlrev_b32_e32 v40, 16, v126
	v_pk_mul_f32 v[44:45], v[42:43], v[42:43]
	v_and_b32_e32 v47, 0xffff0000, v129
	v_pk_fma_f32 v[44:45], v[40:41], v[40:41], v[44:45]
	v_and_b32_e32 v51, 0xffff0000, v123
	v_add_f32_e32 v44, v44, v46
	v_and_b32_e32 v46, 0xffff0000, v128
	v_add_f32_e32 v50, v45, v44
	v_lshlrev_b32_e32 v45, 16, v129
	v_lshlrev_b32_e32 v44, 16, v128
	v_pk_mul_f32 v[48:49], v[46:47], v[46:47]
	v_and_b32_e32 v55, 0xffff0000, v125
	v_pk_fma_f32 v[48:49], v[44:45], v[44:45], v[48:49]
	v_mul_f32_e32 v36, v148, v36
	v_add_f32_e32 v48, v48, v50
	v_and_b32_e32 v50, 0xffff0000, v122
	v_add_f32_e32 v54, v49, v48
	v_lshlrev_b32_e32 v49, 16, v123
	v_lshlrev_b32_e32 v48, 16, v122
	v_pk_mul_f32 v[52:53], v[50:51], v[50:51]
	v_mul_f32_e32 v36, v36, v30
	v_pk_fma_f32 v[52:53], v[48:49], v[48:49], v[52:53]
	v_mul_f32_e32 v34, v148, v34
	v_add_f32_e32 v52, v52, v54
	v_and_b32_e32 v54, 0xffff0000, v124
	v_add_f32_e32 v76, v53, v52
	v_lshlrev_b32_e32 v53, 16, v125
	v_lshlrev_b32_e32 v52, 16, v124
	v_pk_mul_f32 v[56:57], v[54:55], v[54:55]
	v_mul_f32_e32 v34, v34, v31
	v_pk_fma_f32 v[56:57], v[52:53], v[52:53], v[56:57]
	v_cvt_pk_bf16_f32 v112, v36, v34
	v_mul_f32_e32 v34, v148, v37
	v_add_f32_e32 v56, v56, v76
	v_add_f32_e32 v56, v57, v56
	ds_bpermute_b32 v57, v204, v56
	v_mul_f32_e32 v34, v34, v20
	v_mul_f32_e32 v35, v148, v35
	v_mul_f32_e32 v35, v35, v21
	v_cvt_pk_bf16_f32 v113, v34, v35
	s_waitcnt lgkmcnt(0)
	v_add_f32_e32 v56, v56, v57
	ds_bpermute_b32 v57, v205, v56
	v_cvt_pk_bf16_f32 v111, v58, v59
	v_and_b32_e32 v76, 0xffff0000, v117
	s_cselect_b32 s0, 2, 1
	s_cmp_lg_u64 s[8:9], 0
	s_waitcnt lgkmcnt(0)
; __device__ __forceinline__ unsigned cvt_pk_bf16(float lo, float hi) { unsigned r; asm("v_cvt_pk_bf16_f32 %0, %1, %2" : "=v"(r) : "v"(lo), "v"(hi)); return r; }
; __device__ __forceinline__ void attn_phase(const Params& p, LAS unsigned char* lds, int li, int tid, int G, bf16_t* __restrict__ dst, const bf16_t* __restrict__ ZGA) {
;     ...
;         bf16x8 Qf[3][4];
;         {
;             const float* qg = p.q_gain + li * 128; const float* kg = p.k_gain + li * 128;
; #pragma unroll
;             for (int mb = 0; mb < 3; ++mb) {
;                 u32x4 raw[4]; float ss = 0.f;
; #pragma unroll
;                 for (int ks = 0; ks < 4; ++ks) { raw[ks] = qraw[mb][ks];
; #pragma unroll
;                     for (int e = 0; e < 4; ++e) { const float a = bf_lo(raw[ks][e]), b = bf_hi(raw[ks][e]); ss += a * a + b * b; } }
;                 ss += __shfl_xor(ss, 16); ss += __shfl_xor(ss, 32);
;                 const float rq = rsqrtf(ss * (1.f / 128.f) + EPS) * (0.08838834764831845f * LOG2E);
; #pragma unroll
;                 for (int ks = 0; ks < 4; ++ks) {
;                     const f32x4 g0 = *(const f32x4*)(qg + 32 * ks + 8 * g) * *(const f32x4*)(kg + 32 * ks + 8 * g), g1 = *(const f32x4*)(qg + 32 * ks + 8 * g + 4) * *(const f32x4*)(kg + 32 * ks + 8 * g + 4);
;                     u32x4 o;
;                     o.x = cvt_pk_bf16(bf_lo(raw[ks].x) * rq * g0[0], bf_hi(raw[ks].x) * rq * g0[1]);
;                     o.y = cvt_pk_bf16(bf_lo(raw[ks].y) * rq * g0[2], bf_hi(raw[ks].y) * rq * g0[3]);
;                     o.z = cvt_pk_bf16(bf_lo(raw[ks].z) * rq * g1[0], bf_hi(raw[ks].z) * rq * g1[1]);
;                     o.w = cvt_pk_bf16(bf_lo(raw[ks].w) * rq * g1[2], bf_hi(raw[ks].w) * rq * g1[3]);
;                     Qf[mb][ks] = __builtin_bit_cast(bf16x8, o);
;                 }
	v_add_f32_e32 v36, v56, v57
	v_fmamk_f32 v36, v36, 0x3c000000, v201
	v_mul_f32_e32 v37, 0x4b800000, v36
	v_cmp_gt_f32_e32 vcc, s7, v36
	s_addc_u32 s41, s0, 0
	s_cmp_gt_i32 s38, -1
	v_cndmask_b32_e32 v36, v36, v37, vcc
	v_rsq_f32_e32 v36, v36
	v_and_b32_e32 v37, 0xffff0000, v143
	s_cselect_b64 s[60:61], -1, 0
	s_lshl_b32 s0, s38, 5
	v_mul_f32_e32 v34, 0x45800000, v36
	v_cndmask_b32_e32 v34, v36, v34, vcc
	v_mul_f32_e32 v58, 0x3e0293ee, v34
	v_mul_f32_e32 v34, v58, v60
	v_mul_f32_e32 v34, v24, v34
	v_mul_f32_e32 v35, v58, v61
	v_mul_f32_e32 v35, v25, v35
	v_cvt_pk_bf16_f32 v122, v34, v35
	v_mul_f32_e32 v34, v58, v62
	v_mul_f32_e32 v34, v14, v34
	v_mul_f32_e32 v35, v58, v63
	v_mul_f32_e32 v35, v15, v35
	v_cvt_pk_bf16_f32 v123, v34, v35
	v_mul_f32_e32 v34, v58, v64
	v_mul_f32_e32 v34, v8, v34
	v_mul_f32_e32 v35, v58, v65
	v_mul_f32_e32 v35, v9, v35
	v_cvt_pk_bf16_f32 v124, v34, v35
	v_mul_f32_e32 v34, v58, v66
	v_mul_f32_e32 v34, v2, v34
	v_mul_f32_e32 v35, v58, v67
	v_mul_f32_e32 v35, v3, v35
	v_cvt_pk_bf16_f32 v125, v34, v35
	v_mul_f32_e32 v34, v58, v68
	v_mul_f32_e32 v34, v26, v34
	v_mul_f32_e32 v35, v58, v69
	v_mul_f32_e32 v35, v27, v35
	v_cvt_pk_bf16_f32 v126, v34, v35
	v_mul_f32_e32 v34, v58, v70
	v_mul_f32_e32 v34, v16, v34
	v_mul_f32_e32 v35, v58, v71
	v_mul_f32_e32 v35, v17, v35
	v_cvt_pk_bf16_f32 v127, v34, v35
	v_mul_f32_e32 v34, v58, v72
	v_mul_f32_e32 v34, v10, v34
	v_mul_f32_e32 v35, v58, v73
	v_mul_f32_e32 v35, v11, v35
	v_cvt_pk_bf16_f32 v128, v34, v35
	v_mul_f32_e32 v34, v58, v74
	v_mul_f32_e32 v34, v4, v34
	v_mul_f32_e32 v35, v58, v75
	v_mul_f32_e32 v35, v5, v35
	v_cvt_pk_bf16_f32 v129, v34, v35
	v_mul_f32_e32 v34, v58, v40
	v_mul_f32_e32 v34, v28, v34
	v_mul_f32_e32 v35, v58, v42
	v_mul_f32_e32 v35, v29, v35
	v_cvt_pk_bf16_f32 v130, v34, v35
	v_mul_f32_e32 v34, v58, v41
	v_mul_f32_e32 v34, v18, v34
	v_mul_f32_e32 v35, v58, v43
	v_mul_f32_e32 v35, v19, v35
	v_cvt_pk_bf16_f32 v131, v34, v35
	v_mul_f32_e32 v34, v58, v44
	v_mul_f32_e32 v34, v12, v34
	v_mul_f32_e32 v35, v58, v46
	v_mul_f32_e32 v35, v13, v35
	v_cvt_pk_bf16_f32 v132, v34, v35
	v_mul_f32_e32 v34, v58, v45
	v_mul_f32_e32 v34, v6, v34
	v_mul_f32_e32 v35, v58, v47
	v_mul_f32_e32 v35, v7, v35
	v_cvt_pk_bf16_f32 v133, v34, v35
	v_mul_f32_e32 v34, v58, v48
	v_mul_f32_e32 v34, v32, v34
	v_mul_f32_e32 v35, v58, v50
	v_mul_f32_e32 v35, v33, v35
	v_cvt_pk_bf16_f32 v134, v34, v35
	v_mul_f32_e32 v34, v58, v49
	v_mul_f32_e32 v59, v22, v34
	v_mul_f32_e32 v34, v58, v51
	v_and_b32_e32 v62, 0xffff0000, v118
	v_and_b32_e32 v64, 0xffff0000, v119
	v_mul_f32_e32 v60, v23, v34
	v_lshlrev_b32_e32 v61, 16, v118
	v_mul_f32_e32 v34, v62, v62
	v_lshlrev_b32_e32 v63, 16, v119
	v_mul_f32_e32 v35, v64, v64
	v_fmac_f32_e32 v34, v61, v61
	v_fmac_f32_e32 v35, v63, v63
	v_and_b32_e32 v66, 0xffff0000, v120
	v_add_f32_e32 v34, v34, v35
	v_lshlrev_b32_e32 v65, 16, v120
	v_mul_f32_e32 v35, v66, v66
	v_fmac_f32_e32 v35, v65, v65
	v_and_b32_e32 v68, 0xffff0000, v121
	v_add_f32_e32 v34, v35, v34
	v_lshlrev_b32_e32 v67, 16, v121
	v_mul_f32_e32 v35, v68, v68
	v_fmac_f32_e32 v35, v67, v67
	v_and_b32_e32 v70, 0xffff0000, v114
	v_add_f32_e32 v34, v35, v34
	v_lshlrev_b32_e32 v69, 16, v114
	v_mul_f32_e32 v35, v70, v70
	v_fmac_f32_e32 v35, v69, v69
	v_and_b32_e32 v72, 0xffff0000, v115
	v_add_f32_e32 v34, v35, v34
	v_lshlrev_b32_e32 v71, 16, v115
	v_mul_f32_e32 v35, v72, v72
	v_fmac_f32_e32 v35, v71, v71
	v_and_b32_e32 v74, 0xffff0000, v116
	v_add_f32_e32 v34, v35, v34
	v_lshlrev_b32_e32 v73, 16, v116
	v_mul_f32_e32 v35, v74, v74
	v_fmac_f32_e32 v35, v73, v73
	v_add_f32_e32 v34, v35, v34
	v_lshlrev_b32_e32 v75, 16, v117
	v_mul_f32_e32 v35, v76, v76
	v_fmac_f32_e32 v35, v75, v75
	v_and_b32_e32 v36, 0xffff0000, v142
	v_add_f32_e32 v42, v35, v34
	v_lshlrev_b32_e32 v35, 16, v143
	v_lshlrev_b32_e32 v34, 16, v142
	v_pk_mul_f32 v[40:41], v[36:37], v[36:37]
	v_and_b32_e32 v43, 0xffff0000, v145
	v_pk_fma_f32 v[40:41], v[34:35], v[34:35], v[40:41]
	v_and_b32_e32 v47, 0xffff0000, v139
	v_add_f32_e32 v40, v40, v42
	v_and_b32_e32 v42, 0xffff0000, v144
	v_add_f32_e32 v46, v41, v40
	v_lshlrev_b32_e32 v41, 16, v145
	v_lshlrev_b32_e32 v40, 16, v144
	v_pk_mul_f32 v[44:45], v[42:43], v[42:43]
	v_and_b32_e32 v51, 0xffff0000, v141
	v_pk_fma_f32 v[44:45], v[40:41], v[40:41], v[44:45]
	v_mul_f32_e32 v52, v58, v52
	v_add_f32_e32 v44, v44, v46
	v_and_b32_e32 v46, 0xffff0000, v138
	v_add_f32_e32 v50, v45, v44
	v_lshlrev_b32_e32 v45, 16, v139
	v_lshlrev_b32_e32 v44, 16, v138
	v_pk_mul_f32 v[48:49], v[46:47], v[46:47]
	v_mul_f32_e32 v52, v30, v52
	v_pk_fma_f32 v[48:49], v[44:45], v[44:45], v[48:49]
	v_mul_f32_e32 v54, v58, v54
	v_add_f32_e32 v48, v48, v50
	v_and_b32_e32 v50, 0xffff0000, v140
	v_add_f32_e32 v77, v49, v48
	v_lshlrev_b32_e32 v49, 16, v141
	v_lshlrev_b32_e32 v48, 16, v140
	v_pk_mul_f32 v[56:57], v[50:51], v[50:51]
	v_mul_f32_e32 v54, v31, v54
	v_pk_fma_f32 v[56:57], v[48:49], v[48:49], v[56:57]
	v_cvt_pk_bf16_f32 v136, v52, v54
	v_mul_f32_e32 v52, v58, v53
	v_add_f32_e32 v56, v56, v77
	v_add_f32_e32 v56, v57, v56
	ds_bpermute_b32 v57, v204, v56
	v_mul_f32_e32 v52, v20, v52
	s_and_b32 s27, s0, 0x7fffff80
	s_lshl_b32 s0, s38, 7
	s_and_b32 s30, s0, 0x180
	s_waitcnt lgkmcnt(0)
	v_add_f32_e32 v56, v56, v57
	ds_bpermute_b32 v57, v205, v56
	s_lshl_b32 s0, s30, 1
	s_add_u32 s62, s50, s0
	s_addc_u32 s63, s51, 0
	s_lshl_b32 s0, s27, 1
	s_waitcnt lgkmcnt(0)
; #define LAS __attribute__((address_space(3)))
; __device__ __forceinline__ unsigned cvt_pk_bf16(float lo, float hi) { unsigned r; asm("v_cvt_pk_bf16_f32 %0, %1, %2" : "=v"(r) : "v"(lo), "v"(hi)); return r; }
; __device__ __forceinline__ void attn_phase(const Params& p, LAS unsigned char* lds, int li, int tid, int G, bf16_t* __restrict__ dst, const bf16_t* __restrict__ ZGA) {
;     ...
;             for (int mb = 0; mb < 3; ++mb) {
;                 u32x4 raw[4]; float ss = 0.f;
; #pragma unroll
;                 for (int ks = 0; ks < 4; ++ks) { raw[ks] = qraw[mb][ks];
; #pragma unroll
;                     for (int e = 0; e < 4; ++e) { const float a = bf_lo(raw[ks][e]), b = bf_hi(raw[ks][e]); ss += a * a + b * b; } }
;                 ss += __shfl_xor(ss, 16); ss += __shfl_xor(ss, 32);
;                 const float rq = rsqrtf(ss * (1.f / 128.f) + EPS) * (0.08838834764831845f * LOG2E);
; #pragma unroll
;                 for (int ks = 0; ks < 4; ++ks) {
;                     const f32x4 g0 = *(const f32x4*)(qg + 32 * ks + 8 * g) * *(const f32x4*)(kg + 32 * ks + 8 * g), g1 = *(const f32x4*)(qg + 32 * ks + 8 * g + 4) * *(const f32x4*)(kg + 32 * ks + 8 * g + 4);
;                     u32x4 o;
;                     o.x = cvt_pk_bf16(bf_lo(raw[ks].x) * rq * g0[0], bf_hi(raw[ks].x) * rq * g0[1]);
;                     o.y = cvt_pk_bf16(bf_lo(raw[ks].y) * rq * g0[2], bf_hi(raw[ks].y) * rq * g0[3]);
;                     o.z = cvt_pk_bf16(bf_lo(raw[ks].z) * rq * g1[0], bf_hi(raw[ks].z) * rq * g1[1]);
;                     o.w = cvt_pk_bf16(bf_lo(raw[ks].w) * rq * g1[2], bf_hi(raw[ks].w) * rq * g1[3]);
;                     Qf[mb][ks] = __builtin_bit_cast(bf16x8, o);
;                 }
;             }
;         }
;         f32x4 oacc[3][8];
;         float lrun[3];
; #pragma unroll
;         for (int mb = 0; mb < 3; ++mb) {
;             lrun[mb] = 0.f;
; #pragma unroll
;             for (int db = 0; db < 8; ++db) oacc[mb][db] = (f32x4){0.f, 0.f, 0.f, 0.f};
;         }
;     ...
;                 const int key = 16 * w + (l >> 2), part = l & 3;
;                 u32x4 v[4]; float ss = 0.f;
; #pragma unroll
;                 for (int i = 0; i < 4; ++i) { v[i] = *(const LAS u32x4*)(KS + key * 256 + (((4 * part + i) ^ (key & 15)) << 4));
	v_add_f32_e32 v53, v56, v57
	v_fmamk_f32 v53, v53, 0x3c000000, v201
	v_mul_f32_e32 v54, 0x4b800000, v53
	v_cmp_gt_f32_e32 vcc, s7, v53
	s_add_u32 s64, s52, s0
	v_and_b32_e32 v208, 15, v0
	v_cndmask_b32_e32 v53, v53, v54, vcc
	v_rsq_f32_e32 v53, v53
	v_mul_f32_e32 v54, v58, v55
	v_mul_f32_e32 v54, v21, v54
	v_cvt_pk_bf16_f32 v137, v52, v54
	v_mul_f32_e32 v52, 0x45800000, v53
	v_cndmask_b32_e32 v52, v53, v52, vcc
	v_mul_f32_e32 v52, 0x3e0293ee, v52
	v_mul_f32_e32 v53, v52, v61
	v_mul_f32_e32 v24, v24, v53
	v_mul_f32_e32 v53, v52, v62
	v_mul_f32_e32 v25, v25, v53
	v_cvt_pk_bf16_f32 v114, v24, v25
	v_mul_f32_e32 v24, v52, v63
	v_mul_f32_e32 v14, v14, v24
	v_mul_f32_e32 v24, v52, v64
	v_mul_f32_e32 v15, v15, v24
	v_cvt_pk_bf16_f32 v115, v14, v15
	v_mul_f32_e32 v14, v52, v65
	v_mul_f32_e32 v8, v8, v14
	v_mul_f32_e32 v14, v52, v66
	v_mul_f32_e32 v9, v9, v14
	v_cvt_pk_bf16_f32 v116, v8, v9
	v_mul_f32_e32 v8, v52, v67
	v_mul_f32_e32 v2, v2, v8
	v_mul_f32_e32 v8, v52, v68
	v_mul_f32_e32 v3, v3, v8
	v_cvt_pk_bf16_f32 v117, v2, v3
	v_mul_f32_e32 v2, v52, v69
	v_mul_f32_e32 v2, v26, v2
	v_mul_f32_e32 v3, v52, v70
	v_mul_f32_e32 v3, v27, v3
	v_cvt_pk_bf16_f32 v118, v2, v3
	v_mul_f32_e32 v2, v52, v71
	v_mul_f32_e32 v2, v16, v2
	v_mul_f32_e32 v3, v52, v72
	v_mul_f32_e32 v3, v17, v3
	v_cvt_pk_bf16_f32 v119, v2, v3
	v_mul_f32_e32 v2, v52, v73
	v_mul_f32_e32 v2, v10, v2
	v_mul_f32_e32 v3, v52, v74
	v_mul_f32_e32 v3, v11, v3
	v_cvt_pk_bf16_f32 v120, v2, v3
	v_mul_f32_e32 v2, v52, v75
	v_mul_f32_e32 v2, v4, v2
	v_mul_f32_e32 v3, v52, v76
	v_mul_f32_e32 v3, v5, v3
	v_cvt_pk_bf16_f32 v121, v2, v3
	v_mul_f32_e32 v2, v52, v34
	v_mul_f32_e32 v2, v28, v2
	v_mul_f32_e32 v3, v52, v36
	v_mul_f32_e32 v3, v29, v3
	v_cvt_pk_bf16_f32 v138, v2, v3
	v_mul_f32_e32 v2, v52, v35
	v_mul_f32_e32 v2, v18, v2
	v_mul_f32_e32 v3, v52, v37
	v_mul_f32_e32 v3, v19, v3
	v_cvt_pk_bf16_f32 v139, v2, v3
	v_mul_f32_e32 v2, v52, v40
	v_mul_f32_e32 v2, v12, v2
	v_mul_f32_e32 v3, v52, v42
	v_mul_f32_e32 v3, v13, v3
	v_cvt_pk_bf16_f32 v140, v2, v3
	v_mul_f32_e32 v2, v52, v41
	v_mul_f32_e32 v2, v6, v2
	v_mul_f32_e32 v3, v52, v43
	v_mul_f32_e32 v3, v7, v3
	v_cvt_pk_bf16_f32 v141, v2, v3
	v_mul_f32_e32 v2, v52, v44
	v_mul_f32_e32 v2, v32, v2
	v_mul_f32_e32 v3, v52, v46
	v_mul_f32_e32 v3, v33, v3
	v_cvt_pk_bf16_f32 v142, v2, v3
	v_mul_f32_e32 v2, v52, v45
	v_mul_f32_e32 v2, v22, v2
	v_mul_f32_e32 v3, v52, v47
	v_mul_f32_e32 v3, v23, v3
	v_cvt_pk_bf16_f32 v143, v2, v3
	v_mul_f32_e32 v2, v52, v48
	v_mul_f32_e32 v2, v30, v2
	v_mul_f32_e32 v3, v52, v50
	v_mul_f32_e32 v3, v31, v3
	v_cvt_pk_bf16_f32 v144, v2, v3
	v_mul_f32_e32 v2, v52, v49
	v_mul_f32_e32 v2, v20, v2
	v_mul_f32_e32 v3, v52, v51
	v_mul_f32_e32 v3, v21, v3
	v_cvt_pk_bf16_f32 v145, v2, v3
	v_ashrrev_i32_e32 v2, 2, v0
	v_add_lshl_u32 v171, v2, s89, 8
	v_lshlrev_b32_e32 v3, 2, v0
	v_and_b32_e32 v2, 15, v2
	v_and_b32_e32 v4, 12, v3
	v_bitop3_b32 v3, v3, v2, 12 bitop3:0x6c
	v_lshlrev_b32_e32 v177, 4, v3
	v_bitop3_b32 v3, v4, v2, 1 bitop3:0x36
	v_lshlrev_b32_e32 v178, 4, v3
	v_bitop3_b32 v3, v4, v2, 2 bitop3:0x36
	v_bitop3_b32 v2, v4, v2, 3 bitop3:0x36
	v_lshlrev_b32_e32 v180, 4, v2
	v_xor_b32_e32 v2, 1, v202
	v_cmp_lt_i32_e32 vcc, v2, v39
	s_addc_u32 s65, s53, 0
	s_lshl_b32 s0, s34, 5
	v_cndmask_b32_e32 v2, v202, v2, vcc
	v_lshlrev_b32_e32 v181, 2, v2
	v_xor_b32_e32 v2, 2, v202
	v_cmp_lt_i32_e32 vcc, v2, v39
	v_lshlrev_b32_e32 v179, 4, v3
	v_add_u32_e32 v3, 4, v38
	v_cndmask_b32_e32 v2, v202, v2, vcc
	s_and_b32 s81, s0, 0xffffff80
	s_lshl_b32 s0, s34, 7
	v_lshlrev_b32_e32 v174, 8, v208
	v_lshlrev_b32_e32 v182, 2, v2
	v_bitop3_b32 v2, v38, v0, 15 bitop3:0x78
	v_bitop3_b32 v3, v3, v0, 15 bitop3:0x78
	v_add_u32_e32 v4, 8, v38
	v_add_u32_e32 v5, 12, v38
	s_and_b32 s1, s0, 0x180
	v_lshlrev_b32_e32 v170, 2, v38
	v_ashrrev_i32_e32 v176, 5, v0
	v_bitop3_b32 v4, v4, v0, 15 bitop3:0x78
	v_bitop3_b32 v0, v5, v0, 15 bitop3:0x78
	v_lshl_add_u32 v184, v2, 4, v174
	v_lshl_add_u32 v185, v3, 4, v174
	v_mov_b32_e32 v2, v1
	v_mov_b32_e32 v3, v1
	v_cvt_pk_bf16_f32 v135, v59, v60
	s_lshl_b32 s0, s1, 1
	v_add_u32_e32 v5, s31, v170
	v_lshl_add_u32 v187, v0, 4, v174
	v_mov_b32_e32 v0, v1
	v_mov_b64_e32 v[80:81], v[2:3]
	v_mov_b64_e32 v[84:85], v[2:3]
	v_mov_b64_e32 v[88:89], v[2:3]
	v_mov_b64_e32 v[92:93], v[2:3]
	v_mov_b64_e32 v[96:97], v[2:3]
	v_mov_b64_e32 v[76:77], v[2:3]
	v_mov_b64_e32 v[72:73], v[2:3]
	v_mov_b64_e32 v[68:69], v[2:3]
	v_mov_b64_e32 v[64:65], v[2:3]
	v_mov_b64_e32 v[60:61], v[2:3]
	v_mov_b64_e32 v[56:57], v[2:3]
	v_mov_b64_e32 v[52:53], v[2:3]
	v_mov_b64_e32 v[48:49], v[2:3]
	v_mov_b64_e32 v[44:45], v[2:3]
	v_mov_b64_e32 v[40:41], v[2:3]
	v_mov_b64_e32 v[36:37], v[2:3]
	v_mov_b64_e32 v[32:33], v[2:3]
	v_mov_b64_e32 v[28:29], v[2:3]
	v_mov_b64_e32 v[24:25], v[2:3]
	v_mov_b64_e32 v[20:21], v[2:3]
	v_mov_b64_e32 v[16:17], v[2:3]
	v_mov_b64_e32 v[12:13], v[2:3]
	v_mov_b64_e32 v[8:9], v[2:3]
	s_add_u32 s66, s50, s0
	v_sub_u32_e32 v183, v5, v208
	v_lshl_add_u32 v186, v4, 4, v174
	v_mov_b64_e32 v[78:79], v[0:1]
	v_mov_b64_e32 v[82:83], v[0:1]
	v_mov_b64_e32 v[86:87], v[0:1]
	v_mov_b64_e32 v[90:91], v[0:1]
	v_mov_b64_e32 v[94:95], v[0:1]
	v_mov_b64_e32 v[74:75], v[0:1]
	v_mov_b64_e32 v[70:71], v[0:1]
	v_mov_b64_e32 v[66:67], v[0:1]
	v_mov_b64_e32 v[62:63], v[0:1]
	v_mov_b64_e32 v[58:59], v[0:1]
	v_mov_b64_e32 v[54:55], v[0:1]
	v_mov_b64_e32 v[50:51], v[0:1]
	v_mov_b64_e32 v[46:47], v[0:1]
	v_mov_b64_e32 v[42:43], v[0:1]
	v_mov_b64_e32 v[38:39], v[0:1]
	v_mov_b64_e32 v[34:35], v[0:1]
	v_mov_b64_e32 v[30:31], v[0:1]
	v_mov_b64_e32 v[26:27], v[0:1]
	v_mov_b64_e32 v[22:23], v[0:1]
	v_mov_b64_e32 v[18:19], v[0:1]
	v_mov_b64_e32 v[14:15], v[0:1]
	v_mov_b64_e32 v[10:11], v[0:1]
	v_mov_b64_e32 v[6:7], v[0:1]
	v_mov_b64_e32 v[4:5], v[2:3]
	s_mov_b32 s74, 0
	s_addc_u32 s67, s51, 0
	v_and_b32_e32 v175, 8, v172
	v_mov_b32_e32 v206, 0
	v_mov_b32_e32 v207, 0
	v_mov_b32_e32 v209, 0
	v_mov_b64_e32 v[2:3], v[0:1]
